# baseline (speedup 1.0000x reference)
; #define LDA(dst, b, h)                                                                                     \
;   _Pragma("unroll") for (int m = 0; m < 4; ++m) _Pragma("unroll") for (int k = 0; k < 2; ++k) dst[m][k] = \
;       *reinterpret_cast<const bf16x8*>(shmc + aL + (((b) * 2 + (h)) * 16384 + (m * 2 + k) * 1024))
; #define LDB(dst, b, h)                                                                                     \
;   _Pragma("unroll") for (int n = 0; n < 2; ++n) _Pragma("unroll") for (int k = 0; k < 2; ++k) dst[n][k] = \
;       *reinterpret_cast<const bf16x8*>(shmc + bL + (((b) * 2 + (h)) * 16384 + (n * 2 + k) * 1024))
; #define OPAQ asm volatile("" : "+v"(aL), "+v"(bL))
; #define WAIT_V(n) asm volatile("s_waitcnt vmcnt(" #n ")" ::: "memory")
; #define WAIT_L(n) asm volatile("s_waitcnt lgkmcnt(" #n ")" ::: "memory")
; #define BAR __builtin_amdgcn_s_barrier()
; #define SCHED __builtin_amdgcn_sched_barrier(0)
; template <int EPI>
; __device__ __forceinline__ void phase_gemm(const Params& p, const GemmDesc& d, char* shmc) {
;     ...
;     for (int t = 0; t < nt - 2; t += 2) {
;       OPAQ;
;       LDB(B0, 0, 0); SCHED; LDA(At, 0, 0); STAGE_A(SA(1, 1), 1, t + 1);
;       WAIT_L(8); BAR; WAIT_L(0); MMA(0, 0, At, B0); BAR; SCHED;
;       LDB(B1, 0, 1); STAGE_B(SB(0, 0), 0, t + 2);
;       BAR; WAIT_L(0); MMA(0, 1, At, B1); BAR;
;       LDA(At, 0, 1); STAGE_A(SA(0, 0), 0, t + 2);
;       BAR; WAIT_L(0); MMA(1, 0, At, B0); BAR; SCHED;
;       STAGE_B(SB(0, 1), 1, t + 2);
;       WAIT_V(6); BAR; MMA(1, 1, At, B1); BAR;
.LBB0_296:
	s_nop 0
	v_add_u32_e32 v162, 0, v205
	v_add_u32_e32 v175, 0, v204
	s_setprio 0
	s_mov_b32 m0, s93
	s_nop 0
	global_load_lds_dwordx4 v202, s[98:99]
	s_mov_b32 m0, s94
	s_nop 0
	global_load_lds_dwordx4 v203, s[98:99]
	ds_read_b128 v[138:141], v162
	ds_read_b128 v[142:145], v162 offset:1024
	ds_read_b128 v[146:149], v162 offset:2048
	ds_read_b128 v[150:153], v162 offset:3072
	ds_read_b128 v[208:211], v162 offset:16384
	ds_read_b128 v[212:215], v162 offset:17408
	ds_read_b128 v[216:219], v162 offset:18432
	ds_read_b128 v[220:223], v162 offset:19456
	ds_read_b128 v[154:157], v175
	ds_read_b128 v[158:161], v175 offset:1024
	ds_read_b128 v[178:181], v175 offset:2048
	ds_read_b128 v[182:185], v175 offset:3072
	ds_read_b128 v[186:189], v175 offset:4096
	ds_read_b128 v[190:193], v175 offset:5120
	ds_read_b128 v[194:197], v175 offset:6144
	ds_read_b128 v[198:201], v175 offset:7168
	s_waitcnt vmcnt(8)
	s_waitcnt lgkmcnt(0)
	s_setprio 1
	s_barrier
	v_mfma_f32_16x16x32_bf16 v[2:5], v[154:157], v[138:141], v[2:5]
	v_mfma_f32_16x16x32_bf16 v[6:9], v[154:157], v[146:149], v[6:9]
	v_mfma_f32_16x16x32_bf16 v[10:13], v[178:181], v[138:141], v[10:13]
	v_mfma_f32_16x16x32_bf16 v[18:21], v[178:181], v[146:149], v[18:21]
	v_mfma_f32_16x16x32_bf16 v[30:33], v[186:189], v[138:141], v[30:33]
	v_mfma_f32_16x16x32_bf16 v[42:45], v[186:189], v[146:149], v[42:45]
	v_mfma_f32_16x16x32_bf16 v[54:57], v[194:197], v[138:141], v[54:57]
	v_mfma_f32_16x16x32_bf16 v[66:69], v[194:197], v[146:149], v[66:69]
	v_mfma_f32_16x16x32_bf16 v[2:5], v[158:161], v[142:145], v[2:5]
	v_mfma_f32_16x16x32_bf16 v[6:9], v[158:161], v[150:153], v[6:9]
	v_mfma_f32_16x16x32_bf16 v[10:13], v[182:185], v[142:145], v[10:13]
	v_mfma_f32_16x16x32_bf16 v[18:21], v[182:185], v[150:153], v[18:21]
	v_mfma_f32_16x16x32_bf16 v[30:33], v[190:193], v[142:145], v[30:33]
	v_mfma_f32_16x16x32_bf16 v[42:45], v[190:193], v[150:153], v[42:45]
	v_mfma_f32_16x16x32_bf16 v[54:57], v[198:201], v[142:145], v[54:57]
	v_mfma_f32_16x16x32_bf16 v[66:69], v[198:201], v[150:153], v[66:69]
	v_mfma_f32_16x16x32_bf16 v[14:17], v[154:157], v[208:211], v[14:17]
	v_mfma_f32_16x16x32_bf16 v[22:25], v[154:157], v[216:219], v[22:25]
	v_mfma_f32_16x16x32_bf16 v[34:37], v[178:181], v[208:211], v[34:37]
	v_mfma_f32_16x16x32_bf16 v[46:49], v[178:181], v[216:219], v[46:49]
	v_mfma_f32_16x16x32_bf16 v[58:61], v[186:189], v[208:211], v[58:61]
	v_mfma_f32_16x16x32_bf16 v[70:73], v[186:189], v[216:219], v[70:73]
	v_mfma_f32_16x16x32_bf16 v[78:81], v[194:197], v[208:211], v[78:81]
	v_mfma_f32_16x16x32_bf16 v[86:89], v[194:197], v[216:219], v[86:89]
	v_mfma_f32_16x16x32_bf16 v[14:17], v[158:161], v[212:215], v[14:17]
	v_mfma_f32_16x16x32_bf16 v[22:25], v[158:161], v[220:223], v[22:25]
	v_mfma_f32_16x16x32_bf16 v[34:37], v[182:185], v[212:215], v[34:37]
	v_mfma_f32_16x16x32_bf16 v[46:49], v[182:185], v[220:223], v[46:49]
	v_mfma_f32_16x16x32_bf16 v[58:61], v[190:193], v[212:215], v[58:61]
	v_mfma_f32_16x16x32_bf16 v[70:73], v[190:193], v[220:223], v[70:73]
	v_mfma_f32_16x16x32_bf16 v[78:81], v[198:201], v[212:215], v[78:81]
	v_mfma_f32_16x16x32_bf16 v[86:89], v[198:201], v[220:223], v[86:89]
	s_barrier
	s_setprio 0
	s_mov_b32 m0, s80
	s_nop 0
	global_load_lds_dwordx4 v224, s[100:101]
	s_mov_b32 m0, s81
	s_nop 0
	global_load_lds_dwordx4 v225, s[100:101]
	s_mov_b32 m0, s77
	s_nop 0
	global_load_lds_dwordx4 v226, s[98:99]
	s_mov_b32 m0, s82
	s_nop 0
	global_load_lds_dwordx4 v227, s[98:99]
	s_mov_b32 m0, s83
	s_nop 0
	global_load_lds_dwordx4 v228, s[100:101]
	s_mov_b32 m0, s84
	s_nop 0
	global_load_lds_dwordx4 v229, s[100:101]
	ds_read_b128 v[154:157], v175 offset:16384
	ds_read_b128 v[158:161], v175 offset:17408
	ds_read_b128 v[178:181], v175 offset:18432
	ds_read_b128 v[182:185], v175 offset:19456
	ds_read_b128 v[186:189], v175 offset:20480
	ds_read_b128 v[190:193], v175 offset:21504
	ds_read_b128 v[194:197], v175 offset:22528
	ds_read_b128 v[198:201], v175 offset:23552
	s_waitcnt vmcnt(8)
	s_waitcnt lgkmcnt(0)
	s_setprio 1
	s_barrier
	v_mfma_f32_16x16x32_bf16 v[26:29], v[154:157], v[138:141], v[26:29]
	v_mfma_f32_16x16x32_bf16 v[38:41], v[154:157], v[146:149], v[38:41]
	v_mfma_f32_16x16x32_bf16 v[50:53], v[178:181], v[138:141], v[50:53]
	v_mfma_f32_16x16x32_bf16 v[62:65], v[178:181], v[146:149], v[62:65]
	v_mfma_f32_16x16x32_bf16 v[74:77], v[186:189], v[138:141], v[74:77]
	v_mfma_f32_16x16x32_bf16 v[82:85], v[186:189], v[146:149], v[82:85]
	v_mfma_f32_16x16x32_bf16 v[90:93], v[194:197], v[138:141], v[90:93]
	v_mfma_f32_16x16x32_bf16 v[94:97], v[194:197], v[146:149], v[94:97]
	v_mfma_f32_16x16x32_bf16 v[26:29], v[158:161], v[142:145], v[26:29]
	v_mfma_f32_16x16x32_bf16 v[38:41], v[158:161], v[150:153], v[38:41]
	v_mfma_f32_16x16x32_bf16 v[50:53], v[182:185], v[142:145], v[50:53]
	v_mfma_f32_16x16x32_bf16 v[62:65], v[182:185], v[150:153], v[62:65]
	v_mfma_f32_16x16x32_bf16 v[74:77], v[190:193], v[142:145], v[74:77]
	v_mfma_f32_16x16x32_bf16 v[82:85], v[190:193], v[150:153], v[82:85]
	v_mfma_f32_16x16x32_bf16 v[90:93], v[198:201], v[142:145], v[90:93]
	v_mfma_f32_16x16x32_bf16 v[94:97], v[198:201], v[150:153], v[94:97]
	v_mfma_f32_16x16x32_bf16 v[98:101], v[154:157], v[208:211], v[98:101]
	v_mfma_f32_16x16x32_bf16 v[102:105], v[154:157], v[216:219], v[102:105]
	v_mfma_f32_16x16x32_bf16 v[106:109], v[178:181], v[208:211], v[106:109]
	v_mfma_f32_16x16x32_bf16 v[110:113], v[178:181], v[216:219], v[110:113]
	v_mfma_f32_16x16x32_bf16 v[114:117], v[186:189], v[208:211], v[114:117]
	v_mfma_f32_16x16x32_bf16 v[118:121], v[186:189], v[216:219], v[118:121]
	v_mfma_f32_16x16x32_bf16 v[122:125], v[194:197], v[208:211], v[122:125]
	v_mfma_f32_16x16x32_bf16 v[126:129], v[194:197], v[216:219], v[126:129]
	v_mfma_f32_16x16x32_bf16 v[98:101], v[158:161], v[212:215], v[98:101]
	v_mfma_f32_16x16x32_bf16 v[102:105], v[158:161], v[220:223], v[102:105]
	v_mfma_f32_16x16x32_bf16 v[106:109], v[182:185], v[212:215], v[106:109]
	v_mfma_f32_16x16x32_bf16 v[110:113], v[182:185], v[220:223], v[110:113]
	v_mfma_f32_16x16x32_bf16 v[114:117], v[190:193], v[212:215], v[114:117]
	v_mfma_f32_16x16x32_bf16 v[118:121], v[190:193], v[220:223], v[118:121]
	v_mfma_f32_16x16x32_bf16 v[122:125], v[198:201], v[212:215], v[122:125]
	v_mfma_f32_16x16x32_bf16 v[126:129], v[198:201], v[220:223], v[126:129]
	s_barrier
; #define LDA(dst, b, h)                                                                                     \
;   _Pragma("unroll") for (int m = 0; m < 4; ++m) _Pragma("unroll") for (int k = 0; k < 2; ++k) dst[m][k] = \
;       *reinterpret_cast<const bf16x8*>(shmc + aL + (((b) * 2 + (h)) * 16384 + (m * 2 + k) * 1024))
; #define LDB(dst, b, h)                                                                                     \
;   _Pragma("unroll") for (int n = 0; n < 2; ++n) _Pragma("unroll") for (int k = 0; k < 2; ++k) dst[n][k] = \
;       *reinterpret_cast<const bf16x8*>(shmc + bL + (((b) * 2 + (h)) * 16384 + (n * 2 + k) * 1024))
; #define WAIT_V(n) asm volatile("s_waitcnt vmcnt(" #n ")" ::: "memory")
; #define WAIT_L(n) asm volatile("s_waitcnt lgkmcnt(" #n ")" ::: "memory")
; #define BAR __builtin_amdgcn_s_barrier()
; #define SCHED __builtin_amdgcn_sched_barrier(0)
; template <int EPI>
; __device__ __forceinline__ void phase_gemm(const Params& p, const GemmDesc& d, char* shmc) {
;     ...
;       LDB(B0, 1, 0); SCHED; LDA(At, 1, 0); STAGE_A(SA(0, 1), 1, t + 2);
;       WAIT_L(8); BAR; WAIT_L(0); MMA(0, 0, At, B0); BAR; SCHED;
;       LDB(B1, 1, 1); STAGE_B(SB(1, 0), 0, t + 3);
;       BAR; WAIT_L(0); MMA(0, 1, At, B1); BAR;
;       LDA(At, 1, 1); STAGE_A(SA(1, 0), 0, t + 3);
;       BAR; WAIT_L(0); MMA(1, 0, At, B0); BAR; SCHED;
;       STAGE_B(SB(1, 1), 1, t + 3);
;       WAIT_V(6); BAR; MMA(1, 1, At, B1); BAR;
;     }
	s_setprio 0
	s_mov_b32 m0, s85
	s_nop 0
	global_load_lds_dwordx4 v230, s[98:99]
	s_mov_b32 m0, s86
	s_nop 0
	global_load_lds_dwordx4 v231, s[98:99]
	ds_read_b128 v[138:141], v162 offset:32768
	ds_read_b128 v[142:145], v162 offset:33792
	ds_read_b128 v[146:149], v162 offset:34816
	ds_read_b128 v[150:153], v162 offset:35840
	ds_read_b128 v[208:211], v162 offset:49152
	ds_read_b128 v[212:215], v162 offset:50176
	ds_read_b128 v[216:219], v162 offset:51200
	ds_read_b128 v[220:223], v162 offset:52224
	ds_read_b128 v[154:157], v175 offset:32768
	ds_read_b128 v[158:161], v175 offset:33792
	ds_read_b128 v[178:181], v175 offset:34816
	ds_read_b128 v[182:185], v175 offset:35840
	ds_read_b128 v[186:189], v175 offset:36864
	ds_read_b128 v[190:193], v175 offset:37888
	ds_read_b128 v[194:197], v175 offset:38912
	ds_read_b128 v[198:201], v175 offset:39936
	s_waitcnt vmcnt(8)
	s_waitcnt lgkmcnt(0)
	s_setprio 1
	s_barrier
	v_mfma_f32_16x16x32_bf16 v[2:5], v[154:157], v[138:141], v[2:5]
	v_mfma_f32_16x16x32_bf16 v[6:9], v[154:157], v[146:149], v[6:9]
	v_mfma_f32_16x16x32_bf16 v[10:13], v[178:181], v[138:141], v[10:13]
	v_mfma_f32_16x16x32_bf16 v[18:21], v[178:181], v[146:149], v[18:21]
	v_mfma_f32_16x16x32_bf16 v[30:33], v[186:189], v[138:141], v[30:33]
	v_mfma_f32_16x16x32_bf16 v[42:45], v[186:189], v[146:149], v[42:45]
	v_mfma_f32_16x16x32_bf16 v[54:57], v[194:197], v[138:141], v[54:57]
	v_mfma_f32_16x16x32_bf16 v[66:69], v[194:197], v[146:149], v[66:69]
	v_mfma_f32_16x16x32_bf16 v[2:5], v[158:161], v[142:145], v[2:5]
	v_mfma_f32_16x16x32_bf16 v[6:9], v[158:161], v[150:153], v[6:9]
	v_mfma_f32_16x16x32_bf16 v[10:13], v[182:185], v[142:145], v[10:13]
	v_mfma_f32_16x16x32_bf16 v[18:21], v[182:185], v[150:153], v[18:21]
	v_mfma_f32_16x16x32_bf16 v[30:33], v[190:193], v[142:145], v[30:33]
	v_mfma_f32_16x16x32_bf16 v[42:45], v[190:193], v[150:153], v[42:45]
	v_mfma_f32_16x16x32_bf16 v[54:57], v[198:201], v[142:145], v[54:57]
	v_mfma_f32_16x16x32_bf16 v[66:69], v[198:201], v[150:153], v[66:69]
	v_mfma_f32_16x16x32_bf16 v[14:17], v[154:157], v[208:211], v[14:17]
	v_mfma_f32_16x16x32_bf16 v[22:25], v[154:157], v[216:219], v[22:25]
	v_mfma_f32_16x16x32_bf16 v[34:37], v[178:181], v[208:211], v[34:37]
	v_mfma_f32_16x16x32_bf16 v[46:49], v[178:181], v[216:219], v[46:49]
	v_mfma_f32_16x16x32_bf16 v[58:61], v[186:189], v[208:211], v[58:61]
	v_mfma_f32_16x16x32_bf16 v[70:73], v[186:189], v[216:219], v[70:73]
	v_mfma_f32_16x16x32_bf16 v[78:81], v[194:197], v[208:211], v[78:81]
	v_mfma_f32_16x16x32_bf16 v[86:89], v[194:197], v[216:219], v[86:89]
	v_mfma_f32_16x16x32_bf16 v[14:17], v[158:161], v[212:215], v[14:17]
	v_mfma_f32_16x16x32_bf16 v[22:25], v[158:161], v[220:223], v[22:25]
	v_mfma_f32_16x16x32_bf16 v[34:37], v[182:185], v[212:215], v[34:37]
	v_mfma_f32_16x16x32_bf16 v[46:49], v[182:185], v[220:223], v[46:49]
	v_mfma_f32_16x16x32_bf16 v[58:61], v[190:193], v[212:215], v[58:61]
	v_mfma_f32_16x16x32_bf16 v[70:73], v[190:193], v[220:223], v[70:73]
	v_mfma_f32_16x16x32_bf16 v[78:81], v[198:201], v[212:215], v[78:81]
	v_mfma_f32_16x16x32_bf16 v[86:89], v[198:201], v[220:223], v[86:89]
	s_barrier
	s_setprio 0
	s_mov_b32 m0, s87
	s_nop 0
	global_load_lds_dwordx4 v232, s[100:101]
	s_mov_b32 m0, s88
	s_nop 0
	global_load_lds_dwordx4 v233, s[100:101]
	s_mov_b32 m0, s89
	s_nop 0
	global_load_lds_dwordx4 v234, s[98:99]
	s_mov_b32 m0, s90
	s_nop 0
	global_load_lds_dwordx4 v235, s[98:99]
	s_mov_b32 m0, s91
	s_nop 0
	global_load_lds_dwordx4 v236, s[100:101]
	s_mov_b32 m0, s92
	s_nop 0
	global_load_lds_dwordx4 v237, s[100:101]
	ds_read_b128 v[154:157], v175 offset:49152
	ds_read_b128 v[158:161], v175 offset:50176
	ds_read_b128 v[178:181], v175 offset:51200
	ds_read_b128 v[182:185], v175 offset:52224
	ds_read_b128 v[186:189], v175 offset:53248
	ds_read_b128 v[190:193], v175 offset:54272
	ds_read_b128 v[194:197], v175 offset:55296
	ds_read_b128 v[198:201], v175 offset:56320
	s_add_i32 s35, s35, 2
	s_add_u32 s10, s10, 0x100
	s_addc_u32 s11, s11, 0
	s_add_u32 s98, s98, 0x100
	s_addc_u32 s99, s99, 0
	s_add_u32 s100, s100, 0x100
	s_addc_u32 s101, s101, 0
	s_cmp_gt_u32 s35, 27
	s_waitcnt vmcnt(8)
	s_waitcnt lgkmcnt(0)
	s_setprio 1
	s_barrier
	v_mfma_f32_16x16x32_bf16 v[26:29], v[154:157], v[138:141], v[26:29]
	v_mfma_f32_16x16x32_bf16 v[38:41], v[154:157], v[146:149], v[38:41]
	v_mfma_f32_16x16x32_bf16 v[50:53], v[178:181], v[138:141], v[50:53]
	v_mfma_f32_16x16x32_bf16 v[62:65], v[178:181], v[146:149], v[62:65]
	v_mfma_f32_16x16x32_bf16 v[74:77], v[186:189], v[138:141], v[74:77]
	v_mfma_f32_16x16x32_bf16 v[82:85], v[186:189], v[146:149], v[82:85]
	v_mfma_f32_16x16x32_bf16 v[90:93], v[194:197], v[138:141], v[90:93]
	v_mfma_f32_16x16x32_bf16 v[94:97], v[194:197], v[146:149], v[94:97]
	v_mfma_f32_16x16x32_bf16 v[26:29], v[158:161], v[142:145], v[26:29]
	v_mfma_f32_16x16x32_bf16 v[38:41], v[158:161], v[150:153], v[38:41]
	v_mfma_f32_16x16x32_bf16 v[50:53], v[182:185], v[142:145], v[50:53]
	v_mfma_f32_16x16x32_bf16 v[62:65], v[182:185], v[150:153], v[62:65]
	v_mfma_f32_16x16x32_bf16 v[74:77], v[190:193], v[142:145], v[74:77]
	v_mfma_f32_16x16x32_bf16 v[82:85], v[190:193], v[150:153], v[82:85]
	v_mfma_f32_16x16x32_bf16 v[90:93], v[198:201], v[142:145], v[90:93]
	v_mfma_f32_16x16x32_bf16 v[94:97], v[198:201], v[150:153], v[94:97]
	v_mfma_f32_16x16x32_bf16 v[98:101], v[154:157], v[208:211], v[98:101]
	v_mfma_f32_16x16x32_bf16 v[102:105], v[154:157], v[216:219], v[102:105]
	v_mfma_f32_16x16x32_bf16 v[106:109], v[178:181], v[208:211], v[106:109]
	v_mfma_f32_16x16x32_bf16 v[110:113], v[178:181], v[216:219], v[110:113]
	v_mfma_f32_16x16x32_bf16 v[114:117], v[186:189], v[208:211], v[114:117]
	v_mfma_f32_16x16x32_bf16 v[118:121], v[186:189], v[216:219], v[118:121]
	v_mfma_f32_16x16x32_bf16 v[122:125], v[194:197], v[208:211], v[122:125]
	v_mfma_f32_16x16x32_bf16 v[126:129], v[194:197], v[216:219], v[126:129]
	v_mfma_f32_16x16x32_bf16 v[98:101], v[158:161], v[212:215], v[98:101]
	v_mfma_f32_16x16x32_bf16 v[102:105], v[158:161], v[220:223], v[102:105]
	v_mfma_f32_16x16x32_bf16 v[106:109], v[182:185], v[212:215], v[106:109]
	v_mfma_f32_16x16x32_bf16 v[110:113], v[182:185], v[220:223], v[110:113]
	v_mfma_f32_16x16x32_bf16 v[114:117], v[190:193], v[212:215], v[114:117]
	v_mfma_f32_16x16x32_bf16 v[118:121], v[190:193], v[220:223], v[118:121]
	v_mfma_f32_16x16x32_bf16 v[122:125], v[198:201], v[212:215], v[122:125]
	v_mfma_f32_16x16x32_bf16 v[126:129], v[198:201], v[220:223], v[126:129]
	s_barrier
; #define LDA(dst, b, h)                                                                                     \
;   _Pragma("unroll") for (int m = 0; m < 4; ++m) _Pragma("unroll") for (int k = 0; k < 2; ++k) dst[m][k] = \
;       *reinterpret_cast<const bf16x8*>(shmc + aL + (((b) * 2 + (h)) * 16384 + (m * 2 + k) * 1024))
; #define LDB(dst, b, h)                                                                                     \
;   _Pragma("unroll") for (int n = 0; n < 2; ++n) _Pragma("unroll") for (int k = 0; k < 2; ++k) dst[n][k] = \
;       *reinterpret_cast<const bf16x8*>(shmc + bL + (((b) * 2 + (h)) * 16384 + (n * 2 + k) * 1024))
; #define OPAQ asm volatile("" : "+v"(aL), "+v"(bL))
; #define WAIT_V(n) asm volatile("s_waitcnt vmcnt(" #n ")" ::: "memory")
; #define WAIT_L(n) asm volatile("s_waitcnt lgkmcnt(" #n ")" ::: "memory")
; #define BAR __builtin_amdgcn_s_barrier()
; template <int EPI>
; __device__ __forceinline__ void phase_gemm(const Params& p, const GemmDesc& d, char* shmc) {
;     ...
;     {
;       OPAQ;
;       LDB(B0, 0, 0); LDA(At, 0, 0); STAGE_A(SA(1, 1), 1, nt - 1);
;       BAR; WAIT_L(0); MMA(0, 0, At, B0); BAR;
;       LDB(B1, 0, 1); BAR; WAIT_L(0); MMA(0, 1, At, B1); BAR;
;       LDA(At, 0, 1); WAIT_V(4); BAR; WAIT_L(0); MMA(1, 0, At, B0); MMA(1, 1, At, B1); BAR;
;     }
	s_cbranch_scc0 .LBB0_296
	s_setprio 0
	s_add_u32 s8, s8, 0x80f80
	s_addc_u32 s9, s9, 0
	v_add_u32_e32 v162, 0, v205
	v_add_u32_e32 v175, 0, v204
	s_mov_b32 m0, s93
	ds_read_b128 v[130:133], v162
	ds_read_b128 v[134:137], v162 offset:1024
	ds_read_b128 v[138:141], v162 offset:2048
	ds_read_b128 v[142:145], v162 offset:3072
	ds_read_b128 v[146:149], v175
	ds_read_b128 v[150:153], v175 offset:1024
	ds_read_b128 v[154:157], v175 offset:2048
	ds_read_b128 v[158:161], v175 offset:3072
	ds_read_b128 v[178:181], v175 offset:4096
	ds_read_b128 v[182:185], v175 offset:5120
	ds_read_b128 v[186:189], v175 offset:6144
	ds_read_b128 v[190:193], v175 offset:7168
	global_load_lds_dwordx4 v174, s[8:9]
	s_mov_b32 m0, s94
	s_nop 0
	global_load_lds_dwordx4 v176, s[8:9]
	s_waitcnt vmcnt(8)
	s_barrier
	s_waitcnt lgkmcnt(0)
	s_setprio 1
	s_waitcnt lgkmcnt(0)
	v_mfma_f32_16x16x32_bf16 v[2:5], v[146:149], v[130:133], v[2:5]
	v_mfma_f32_16x16x32_bf16 v[6:9], v[146:149], v[138:141], v[6:9]
	v_mfma_f32_16x16x32_bf16 v[10:13], v[154:157], v[130:133], v[10:13]
	v_mfma_f32_16x16x32_bf16 v[18:21], v[154:157], v[138:141], v[18:21]
	v_mfma_f32_16x16x32_bf16 v[66:69], v[186:189], v[138:141], v[66:69]
	v_mfma_f32_16x16x32_bf16 v[2:5], v[150:153], v[134:137], v[2:5]
	v_mfma_f32_16x16x32_bf16 v[6:9], v[150:153], v[142:145], v[6:9]
	v_mfma_f32_16x16x32_bf16 v[10:13], v[158:161], v[134:137], v[10:13]
	v_mfma_f32_16x16x32_bf16 v[18:21], v[158:161], v[142:145], v[18:21]
	v_mfma_f32_16x16x32_bf16 v[30:33], v[178:181], v[130:133], v[30:33]
	v_mfma_f32_16x16x32_bf16 v[42:45], v[178:181], v[138:141], v[42:45]
	v_mfma_f32_16x16x32_bf16 v[54:57], v[186:189], v[130:133], v[54:57]
	v_mfma_f32_16x16x32_bf16 v[66:69], v[190:193], v[142:145], v[66:69]
	v_mfma_f32_16x16x32_bf16 v[30:33], v[182:185], v[134:137], v[30:33]
	v_mfma_f32_16x16x32_bf16 v[42:45], v[182:185], v[142:145], v[42:45]
	v_mfma_f32_16x16x32_bf16 v[54:57], v[190:193], v[134:137], v[54:57]
	s_setprio 0
	s_barrier
	ds_read_b128 v[194:197], v162 offset:16384
	ds_read_b128 v[198:201], v162 offset:17408
	ds_read_b128 v[208:211], v162 offset:18432
	ds_read_b128 v[212:215], v162 offset:19456
	s_barrier
	s_waitcnt lgkmcnt(0)
	s_setprio 1
	s_waitcnt lgkmcnt(0)
	v_mfma_f32_16x16x32_bf16 v[14:17], v[146:149], v[194:197], v[14:17]
	v_mfma_f32_16x16x32_bf16 v[22:25], v[146:149], v[208:211], v[22:25]
	v_mfma_f32_16x16x32_bf16 v[58:61], v[178:181], v[194:197], v[58:61]
	v_mfma_f32_16x16x32_bf16 v[14:17], v[150:153], v[198:201], v[14:17]
	v_mfma_f32_16x16x32_bf16 v[22:25], v[150:153], v[212:215], v[22:25]
	v_mfma_f32_16x16x32_bf16 v[150:153], v[182:185], v[198:201], v[58:61]
	v_mfma_f32_16x16x32_bf16 v[58:61], v[178:181], v[208:211], v[70:73]
	v_mfma_f32_16x16x32_bf16 v[34:37], v[154:157], v[194:197], v[34:37]
	v_mfma_f32_16x16x32_bf16 v[46:49], v[154:157], v[208:211], v[46:49]
	v_mfma_f32_16x16x32_bf16 v[154:157], v[182:185], v[212:215], v[58:61]
	v_mfma_f32_16x16x32_bf16 v[58:61], v[186:189], v[194:197], v[78:81]
	v_mfma_f32_16x16x32_bf16 v[78:81], v[190:193], v[198:201], v[58:61]
	v_mfma_f32_16x16x32_bf16 v[58:61], v[186:189], v[208:211], v[86:89]
	v_mfma_f32_16x16x32_bf16 v[86:89], v[190:193], v[212:215], v[58:61]
	v_mfma_f32_16x16x32_bf16 v[34:37], v[158:161], v[198:201], v[34:37]
	v_mfma_f32_16x16x32_bf16 v[46:49], v[158:161], v[212:215], v[46:49]
	s_setprio 0
	s_barrier
	s_nop 2
	ds_read_b128 v[58:61], v175 offset:16384
	ds_read_b128 v[70:73], v175 offset:17408
	ds_read_b128 v[146:149], v175 offset:18432
	ds_read_b128 v[158:161], v175 offset:19456
	ds_read_b128 v[178:181], v175 offset:20480
	ds_read_b128 v[182:185], v175 offset:21504
	ds_read_b128 v[186:189], v175 offset:22528
	ds_read_b128 v[190:193], v175 offset:23552
	s_waitcnt vmcnt(4)
	s_barrier
	s_waitcnt lgkmcnt(0)
	s_setprio 1
	s_waitcnt lgkmcnt(0)
	v_mfma_f32_16x16x32_bf16 v[74:77], v[178:181], v[130:133], v[74:77]
	v_mfma_f32_16x16x32_bf16 v[216:219], v[182:185], v[134:137], v[74:77]
	v_mfma_f32_16x16x32_bf16 v[74:77], v[178:181], v[138:141], v[82:85]
	v_mfma_f32_16x16x32_bf16 v[26:29], v[58:61], v[130:133], v[26:29]
	v_mfma_f32_16x16x32_bf16 v[82:85], v[182:185], v[142:145], v[74:77]
	v_mfma_f32_16x16x32_bf16 v[74:77], v[186:189], v[130:133], v[90:93]
	v_mfma_f32_16x16x32_bf16 v[26:29], v[70:73], v[134:137], v[26:29]
	v_mfma_f32_16x16x32_bf16 v[38:41], v[58:61], v[138:141], v[38:41]
	v_mfma_f32_16x16x32_bf16 v[50:53], v[146:149], v[130:133], v[50:53]
	v_mfma_f32_16x16x32_bf16 v[62:65], v[146:149], v[138:141], v[62:65]
	v_mfma_f32_16x16x32_bf16 v[90:93], v[190:193], v[134:137], v[74:77]
	v_mfma_f32_16x16x32_bf16 v[74:77], v[186:189], v[138:141], v[94:97]
	v_mfma_f32_16x16x32_bf16 v[38:41], v[70:73], v[142:145], v[38:41]
	v_mfma_f32_16x16x32_bf16 v[50:53], v[158:161], v[134:137], v[50:53]
	v_mfma_f32_16x16x32_bf16 v[62:65], v[158:161], v[142:145], v[62:65]
	v_mfma_f32_16x16x32_bf16 v[220:223], v[190:193], v[142:145], v[74:77]
	s_setprio 0
	s_setprio 1
	v_mfma_f32_16x16x32_bf16 v[74:77], v[58:61], v[194:197], v[98:101]
	v_mfma_f32_16x16x32_bf16 v[58:61], v[58:61], v[208:211], v[102:105]
	v_mfma_f32_16x16x32_bf16 v[228:231], v[70:73], v[212:215], v[58:61]
	v_mfma_f32_16x16x32_bf16 v[58:61], v[146:149], v[194:197], v[106:109]
	v_mfma_f32_16x16x32_bf16 v[232:235], v[158:161], v[198:201], v[58:61]
	v_mfma_f32_16x16x32_bf16 v[58:61], v[146:149], v[208:211], v[110:113]
	v_mfma_f32_16x16x32_bf16 v[236:239], v[158:161], v[212:215], v[58:61]
	v_mfma_f32_16x16x32_bf16 v[58:61], v[178:181], v[194:197], v[114:117]
	v_mfma_f32_16x16x32_bf16 v[240:243], v[182:185], v[198:201], v[58:61]
	v_mfma_f32_16x16x32_bf16 v[58:61], v[178:181], v[208:211], v[118:121]
	v_mfma_f32_16x16x32_bf16 v[178:181], v[182:185], v[212:215], v[58:61]
	v_mfma_f32_16x16x32_bf16 v[58:61], v[186:189], v[194:197], v[122:125]
	v_mfma_f32_16x16x32_bf16 v[182:185], v[190:193], v[198:201], v[58:61]
	v_mfma_f32_16x16x32_bf16 v[58:61], v[186:189], v[208:211], v[126:129]
	v_mfma_f32_16x16x32_bf16 v[224:227], v[70:73], v[198:201], v[74:77]
	v_mfma_f32_16x16x32_bf16 v[186:189], v[190:193], v[212:215], v[58:61]
	s_setprio 0
	s_barrier
; #define LDA(dst, b, h)                                                                                     \
;   _Pragma("unroll") for (int m = 0; m < 4; ++m) _Pragma("unroll") for (int k = 0; k < 2; ++k) dst[m][k] = \
;       *reinterpret_cast<const bf16x8*>(shmc + aL + (((b) * 2 + (h)) * 16384 + (m * 2 + k) * 1024))
; #define LDB(dst, b, h)                                                                                     \
;   _Pragma("unroll") for (int n = 0; n < 2; ++n) _Pragma("unroll") for (int k = 0; k < 2; ++k) dst[n][k] = \
;       *reinterpret_cast<const bf16x8*>(shmc + bL + (((b) * 2 + (h)) * 16384 + (n * 2 + k) * 1024))
; #define WAIT_V(n) asm volatile("s_waitcnt vmcnt(" #n ")" ::: "memory")
; #define WAIT_L(n) asm volatile("s_waitcnt lgkmcnt(" #n ")" ::: "memory")
; #define BAR __builtin_amdgcn_s_barrier()
; template <int EPI>
; __device__ __forceinline__ void phase_gemm(const Params& p, const GemmDesc& d, char* shmc) {
;     ...
;     {
;       LDB(B0, 1, 0); LDA(At, 1, 0); WAIT_V(2); BAR; WAIT_L(0); MMA(0, 0, At, B0); BAR;
;       LDB(B1, 1, 1); WAIT_V(0); BAR; WAIT_L(0); MMA(0, 1, At, B1); BAR;
;       LDA(At, 1, 1); BAR; WAIT_L(0); MMA(1, 0, At, B0); MMA(1, 1, At, B1); BAR;
;     }
;     if (wr == 0) BAR;
	ds_read_b128 v[98:101], v162 offset:32768
	ds_read_b128 v[106:109], v162 offset:33792
	ds_read_b128 v[190:193], v162 offset:34816
	ds_read_b128 v[194:197], v162 offset:35840
	ds_read_b128 v[58:61], v175 offset:32768
	ds_read_b128 v[70:73], v175 offset:33792
	ds_read_b128 v[114:117], v175 offset:34816
	ds_read_b128 v[122:125], v175 offset:35840
	ds_read_b128 v[130:133], v175 offset:36864
	ds_read_b128 v[138:141], v175 offset:37888
	ds_read_b128 v[198:201], v175 offset:38912
	ds_read_b128 v[208:211], v175 offset:39936
	s_waitcnt vmcnt(2)
	s_barrier
	s_waitcnt lgkmcnt(0)
	s_setprio 1
	s_waitcnt lgkmcnt(0)
	v_mfma_f32_16x16x32_bf16 v[2:5], v[58:61], v[98:101], v[2:5]
	v_mfma_f32_16x16x32_bf16 v[158:161], v[70:73], v[106:109], v[2:5]
	v_mfma_f32_16x16x32_bf16 v[2:5], v[58:61], v[190:193], v[6:9]
	v_mfma_f32_16x16x32_bf16 v[146:149], v[70:73], v[194:197], v[2:5]
	v_mfma_f32_16x16x32_bf16 v[2:5], v[114:117], v[98:101], v[10:13]
	v_mfma_f32_16x16x32_bf16 v[142:145], v[122:125], v[106:109], v[2:5]
	v_mfma_f32_16x16x32_bf16 v[2:5], v[114:117], v[190:193], v[18:21]
	v_mfma_f32_16x16x32_bf16 v[134:137], v[122:125], v[194:197], v[2:5]
	v_mfma_f32_16x16x32_bf16 v[2:5], v[130:133], v[98:101], v[30:33]
	v_mfma_f32_16x16x32_bf16 v[126:129], v[138:141], v[106:109], v[2:5]
	v_mfma_f32_16x16x32_bf16 v[2:5], v[130:133], v[190:193], v[42:45]
	v_mfma_f32_16x16x32_bf16 v[118:121], v[138:141], v[194:197], v[2:5]
	v_mfma_f32_16x16x32_bf16 v[2:5], v[198:201], v[98:101], v[54:57]
	v_mfma_f32_16x16x32_bf16 v[110:113], v[208:211], v[106:109], v[2:5]
	v_mfma_f32_16x16x32_bf16 v[2:5], v[198:201], v[190:193], v[66:69]
	v_mfma_f32_16x16x32_bf16 v[102:105], v[208:211], v[194:197], v[2:5]
	s_setprio 0
	s_barrier
	ds_read_b128 v[30:33], v162 offset:49152
	ds_read_b128 v[42:45], v162 offset:50176
	ds_read_b128 v[54:57], v162 offset:51200
	ds_read_b128 v[212:215], v162 offset:52224
	s_waitcnt vmcnt(0)
	s_barrier
	s_waitcnt lgkmcnt(0)
	s_setprio 1
	s_waitcnt lgkmcnt(0)
	v_mfma_f32_16x16x32_bf16 v[2:5], v[58:61], v[30:33], v[14:17]
	v_mfma_f32_16x16x32_bf16 v[94:97], v[70:73], v[42:45], v[2:5]
	v_mfma_f32_16x16x32_bf16 v[2:5], v[58:61], v[54:57], v[22:25]
	v_mfma_f32_16x16x32_bf16 v[58:61], v[70:73], v[212:215], v[2:5]
	v_mfma_f32_16x16x32_bf16 v[2:5], v[114:117], v[30:33], v[34:37]
	v_mfma_f32_16x16x32_bf16 v[74:77], v[122:125], v[42:45], v[2:5]
	v_mfma_f32_16x16x32_bf16 v[2:5], v[114:117], v[54:57], v[46:49]
	v_mfma_f32_16x16x32_bf16 v[10:13], v[122:125], v[212:215], v[2:5]
	v_mfma_f32_16x16x32_bf16 v[2:5], v[130:133], v[30:33], v[150:153]
	v_mfma_f32_16x16x32_bf16 v[70:73], v[138:141], v[42:45], v[2:5]
	v_mfma_f32_16x16x32_bf16 v[2:5], v[130:133], v[54:57], v[154:157]
	v_mfma_f32_16x16x32_bf16 v[6:9], v[138:141], v[212:215], v[2:5]
	v_mfma_f32_16x16x32_bf16 v[2:5], v[198:201], v[30:33], v[78:81]
	v_mfma_f32_16x16x32_bf16 v[66:69], v[208:211], v[42:45], v[2:5]
	v_mfma_f32_16x16x32_bf16 v[2:5], v[198:201], v[54:57], v[86:89]
	v_mfma_f32_16x16x32_bf16 v[2:5], v[208:211], v[212:215], v[2:5]
	s_setprio 0
	s_barrier
	ds_read_b128 v[14:17], v175 offset:49152
	ds_read_b128 v[18:21], v175 offset:50176
	ds_read_b128 v[22:25], v175 offset:51200
	ds_read_b128 v[34:37], v175 offset:52224
	ds_read_b128 v[46:49], v175 offset:53248
	ds_read_b128 v[78:81], v175 offset:54272
	ds_read_b128 v[198:201], v175 offset:55296
	ds_read_b128 v[208:211], v175 offset:56320
	s_barrier
	s_waitcnt lgkmcnt(0)
	s_setprio 1
	s_waitcnt lgkmcnt(0)
	v_mfma_f32_16x16x32_bf16 v[26:29], v[14:17], v[98:101], v[26:29]
	v_mfma_f32_16x16x32_bf16 v[154:157], v[18:21], v[106:109], v[26:29]
	v_mfma_f32_16x16x32_bf16 v[26:29], v[14:17], v[190:193], v[38:41]
	v_mfma_f32_16x16x32_bf16 v[150:153], v[18:21], v[194:197], v[26:29]
	v_mfma_f32_16x16x32_bf16 v[26:29], v[22:25], v[98:101], v[50:53]
	v_mfma_f32_16x16x32_bf16 v[138:141], v[34:37], v[106:109], v[26:29]
	v_mfma_f32_16x16x32_bf16 v[26:29], v[22:25], v[190:193], v[62:65]
	v_mfma_f32_16x16x32_bf16 v[130:133], v[34:37], v[194:197], v[26:29]
	v_mfma_f32_16x16x32_bf16 v[26:29], v[46:49], v[98:101], v[216:219]
	v_mfma_f32_16x16x32_bf16 v[122:125], v[78:81], v[106:109], v[26:29]
	v_mfma_f32_16x16x32_bf16 v[26:29], v[46:49], v[190:193], v[82:85]
	v_mfma_f32_16x16x32_bf16 v[114:117], v[78:81], v[194:197], v[26:29]
	v_mfma_f32_16x16x32_bf16 v[26:29], v[198:201], v[98:101], v[90:93]
	v_mfma_f32_16x16x32_bf16 v[106:109], v[208:211], v[106:109], v[26:29]
	v_mfma_f32_16x16x32_bf16 v[26:29], v[198:201], v[190:193], v[220:223]
	v_mfma_f32_16x16x32_bf16 v[98:101], v[208:211], v[194:197], v[26:29]
	s_setprio 0
	s_setprio 1
	v_mfma_f32_16x16x32_bf16 v[26:29], v[14:17], v[30:33], v[224:227]
	v_mfma_f32_16x16x32_bf16 v[14:17], v[14:17], v[54:57], v[228:231]
	v_mfma_f32_16x16x32_bf16 v[90:93], v[18:21], v[42:45], v[26:29]
	v_mfma_f32_16x16x32_bf16 v[26:29], v[18:21], v[212:215], v[14:17]
	v_mfma_f32_16x16x32_bf16 v[14:17], v[22:25], v[30:33], v[232:235]
	v_mfma_f32_16x16x32_bf16 v[86:89], v[34:37], v[42:45], v[14:17]
	v_mfma_f32_16x16x32_bf16 v[14:17], v[22:25], v[54:57], v[236:239]
	v_mfma_f32_16x16x32_bf16 v[22:25], v[34:37], v[212:215], v[14:17]
	v_mfma_f32_16x16x32_bf16 v[14:17], v[46:49], v[30:33], v[240:243]
	v_mfma_f32_16x16x32_bf16 v[82:85], v[78:81], v[42:45], v[14:17]
	v_mfma_f32_16x16x32_bf16 v[14:17], v[46:49], v[54:57], v[178:181]
	v_mfma_f32_16x16x32_bf16 v[18:21], v[78:81], v[212:215], v[14:17]
	v_mfma_f32_16x16x32_bf16 v[14:17], v[198:201], v[30:33], v[182:185]
	v_mfma_f32_16x16x32_bf16 v[78:81], v[208:211], v[42:45], v[14:17]
	v_mfma_f32_16x16x32_bf16 v[14:17], v[198:201], v[54:57], v[186:189]
	v_mfma_f32_16x16x32_bf16 v[14:17], v[208:211], v[212:215], v[14:17]
	s_setprio 0
	s_barrier
	s_and_saveexec_b64 s[8:9], s[6:7]
	s_cbranch_execz .LBB0_299
	s_barrier

; #define LDA(dst, b, h)                                                                                     \
;   _Pragma("unroll") for (int m = 0; m < 4; ++m) _Pragma("unroll") for (int k = 0; k < 2; ++k) dst[m][k] = \
;       *reinterpret_cast<const bf16x8*>(shmc + aL + (((b) * 2 + (h)) * 16384 + (m * 2 + k) * 1024))
; #define LDB(dst, b, h)                                                                                     \
;   _Pragma("unroll") for (int n = 0; n < 2; ++n) _Pragma("unroll") for (int k = 0; k < 2; ++k) dst[n][k] = \
;       *reinterpret_cast<const bf16x8*>(shmc + bL + (((b) * 2 + (h)) * 16384 + (n * 2 + k) * 1024))
; #define OPAQ asm volatile("" : "+v"(aL), "+v"(bL))
; #define WAIT_V(n) asm volatile("s_waitcnt vmcnt(" #n ")" ::: "memory")
; #define WAIT_L(n) asm volatile("s_waitcnt lgkmcnt(" #n ")" ::: "memory")
; #define BAR __builtin_amdgcn_s_barrier()
; #define SCHED __builtin_amdgcn_sched_barrier(0)
; template <int EPI>
; __device__ __forceinline__ void phase_gemm(const Params& p, const GemmDesc& d, char* shmc) {
;     ...
;     for (int t = 0; t < nt - 2; t += 2) {
;       OPAQ;
;       LDB(B0, 0, 0); SCHED; LDA(At, 0, 0); STAGE_A(SA(1, 1), 1, t + 1);
;       WAIT_L(8); BAR; WAIT_L(0); MMA(0, 0, At, B0); BAR; SCHED;
;       LDB(B1, 0, 1); STAGE_B(SB(0, 0), 0, t + 2);
;       BAR; WAIT_L(0); MMA(0, 1, At, B1); BAR;
;       LDA(At, 0, 1); STAGE_A(SA(0, 0), 0, t + 2);
;       BAR; WAIT_L(0); MMA(1, 0, At, B0); BAR; SCHED;
;       STAGE_B(SB(0, 1), 1, t + 2);
;       WAIT_V(6); BAR; MMA(1, 1, At, B1); BAR;
.LBB0_455:
	s_nop 0
	v_add_u32_e32 v130, 0, v153
	v_add_u32_e32 v141, 0, v152
	s_setprio 0
	s_mov_b32 m0, s70
	s_nop 0
	global_load_lds_dwordx4 v220, s[98:99]
	s_mov_b32 m0, s71
	s_nop 0
	global_load_lds_dwordx4 v221, s[98:99]
	ds_read_b128 v[156:159], v130
	ds_read_b128 v[160:163], v130 offset:1024
	ds_read_b128 v[164:167], v130 offset:2048
	ds_read_b128 v[168:171], v130 offset:3072
	ds_read_b128 v[204:207], v130 offset:16384
	ds_read_b128 v[208:211], v130 offset:17408
	ds_read_b128 v[212:215], v130 offset:18432
	ds_read_b128 v[216:219], v130 offset:19456
	ds_read_b128 v[172:175], v141
	ds_read_b128 v[176:179], v141 offset:1024
	ds_read_b128 v[180:183], v141 offset:2048
	ds_read_b128 v[184:187], v141 offset:3072
	ds_read_b128 v[188:191], v141 offset:4096
	ds_read_b128 v[192:195], v141 offset:5120
	ds_read_b128 v[196:199], v141 offset:6144
	ds_read_b128 v[200:203], v141 offset:7168
	s_waitcnt vmcnt(8)
	s_waitcnt lgkmcnt(0)
	s_setprio 1
	s_barrier
	v_mfma_f32_16x16x32_bf16 v[126:129], v[156:159], v[172:175], v[126:129]
	v_mfma_f32_16x16x32_bf16 v[122:125], v[164:167], v[172:175], v[122:125]
	v_mfma_f32_16x16x32_bf16 v[118:121], v[156:159], v[180:183], v[118:121]
	v_mfma_f32_16x16x32_bf16 v[114:117], v[164:167], v[180:183], v[114:117]
	v_mfma_f32_16x16x32_bf16 v[110:113], v[156:159], v[188:191], v[110:113]
	v_mfma_f32_16x16x32_bf16 v[106:109], v[164:167], v[188:191], v[106:109]
	v_mfma_f32_16x16x32_bf16 v[102:105], v[156:159], v[196:199], v[102:105]
	v_mfma_f32_16x16x32_bf16 v[98:101], v[164:167], v[196:199], v[98:101]
	v_mfma_f32_16x16x32_bf16 v[126:129], v[160:163], v[176:179], v[126:129]
	v_mfma_f32_16x16x32_bf16 v[122:125], v[168:171], v[176:179], v[122:125]
	v_mfma_f32_16x16x32_bf16 v[118:121], v[160:163], v[184:187], v[118:121]
	v_mfma_f32_16x16x32_bf16 v[114:117], v[168:171], v[184:187], v[114:117]
	v_mfma_f32_16x16x32_bf16 v[110:113], v[160:163], v[192:195], v[110:113]
	v_mfma_f32_16x16x32_bf16 v[106:109], v[168:171], v[192:195], v[106:109]
	v_mfma_f32_16x16x32_bf16 v[102:105], v[160:163], v[200:203], v[102:105]
	v_mfma_f32_16x16x32_bf16 v[98:101], v[168:171], v[200:203], v[98:101]
	v_mfma_f32_16x16x32_bf16 v[86:89], v[204:207], v[172:175], v[86:89]
	v_mfma_f32_16x16x32_bf16 v[70:73], v[212:215], v[172:175], v[70:73]
	v_mfma_f32_16x16x32_bf16 v[54:57], v[204:207], v[180:183], v[54:57]
	v_mfma_f32_16x16x32_bf16 v[50:53], v[212:215], v[180:183], v[50:53]
	v_mfma_f32_16x16x32_bf16 v[46:49], v[204:207], v[188:191], v[46:49]
	v_mfma_f32_16x16x32_bf16 v[42:45], v[212:215], v[188:191], v[42:45]
	v_mfma_f32_16x16x32_bf16 v[38:41], v[204:207], v[196:199], v[38:41]
	v_mfma_f32_16x16x32_bf16 v[34:37], v[212:215], v[196:199], v[34:37]
	v_mfma_f32_16x16x32_bf16 v[86:89], v[208:211], v[176:179], v[86:89]
	v_mfma_f32_16x16x32_bf16 v[70:73], v[216:219], v[176:179], v[70:73]
	v_mfma_f32_16x16x32_bf16 v[54:57], v[208:211], v[184:187], v[54:57]
	v_mfma_f32_16x16x32_bf16 v[50:53], v[216:219], v[184:187], v[50:53]
	v_mfma_f32_16x16x32_bf16 v[46:49], v[208:211], v[192:195], v[46:49]
	v_mfma_f32_16x16x32_bf16 v[42:45], v[216:219], v[192:195], v[42:45]
	v_mfma_f32_16x16x32_bf16 v[38:41], v[208:211], v[200:203], v[38:41]
	v_mfma_f32_16x16x32_bf16 v[34:37], v[216:219], v[200:203], v[34:37]
	s_barrier
	s_setprio 0
	s_mov_b32 m0, s33
	s_nop 0
	global_load_lds_dwordx4 v222, s[100:101]
	s_mov_b32 m0, s34
	s_nop 0
	global_load_lds_dwordx4 v223, s[100:101]
	s_mov_b32 m0, s14
	s_nop 0
	global_load_lds_dwordx4 v224, s[98:99]
	s_mov_b32 m0, s35
	s_nop 0
	global_load_lds_dwordx4 v225, s[98:99]
	s_mov_b32 m0, s58
	s_nop 0
	global_load_lds_dwordx4 v226, s[100:101]
	s_mov_b32 m0, s59
	s_nop 0
	global_load_lds_dwordx4 v227, s[100:101]
	ds_read_b128 v[172:175], v141 offset:16384
	ds_read_b128 v[176:179], v141 offset:17408
	ds_read_b128 v[180:183], v141 offset:18432
	ds_read_b128 v[184:187], v141 offset:19456
	ds_read_b128 v[188:191], v141 offset:20480
	ds_read_b128 v[192:195], v141 offset:21504
	ds_read_b128 v[196:199], v141 offset:22528
	ds_read_b128 v[200:203], v141 offset:23552
	s_waitcnt vmcnt(8)
	s_waitcnt lgkmcnt(0)
	s_setprio 1
	s_barrier
	v_mfma_f32_16x16x32_bf16 v[30:33], v[156:159], v[172:175], v[30:33]
	v_mfma_f32_16x16x32_bf16 v[26:29], v[164:167], v[172:175], v[26:29]
	v_mfma_f32_16x16x32_bf16 v[22:25], v[156:159], v[180:183], v[22:25]
	v_mfma_f32_16x16x32_bf16 v[18:21], v[164:167], v[180:183], v[18:21]
	v_mfma_f32_16x16x32_bf16 v[14:17], v[156:159], v[188:191], v[14:17]
	v_mfma_f32_16x16x32_bf16 v[10:13], v[164:167], v[188:191], v[10:13]
	v_mfma_f32_16x16x32_bf16 v[6:9], v[156:159], v[196:199], v[6:9]
	v_mfma_f32_16x16x32_bf16 v[2:5], v[164:167], v[196:199], v[2:5]
	v_mfma_f32_16x16x32_bf16 v[30:33], v[160:163], v[176:179], v[30:33]
	v_mfma_f32_16x16x32_bf16 v[26:29], v[168:171], v[176:179], v[26:29]
	v_mfma_f32_16x16x32_bf16 v[22:25], v[160:163], v[184:187], v[22:25]
	v_mfma_f32_16x16x32_bf16 v[18:21], v[168:171], v[184:187], v[18:21]
	v_mfma_f32_16x16x32_bf16 v[14:17], v[160:163], v[192:195], v[14:17]
	v_mfma_f32_16x16x32_bf16 v[10:13], v[168:171], v[192:195], v[10:13]
	v_mfma_f32_16x16x32_bf16 v[6:9], v[160:163], v[200:203], v[6:9]
	v_mfma_f32_16x16x32_bf16 v[2:5], v[168:171], v[200:203], v[2:5]
	v_mfma_f32_16x16x32_bf16 v[58:61], v[204:207], v[172:175], v[58:61]
	v_mfma_f32_16x16x32_bf16 v[62:65], v[212:215], v[172:175], v[62:65]
	v_mfma_f32_16x16x32_bf16 v[66:69], v[204:207], v[180:183], v[66:69]
	v_mfma_f32_16x16x32_bf16 v[74:77], v[212:215], v[180:183], v[74:77]
	v_mfma_f32_16x16x32_bf16 v[78:81], v[204:207], v[188:191], v[78:81]
	v_mfma_f32_16x16x32_bf16 v[82:85], v[212:215], v[188:191], v[82:85]
	v_mfma_f32_16x16x32_bf16 v[90:93], v[204:207], v[196:199], v[90:93]
	v_mfma_f32_16x16x32_bf16 v[94:97], v[212:215], v[196:199], v[94:97]
	v_mfma_f32_16x16x32_bf16 v[58:61], v[208:211], v[176:179], v[58:61]
	v_mfma_f32_16x16x32_bf16 v[62:65], v[216:219], v[176:179], v[62:65]
	v_mfma_f32_16x16x32_bf16 v[66:69], v[208:211], v[184:187], v[66:69]
	v_mfma_f32_16x16x32_bf16 v[74:77], v[216:219], v[184:187], v[74:77]
	v_mfma_f32_16x16x32_bf16 v[78:81], v[208:211], v[192:195], v[78:81]
	v_mfma_f32_16x16x32_bf16 v[82:85], v[216:219], v[192:195], v[82:85]
	v_mfma_f32_16x16x32_bf16 v[90:93], v[208:211], v[200:203], v[90:93]
	v_mfma_f32_16x16x32_bf16 v[94:97], v[216:219], v[200:203], v[94:97]
	s_barrier
; #define LDA(dst, b, h)                                                                                     \
;   _Pragma("unroll") for (int m = 0; m < 4; ++m) _Pragma("unroll") for (int k = 0; k < 2; ++k) dst[m][k] = \
;       *reinterpret_cast<const bf16x8*>(shmc + aL + (((b) * 2 + (h)) * 16384 + (m * 2 + k) * 1024))
; #define LDB(dst, b, h)                                                                                     \
;   _Pragma("unroll") for (int n = 0; n < 2; ++n) _Pragma("unroll") for (int k = 0; k < 2; ++k) dst[n][k] = \
;       *reinterpret_cast<const bf16x8*>(shmc + bL + (((b) * 2 + (h)) * 16384 + (n * 2 + k) * 1024))
; #define WAIT_V(n) asm volatile("s_waitcnt vmcnt(" #n ")" ::: "memory")
; #define WAIT_L(n) asm volatile("s_waitcnt lgkmcnt(" #n ")" ::: "memory")
; #define BAR __builtin_amdgcn_s_barrier()
; #define SCHED __builtin_amdgcn_sched_barrier(0)
; template <int EPI>
; __device__ __forceinline__ void phase_gemm(const Params& p, const GemmDesc& d, char* shmc) {
;     ...
;       LDB(B0, 1, 0); SCHED; LDA(At, 1, 0); STAGE_A(SA(0, 1), 1, t + 2);
;       WAIT_L(8); BAR; WAIT_L(0); MMA(0, 0, At, B0); BAR; SCHED;
;       LDB(B1, 1, 1); STAGE_B(SB(1, 0), 0, t + 3);
;       BAR; WAIT_L(0); MMA(0, 1, At, B1); BAR;
;       LDA(At, 1, 1); STAGE_A(SA(1, 0), 0, t + 3);
;       BAR; WAIT_L(0); MMA(1, 0, At, B0); BAR; SCHED;
;       STAGE_B(SB(1, 1), 1, t + 3);
;       WAIT_V(6); BAR; MMA(1, 1, At, B1); BAR;
;     }
	s_setprio 0
	s_mov_b32 m0, s60
	s_nop 0
	global_load_lds_dwordx4 v228, s[98:99]
	s_mov_b32 m0, s61
	s_nop 0
	global_load_lds_dwordx4 v229, s[98:99]
	ds_read_b128 v[156:159], v130 offset:32768
	ds_read_b128 v[160:163], v130 offset:33792
	ds_read_b128 v[164:167], v130 offset:34816
	ds_read_b128 v[168:171], v130 offset:35840
	ds_read_b128 v[204:207], v130 offset:49152
	ds_read_b128 v[208:211], v130 offset:50176
	ds_read_b128 v[212:215], v130 offset:51200
	ds_read_b128 v[216:219], v130 offset:52224
	ds_read_b128 v[172:175], v141 offset:32768
	ds_read_b128 v[176:179], v141 offset:33792
	ds_read_b128 v[180:183], v141 offset:34816
	ds_read_b128 v[184:187], v141 offset:35840
	ds_read_b128 v[188:191], v141 offset:36864
	ds_read_b128 v[192:195], v141 offset:37888
	ds_read_b128 v[196:199], v141 offset:38912
	ds_read_b128 v[200:203], v141 offset:39936
	s_waitcnt vmcnt(8)
	s_waitcnt lgkmcnt(0)
	s_setprio 1
	s_barrier
	v_mfma_f32_16x16x32_bf16 v[126:129], v[156:159], v[172:175], v[126:129]
	v_mfma_f32_16x16x32_bf16 v[122:125], v[164:167], v[172:175], v[122:125]
	v_mfma_f32_16x16x32_bf16 v[118:121], v[156:159], v[180:183], v[118:121]
	v_mfma_f32_16x16x32_bf16 v[114:117], v[164:167], v[180:183], v[114:117]
	v_mfma_f32_16x16x32_bf16 v[110:113], v[156:159], v[188:191], v[110:113]
	v_mfma_f32_16x16x32_bf16 v[106:109], v[164:167], v[188:191], v[106:109]
	v_mfma_f32_16x16x32_bf16 v[102:105], v[156:159], v[196:199], v[102:105]
	v_mfma_f32_16x16x32_bf16 v[98:101], v[164:167], v[196:199], v[98:101]
	v_mfma_f32_16x16x32_bf16 v[126:129], v[160:163], v[176:179], v[126:129]
	v_mfma_f32_16x16x32_bf16 v[122:125], v[168:171], v[176:179], v[122:125]
	v_mfma_f32_16x16x32_bf16 v[118:121], v[160:163], v[184:187], v[118:121]
	v_mfma_f32_16x16x32_bf16 v[114:117], v[168:171], v[184:187], v[114:117]
	v_mfma_f32_16x16x32_bf16 v[110:113], v[160:163], v[192:195], v[110:113]
	v_mfma_f32_16x16x32_bf16 v[106:109], v[168:171], v[192:195], v[106:109]
	v_mfma_f32_16x16x32_bf16 v[102:105], v[160:163], v[200:203], v[102:105]
	v_mfma_f32_16x16x32_bf16 v[98:101], v[168:171], v[200:203], v[98:101]
	v_mfma_f32_16x16x32_bf16 v[86:89], v[204:207], v[172:175], v[86:89]
	v_mfma_f32_16x16x32_bf16 v[70:73], v[212:215], v[172:175], v[70:73]
	v_mfma_f32_16x16x32_bf16 v[54:57], v[204:207], v[180:183], v[54:57]
	v_mfma_f32_16x16x32_bf16 v[50:53], v[212:215], v[180:183], v[50:53]
	v_mfma_f32_16x16x32_bf16 v[46:49], v[204:207], v[188:191], v[46:49]
	v_mfma_f32_16x16x32_bf16 v[42:45], v[212:215], v[188:191], v[42:45]
	v_mfma_f32_16x16x32_bf16 v[38:41], v[204:207], v[196:199], v[38:41]
	v_mfma_f32_16x16x32_bf16 v[34:37], v[212:215], v[196:199], v[34:37]
	v_mfma_f32_16x16x32_bf16 v[86:89], v[208:211], v[176:179], v[86:89]
	v_mfma_f32_16x16x32_bf16 v[70:73], v[216:219], v[176:179], v[70:73]
	v_mfma_f32_16x16x32_bf16 v[54:57], v[208:211], v[184:187], v[54:57]
	v_mfma_f32_16x16x32_bf16 v[50:53], v[216:219], v[184:187], v[50:53]
	v_mfma_f32_16x16x32_bf16 v[46:49], v[208:211], v[192:195], v[46:49]
	v_mfma_f32_16x16x32_bf16 v[42:45], v[216:219], v[192:195], v[42:45]
	v_mfma_f32_16x16x32_bf16 v[38:41], v[208:211], v[200:203], v[38:41]
	v_mfma_f32_16x16x32_bf16 v[34:37], v[216:219], v[200:203], v[34:37]
	s_barrier
	s_setprio 0
	s_mov_b32 m0, s62
	s_nop 0
	global_load_lds_dwordx4 v232, s[100:101]
	s_mov_b32 m0, s63
	s_nop 0
	global_load_lds_dwordx4 v233, s[100:101]
	s_mov_b32 m0, s64
	s_nop 0
	global_load_lds_dwordx4 v234, s[98:99]
	s_mov_b32 m0, s65
	s_nop 0
	global_load_lds_dwordx4 v235, s[98:99]
	s_mov_b32 m0, s68
	s_nop 0
	global_load_lds_dwordx4 v236, s[100:101]
	s_mov_b32 m0, s69
	s_nop 0
	global_load_lds_dwordx4 v237, s[100:101]
	ds_read_b128 v[172:175], v141 offset:49152
	ds_read_b128 v[176:179], v141 offset:50176
	ds_read_b128 v[180:183], v141 offset:51200
	ds_read_b128 v[184:187], v141 offset:52224
	ds_read_b128 v[188:191], v141 offset:53248
	ds_read_b128 v[192:195], v141 offset:54272
	ds_read_b128 v[196:199], v141 offset:55296
	ds_read_b128 v[200:203], v141 offset:56320
	s_add_i32 s54, s54, 2
	s_add_u32 s52, s52, 0x100
	s_addc_u32 s53, s53, 0
	s_add_u32 s98, s98, 0x100
	s_addc_u32 s99, s99, 0
	s_add_u32 s100, s100, 0x100
	s_addc_u32 s101, s101, 0
	s_cmpk_gt_u32 s54, 0x53
	s_waitcnt vmcnt(8)
	s_waitcnt lgkmcnt(0)
	s_setprio 1
	s_barrier
	v_mfma_f32_16x16x32_bf16 v[30:33], v[156:159], v[172:175], v[30:33]
	v_mfma_f32_16x16x32_bf16 v[26:29], v[164:167], v[172:175], v[26:29]
	v_mfma_f32_16x16x32_bf16 v[22:25], v[156:159], v[180:183], v[22:25]
	v_mfma_f32_16x16x32_bf16 v[18:21], v[164:167], v[180:183], v[18:21]
	v_mfma_f32_16x16x32_bf16 v[14:17], v[156:159], v[188:191], v[14:17]
	v_mfma_f32_16x16x32_bf16 v[10:13], v[164:167], v[188:191], v[10:13]
	v_mfma_f32_16x16x32_bf16 v[6:9], v[156:159], v[196:199], v[6:9]
	v_mfma_f32_16x16x32_bf16 v[2:5], v[164:167], v[196:199], v[2:5]
	v_mfma_f32_16x16x32_bf16 v[30:33], v[160:163], v[176:179], v[30:33]
	v_mfma_f32_16x16x32_bf16 v[26:29], v[168:171], v[176:179], v[26:29]
	v_mfma_f32_16x16x32_bf16 v[22:25], v[160:163], v[184:187], v[22:25]
	v_mfma_f32_16x16x32_bf16 v[18:21], v[168:171], v[184:187], v[18:21]
	v_mfma_f32_16x16x32_bf16 v[14:17], v[160:163], v[192:195], v[14:17]
	v_mfma_f32_16x16x32_bf16 v[10:13], v[168:171], v[192:195], v[10:13]
	v_mfma_f32_16x16x32_bf16 v[6:9], v[160:163], v[200:203], v[6:9]
	v_mfma_f32_16x16x32_bf16 v[2:5], v[168:171], v[200:203], v[2:5]
	v_mfma_f32_16x16x32_bf16 v[58:61], v[204:207], v[172:175], v[58:61]
	v_mfma_f32_16x16x32_bf16 v[62:65], v[212:215], v[172:175], v[62:65]
	v_mfma_f32_16x16x32_bf16 v[66:69], v[204:207], v[180:183], v[66:69]
	v_mfma_f32_16x16x32_bf16 v[74:77], v[212:215], v[180:183], v[74:77]
	v_mfma_f32_16x16x32_bf16 v[78:81], v[204:207], v[188:191], v[78:81]
	v_mfma_f32_16x16x32_bf16 v[82:85], v[212:215], v[188:191], v[82:85]
	v_mfma_f32_16x16x32_bf16 v[90:93], v[204:207], v[196:199], v[90:93]
	v_mfma_f32_16x16x32_bf16 v[94:97], v[212:215], v[196:199], v[94:97]
	v_mfma_f32_16x16x32_bf16 v[58:61], v[208:211], v[176:179], v[58:61]
	v_mfma_f32_16x16x32_bf16 v[62:65], v[216:219], v[176:179], v[62:65]
	v_mfma_f32_16x16x32_bf16 v[66:69], v[208:211], v[184:187], v[66:69]
	v_mfma_f32_16x16x32_bf16 v[74:77], v[216:219], v[184:187], v[74:77]
	v_mfma_f32_16x16x32_bf16 v[78:81], v[208:211], v[192:195], v[78:81]
	v_mfma_f32_16x16x32_bf16 v[82:85], v[216:219], v[192:195], v[82:85]
	v_mfma_f32_16x16x32_bf16 v[90:93], v[208:211], v[200:203], v[90:93]
	v_mfma_f32_16x16x32_bf16 v[94:97], v[216:219], v[200:203], v[94:97]
	s_barrier
; #define LDA(dst, b, h)                                                                                     \
;   _Pragma("unroll") for (int m = 0; m < 4; ++m) _Pragma("unroll") for (int k = 0; k < 2; ++k) dst[m][k] = \
;       *reinterpret_cast<const bf16x8*>(shmc + aL + (((b) * 2 + (h)) * 16384 + (m * 2 + k) * 1024))
; #define LDB(dst, b, h)                                                                                     \
;   _Pragma("unroll") for (int n = 0; n < 2; ++n) _Pragma("unroll") for (int k = 0; k < 2; ++k) dst[n][k] = \
;       *reinterpret_cast<const bf16x8*>(shmc + bL + (((b) * 2 + (h)) * 16384 + (n * 2 + k) * 1024))
; #define OPAQ asm volatile("" : "+v"(aL), "+v"(bL))
; #define WAIT_V(n) asm volatile("s_waitcnt vmcnt(" #n ")" ::: "memory")
; #define WAIT_L(n) asm volatile("s_waitcnt lgkmcnt(" #n ")" ::: "memory")
; #define BAR __builtin_amdgcn_s_barrier()
; template <int EPI>
; __device__ __forceinline__ void phase_gemm(const Params& p, const GemmDesc& d, char* shmc) {
;     ...
;     {
;       OPAQ;
;       LDB(B0, 0, 0); LDA(At, 0, 0); STAGE_A(SA(1, 1), 1, nt - 1);
;       BAR; WAIT_L(0); MMA(0, 0, At, B0); BAR;
;       LDB(B1, 0, 1); BAR; WAIT_L(0); MMA(0, 1, At, B1); BAR;
;       LDA(At, 0, 1); WAIT_V(4); BAR; WAIT_L(0); MMA(1, 0, At, B0); MMA(1, 1, At, B1); BAR;
;     }
	s_cbranch_scc0 .LBB0_455
	s_setprio 0
	s_add_u32 s48, s48, 0x162b80
	s_addc_u32 s49, s49, 0
	v_add_u32_e32 v130, 0, v153
	v_add_u32_e32 v141, 0, v152
	s_mov_b32 m0, s70
	ds_read_b128 v[144:147], v130
	ds_read_b128 v[148:151], v130 offset:1024
	ds_read_b128 v[156:159], v130 offset:2048
	ds_read_b128 v[160:163], v130 offset:3072
	ds_read_b128 v[164:167], v141
	ds_read_b128 v[168:171], v141 offset:1024
	ds_read_b128 v[172:175], v141 offset:2048
	ds_read_b128 v[176:179], v141 offset:3072
	ds_read_b128 v[180:183], v141 offset:4096
	ds_read_b128 v[184:187], v141 offset:5120
	ds_read_b128 v[188:191], v141 offset:6144
	ds_read_b128 v[192:195], v141 offset:7168
	global_load_lds_dwordx4 v140, s[48:49]
	s_mov_b32 m0, s71
	s_nop 0
	global_load_lds_dwordx4 v142, s[48:49]
	s_waitcnt vmcnt(8)
	s_barrier
	s_waitcnt lgkmcnt(0)
	s_setprio 1
	s_waitcnt lgkmcnt(0)
	v_mfma_f32_16x16x32_bf16 v[126:129], v[144:147], v[164:167], v[126:129]
	v_mfma_f32_16x16x32_bf16 v[122:125], v[156:159], v[164:167], v[122:125]
	v_mfma_f32_16x16x32_bf16 v[114:117], v[156:159], v[172:175], v[114:117]
	v_mfma_f32_16x16x32_bf16 v[110:113], v[144:147], v[180:183], v[110:113]
	v_mfma_f32_16x16x32_bf16 v[102:105], v[144:147], v[188:191], v[102:105]
	v_mfma_f32_16x16x32_bf16 v[126:129], v[148:151], v[168:171], v[126:129]
	v_mfma_f32_16x16x32_bf16 v[122:125], v[160:163], v[168:171], v[122:125]
	v_mfma_f32_16x16x32_bf16 v[118:121], v[144:147], v[172:175], v[118:121]
	v_mfma_f32_16x16x32_bf16 v[114:117], v[160:163], v[176:179], v[114:117]
	v_mfma_f32_16x16x32_bf16 v[110:113], v[148:151], v[184:187], v[110:113]
	v_mfma_f32_16x16x32_bf16 v[106:109], v[156:159], v[180:183], v[106:109]
	v_mfma_f32_16x16x32_bf16 v[102:105], v[148:151], v[192:195], v[102:105]
	v_mfma_f32_16x16x32_bf16 v[98:101], v[156:159], v[188:191], v[98:101]
	v_mfma_f32_16x16x32_bf16 v[196:199], v[148:151], v[176:179], v[118:121]
	v_mfma_f32_16x16x32_bf16 v[200:203], v[160:163], v[184:187], v[106:109]
	v_mfma_f32_16x16x32_bf16 v[204:207], v[160:163], v[192:195], v[98:101]
	s_setprio 0
	s_barrier
	s_nop 2
	ds_read_b128 v[98:101], v130 offset:16384
	ds_read_b128 v[106:109], v130 offset:17408
	ds_read_b128 v[118:121], v130 offset:18432
	ds_read_b128 v[208:211], v130 offset:19456
	s_barrier
	s_waitcnt lgkmcnt(0)
	s_setprio 1
	s_waitcnt lgkmcnt(0)
	v_mfma_f32_16x16x32_bf16 v[86:89], v[98:101], v[164:167], v[86:89]
	v_mfma_f32_16x16x32_bf16 v[70:73], v[118:121], v[164:167], v[70:73]
	v_mfma_f32_16x16x32_bf16 v[54:57], v[98:101], v[172:175], v[54:57]
	v_mfma_f32_16x16x32_bf16 v[50:53], v[118:121], v[172:175], v[50:53]
	v_mfma_f32_16x16x32_bf16 v[46:49], v[98:101], v[180:183], v[46:49]
	v_mfma_f32_16x16x32_bf16 v[42:45], v[118:121], v[180:183], v[42:45]
	v_mfma_f32_16x16x32_bf16 v[38:41], v[98:101], v[188:191], v[38:41]
	v_mfma_f32_16x16x32_bf16 v[34:37], v[118:121], v[188:191], v[34:37]
	v_mfma_f32_16x16x32_bf16 v[86:89], v[106:109], v[168:171], v[86:89]
	v_mfma_f32_16x16x32_bf16 v[70:73], v[208:211], v[168:171], v[70:73]
	v_mfma_f32_16x16x32_bf16 v[54:57], v[106:109], v[176:179], v[54:57]
	v_mfma_f32_16x16x32_bf16 v[50:53], v[208:211], v[176:179], v[50:53]
	v_mfma_f32_16x16x32_bf16 v[46:49], v[106:109], v[184:187], v[46:49]
	v_mfma_f32_16x16x32_bf16 v[42:45], v[208:211], v[184:187], v[42:45]
	v_mfma_f32_16x16x32_bf16 v[38:41], v[106:109], v[192:195], v[38:41]
	v_mfma_f32_16x16x32_bf16 v[34:37], v[208:211], v[192:195], v[34:37]
	s_setprio 0
	s_barrier
	ds_read_b128 v[164:167], v141 offset:16384
	ds_read_b128 v[168:171], v141 offset:17408
	ds_read_b128 v[172:175], v141 offset:18432
	ds_read_b128 v[176:179], v141 offset:19456
	ds_read_b128 v[180:183], v141 offset:20480
	ds_read_b128 v[184:187], v141 offset:21504
	ds_read_b128 v[188:191], v141 offset:22528
	ds_read_b128 v[192:195], v141 offset:23552
	s_waitcnt vmcnt(4)
	s_barrier
	s_waitcnt lgkmcnt(0)
	s_setprio 1
	s_waitcnt lgkmcnt(0)
	v_mfma_f32_16x16x32_bf16 v[30:33], v[144:147], v[164:167], v[30:33]
	v_mfma_f32_16x16x32_bf16 v[26:29], v[156:159], v[164:167], v[26:29]
	v_mfma_f32_16x16x32_bf16 v[22:25], v[144:147], v[172:175], v[22:25]
	v_mfma_f32_16x16x32_bf16 v[18:21], v[156:159], v[172:175], v[18:21]
	v_mfma_f32_16x16x32_bf16 v[14:17], v[144:147], v[180:183], v[14:17]
	v_mfma_f32_16x16x32_bf16 v[10:13], v[156:159], v[180:183], v[10:13]
	v_mfma_f32_16x16x32_bf16 v[6:9], v[144:147], v[188:191], v[6:9]
	v_mfma_f32_16x16x32_bf16 v[2:5], v[156:159], v[188:191], v[2:5]
	v_mfma_f32_16x16x32_bf16 v[30:33], v[148:151], v[168:171], v[30:33]
	v_mfma_f32_16x16x32_bf16 v[26:29], v[160:163], v[168:171], v[26:29]
	v_mfma_f32_16x16x32_bf16 v[22:25], v[148:151], v[176:179], v[22:25]
	v_mfma_f32_16x16x32_bf16 v[18:21], v[160:163], v[176:179], v[18:21]
	v_mfma_f32_16x16x32_bf16 v[14:17], v[148:151], v[184:187], v[14:17]
	v_mfma_f32_16x16x32_bf16 v[10:13], v[160:163], v[184:187], v[10:13]
	v_mfma_f32_16x16x32_bf16 v[6:9], v[148:151], v[192:195], v[6:9]
	v_mfma_f32_16x16x32_bf16 v[2:5], v[160:163], v[192:195], v[2:5]
	s_setprio 0
	s_setprio 1
	v_mfma_f32_16x16x32_bf16 v[62:65], v[118:121], v[164:167], v[62:65]
	v_mfma_f32_16x16x32_bf16 v[144:147], v[208:211], v[168:171], v[62:65]
	v_mfma_f32_16x16x32_bf16 v[62:65], v[98:101], v[172:175], v[66:69]
	v_mfma_f32_16x16x32_bf16 v[148:151], v[106:109], v[176:179], v[62:65]
	v_mfma_f32_16x16x32_bf16 v[62:65], v[118:121], v[172:175], v[74:77]
	v_mfma_f32_16x16x32_bf16 v[156:159], v[208:211], v[176:179], v[62:65]
	v_mfma_f32_16x16x32_bf16 v[62:65], v[98:101], v[180:183], v[78:81]
	v_mfma_f32_16x16x32_bf16 v[160:163], v[106:109], v[184:187], v[62:65]
	v_mfma_f32_16x16x32_bf16 v[62:65], v[118:121], v[180:183], v[82:85]
	v_mfma_f32_16x16x32_bf16 v[58:61], v[98:101], v[164:167], v[58:61]
	v_mfma_f32_16x16x32_bf16 v[164:167], v[208:211], v[184:187], v[62:65]
	v_mfma_f32_16x16x32_bf16 v[62:65], v[98:101], v[188:191], v[90:93]
	v_mfma_f32_16x16x32_bf16 v[58:61], v[106:109], v[168:171], v[58:61]
	v_mfma_f32_16x16x32_bf16 v[168:171], v[106:109], v[192:195], v[62:65]
	v_mfma_f32_16x16x32_bf16 v[62:65], v[118:121], v[188:191], v[94:97]
	v_mfma_f32_16x16x32_bf16 v[172:175], v[208:211], v[192:195], v[62:65]
	s_setprio 0
	s_barrier
; #define LDA(dst, b, h)                                                                                     \
;   _Pragma("unroll") for (int m = 0; m < 4; ++m) _Pragma("unroll") for (int k = 0; k < 2; ++k) dst[m][k] = \
;       *reinterpret_cast<const bf16x8*>(shmc + aL + (((b) * 2 + (h)) * 16384 + (m * 2 + k) * 1024))
; #define LDB(dst, b, h)                                                                                     \
;   _Pragma("unroll") for (int n = 0; n < 2; ++n) _Pragma("unroll") for (int k = 0; k < 2; ++k) dst[n][k] = \
;       *reinterpret_cast<const bf16x8*>(shmc + bL + (((b) * 2 + (h)) * 16384 + (n * 2 + k) * 1024))
; #define WAIT_V(n) asm volatile("s_waitcnt vmcnt(" #n ")" ::: "memory")
; #define WAIT_L(n) asm volatile("s_waitcnt lgkmcnt(" #n ")" ::: "memory")
; #define BAR __builtin_amdgcn_s_barrier()
; template <int EPI>
; __device__ __forceinline__ void phase_gemm(const Params& p, const GemmDesc& d, char* shmc) {
;     ...
;     {
;       LDB(B0, 1, 0); LDA(At, 1, 0); WAIT_V(2); BAR; WAIT_L(0); MMA(0, 0, At, B0); BAR;
;       LDB(B1, 1, 1); WAIT_V(0); BAR; WAIT_L(0); MMA(0, 1, At, B1); BAR;
;       LDA(At, 1, 1); BAR; WAIT_L(0); MMA(1, 0, At, B0); MMA(1, 1, At, B1); BAR;
;     }
;     if (wr == 0) BAR;
	ds_read_b128 v[176:179], v130 offset:32768
	ds_read_b128 v[180:183], v130 offset:33792
	ds_read_b128 v[184:187], v130 offset:34816
	ds_read_b128 v[188:191], v130 offset:35840
	s_nop 0
	ds_read_b128 v[62:65], v141 offset:32768
	ds_read_b128 v[78:81], v141 offset:33792
	ds_read_b128 v[94:97], v141 offset:34816
	ds_read_b128 v[192:195], v141 offset:35840
	ds_read_b128 v[208:211], v141 offset:36864
	ds_read_b128 v[212:215], v141 offset:37888
	ds_read_b128 v[216:219], v141 offset:38912
	ds_read_b128 v[220:223], v141 offset:39936
	s_waitcnt vmcnt(2)
	s_barrier
	s_waitcnt lgkmcnt(0)
	s_setprio 1
	s_waitcnt lgkmcnt(0)
	v_mfma_f32_16x16x32_bf16 v[66:69], v[176:179], v[62:65], v[126:129]
	v_mfma_f32_16x16x32_bf16 v[126:129], v[180:183], v[78:81], v[66:69]
	v_mfma_f32_16x16x32_bf16 v[66:69], v[184:187], v[62:65], v[122:125]
	v_mfma_f32_16x16x32_bf16 v[118:121], v[188:191], v[78:81], v[66:69]
	v_mfma_f32_16x16x32_bf16 v[66:69], v[176:179], v[94:97], v[196:199]
	v_mfma_f32_16x16x32_bf16 v[106:109], v[180:183], v[192:195], v[66:69]
	v_mfma_f32_16x16x32_bf16 v[66:69], v[184:187], v[94:97], v[114:117]
	v_mfma_f32_16x16x32_bf16 v[98:101], v[188:191], v[192:195], v[66:69]
	v_mfma_f32_16x16x32_bf16 v[66:69], v[176:179], v[208:211], v[110:113]
	v_mfma_f32_16x16x32_bf16 v[90:93], v[180:183], v[212:215], v[66:69]
	v_mfma_f32_16x16x32_bf16 v[66:69], v[184:187], v[208:211], v[200:203]
	v_mfma_f32_16x16x32_bf16 v[82:85], v[188:191], v[212:215], v[66:69]
	v_mfma_f32_16x16x32_bf16 v[66:69], v[176:179], v[216:219], v[102:105]
	v_mfma_f32_16x16x32_bf16 v[74:77], v[180:183], v[220:223], v[66:69]
	v_mfma_f32_16x16x32_bf16 v[66:69], v[184:187], v[216:219], v[204:207]
	v_mfma_f32_16x16x32_bf16 v[66:69], v[188:191], v[220:223], v[66:69]
	s_setprio 0
	s_barrier
	ds_read_b128 v[196:199], v130 offset:49152
	ds_read_b128 v[200:203], v130 offset:50176
	ds_read_b128 v[204:207], v130 offset:51200
	ds_read_b128 v[224:227], v130 offset:52224
	s_waitcnt vmcnt(0)
	s_barrier
	s_waitcnt lgkmcnt(0)
	s_setprio 1
	s_waitcnt lgkmcnt(0)
	v_mfma_f32_16x16x32_bf16 v[86:89], v[196:199], v[62:65], v[86:89]
	v_mfma_f32_16x16x32_bf16 v[62:65], v[204:207], v[62:65], v[70:73]
	v_mfma_f32_16x16x32_bf16 v[54:57], v[196:199], v[94:97], v[54:57]
	v_mfma_f32_16x16x32_bf16 v[50:53], v[204:207], v[94:97], v[50:53]
	v_mfma_f32_16x16x32_bf16 v[46:49], v[196:199], v[208:211], v[46:49]
	v_mfma_f32_16x16x32_bf16 v[42:45], v[204:207], v[208:211], v[42:45]
	v_mfma_f32_16x16x32_bf16 v[38:41], v[196:199], v[216:219], v[38:41]
	v_mfma_f32_16x16x32_bf16 v[34:37], v[204:207], v[216:219], v[34:37]
	v_mfma_f32_16x16x32_bf16 v[122:125], v[200:203], v[78:81], v[86:89]
	v_mfma_f32_16x16x32_bf16 v[114:117], v[224:227], v[78:81], v[62:65]
	v_mfma_f32_16x16x32_bf16 v[110:113], v[200:203], v[192:195], v[54:57]
	v_mfma_f32_16x16x32_bf16 v[102:105], v[224:227], v[192:195], v[50:53]
	v_mfma_f32_16x16x32_bf16 v[94:97], v[200:203], v[212:215], v[46:49]
	v_mfma_f32_16x16x32_bf16 v[86:89], v[224:227], v[212:215], v[42:45]
	v_mfma_f32_16x16x32_bf16 v[78:81], v[200:203], v[220:223], v[38:41]
	v_mfma_f32_16x16x32_bf16 v[70:73], v[224:227], v[220:223], v[34:37]
	s_setprio 0
	s_barrier
	s_nop 0
	ds_read_b128 v[34:37], v141 offset:49152
	ds_read_b128 v[42:45], v141 offset:50176
	ds_read_b128 v[192:195], v141 offset:51200
	ds_read_b128 v[208:211], v141 offset:52224
	ds_read_b128 v[212:215], v141 offset:53248
	ds_read_b128 v[216:219], v141 offset:54272
	ds_read_b128 v[220:223], v141 offset:55296
	ds_read_b128 v[228:231], v141 offset:56320
	s_barrier
	s_waitcnt lgkmcnt(0)
	s_setprio 1
	s_waitcnt lgkmcnt(0)
	v_mfma_f32_16x16x32_bf16 v[30:33], v[176:179], v[34:37], v[30:33]
	v_mfma_f32_16x16x32_bf16 v[26:29], v[184:187], v[34:37], v[26:29]
	v_mfma_f32_16x16x32_bf16 v[22:25], v[176:179], v[192:195], v[22:25]
	v_mfma_f32_16x16x32_bf16 v[18:21], v[184:187], v[192:195], v[18:21]
	v_mfma_f32_16x16x32_bf16 v[14:17], v[176:179], v[212:215], v[14:17]
	v_mfma_f32_16x16x32_bf16 v[10:13], v[184:187], v[212:215], v[10:13]
	v_mfma_f32_16x16x32_bf16 v[6:9], v[176:179], v[220:223], v[6:9]
	v_mfma_f32_16x16x32_bf16 v[2:5], v[184:187], v[220:223], v[2:5]
	v_mfma_f32_16x16x32_bf16 v[62:65], v[180:183], v[42:45], v[30:33]
	v_mfma_f32_16x16x32_bf16 v[54:57], v[188:191], v[42:45], v[26:29]
	v_mfma_f32_16x16x32_bf16 v[46:49], v[180:183], v[208:211], v[22:25]
	v_mfma_f32_16x16x32_bf16 v[38:41], v[188:191], v[208:211], v[18:21]
	v_mfma_f32_16x16x32_bf16 v[30:33], v[180:183], v[216:219], v[14:17]
	v_mfma_f32_16x16x32_bf16 v[22:25], v[188:191], v[216:219], v[10:13]
	v_mfma_f32_16x16x32_bf16 v[14:17], v[180:183], v[228:231], v[6:9]
	v_mfma_f32_16x16x32_bf16 v[6:9], v[188:191], v[228:231], v[2:5]
	s_setprio 0
	s_setprio 1
	v_mfma_f32_16x16x32_bf16 v[2:5], v[196:199], v[34:37], v[58:61]
	v_mfma_f32_16x16x32_bf16 v[58:61], v[200:203], v[42:45], v[2:5]
	v_mfma_f32_16x16x32_bf16 v[2:5], v[204:207], v[34:37], v[144:147]
	v_mfma_f32_16x16x32_bf16 v[50:53], v[224:227], v[42:45], v[2:5]
	v_mfma_f32_16x16x32_bf16 v[2:5], v[196:199], v[192:195], v[148:151]
	v_mfma_f32_16x16x32_bf16 v[42:45], v[200:203], v[208:211], v[2:5]
	v_mfma_f32_16x16x32_bf16 v[2:5], v[204:207], v[192:195], v[156:159]
	v_mfma_f32_16x16x32_bf16 v[34:37], v[224:227], v[208:211], v[2:5]
	v_mfma_f32_16x16x32_bf16 v[2:5], v[196:199], v[212:215], v[160:163]
	v_mfma_f32_16x16x32_bf16 v[26:29], v[200:203], v[216:219], v[2:5]
	v_mfma_f32_16x16x32_bf16 v[2:5], v[204:207], v[212:215], v[164:167]
	v_mfma_f32_16x16x32_bf16 v[18:21], v[224:227], v[216:219], v[2:5]
	v_mfma_f32_16x16x32_bf16 v[2:5], v[196:199], v[220:223], v[168:171]
	v_mfma_f32_16x16x32_bf16 v[10:13], v[200:203], v[228:231], v[2:5]
	v_mfma_f32_16x16x32_bf16 v[2:5], v[204:207], v[220:223], v[172:175]
	v_mfma_f32_16x16x32_bf16 v[2:5], v[224:227], v[228:231], v[2:5]
	s_setprio 0
	s_barrier
	s_and_saveexec_b64 s[48:49], s[4:5]
	s_cbranch_execz .LBB0_458
	s_barrier

; #define LDA(dst, b, h)                                                                                     \
;   _Pragma("unroll") for (int m = 0; m < 4; ++m) _Pragma("unroll") for (int k = 0; k < 2; ++k) dst[m][k] = \
;       *reinterpret_cast<const bf16x8*>(shmc + aL + (((b) * 2 + (h)) * 16384 + (m * 2 + k) * 1024))
; #define LDB(dst, b, h)                                                                                     \
;   _Pragma("unroll") for (int n = 0; n < 2; ++n) _Pragma("unroll") for (int k = 0; k < 2; ++k) dst[n][k] = \
;       *reinterpret_cast<const bf16x8*>(shmc + bL + (((b) * 2 + (h)) * 16384 + (n * 2 + k) * 1024))
; #define OPAQ asm volatile("" : "+v"(aL), "+v"(bL))
; #define WAIT_V(n) asm volatile("s_waitcnt vmcnt(" #n ")" ::: "memory")
; #define WAIT_L(n) asm volatile("s_waitcnt lgkmcnt(" #n ")" ::: "memory")
; #define BAR __builtin_amdgcn_s_barrier()
; #define SCHED __builtin_amdgcn_sched_barrier(0)
; template <int EPI>
; __device__ __forceinline__ void phase_gemm(const Params& p, const GemmDesc& d, char* shmc) {
;     ...
;     for (int t = 0; t < nt - 2; t += 2) {
;       OPAQ;
;       LDB(B0, 0, 0); SCHED; LDA(At, 0, 0); STAGE_A(SA(1, 1), 1, t + 1);
;       WAIT_L(8); BAR; WAIT_L(0); MMA(0, 0, At, B0); BAR; SCHED;
;       LDB(B1, 0, 1); STAGE_B(SB(0, 0), 0, t + 2);
;       BAR; WAIT_L(0); MMA(0, 1, At, B1); BAR;
;       LDA(At, 0, 1); STAGE_A(SA(0, 0), 0, t + 2);
;       BAR; WAIT_L(0); MMA(1, 0, At, B0); BAR; SCHED;
;       STAGE_B(SB(0, 1), 1, t + 2);
;       WAIT_V(6); BAR; MMA(1, 1, At, B1); BAR;
.LBB0_598:
	s_nop 0
	v_add_u32_e32 v175, 0, v179
	v_add_u32_e32 v176, 0, v177
	s_setprio 0
	s_add_i32 s88, s68, 0xc000
	s_mov_b32 m0, s88
	s_nop 0
	global_load_lds_dwordx4 v222, s[98:99]
	s_add_i32 s89, s68, 0xe000
	s_mov_b32 m0, s89
	s_nop 0
	global_load_lds_dwordx4 v223, s[98:99]
	ds_read_b128 v[138:141], v175
	ds_read_b128 v[142:145], v175 offset:1024
	ds_read_b128 v[146:149], v175 offset:2048
	ds_read_b128 v[150:153], v175 offset:3072
	ds_read_b128 v[206:209], v175 offset:16384
	ds_read_b128 v[210:213], v175 offset:17408
	ds_read_b128 v[214:217], v175 offset:18432
	ds_read_b128 v[218:221], v175 offset:19456
	ds_read_b128 v[154:157], v176
	ds_read_b128 v[158:161], v176 offset:1024
	ds_read_b128 v[182:185], v176 offset:2048
	ds_read_b128 v[186:189], v176 offset:3072
	ds_read_b128 v[190:193], v176 offset:4096
	ds_read_b128 v[194:197], v176 offset:5120
	ds_read_b128 v[198:201], v176 offset:6144
	ds_read_b128 v[202:205], v176 offset:7168
	s_waitcnt vmcnt(8)
	s_waitcnt lgkmcnt(0)
	s_setprio 1
	s_barrier
	v_mfma_f32_16x16x32_bf16 v[126:129], v[154:157], v[138:141], v[126:129]
	v_mfma_f32_16x16x32_bf16 v[122:125], v[154:157], v[146:149], v[122:125]
	v_mfma_f32_16x16x32_bf16 v[118:121], v[182:185], v[138:141], v[118:121]
	v_mfma_f32_16x16x32_bf16 v[114:117], v[182:185], v[146:149], v[114:117]
	v_mfma_f32_16x16x32_bf16 v[110:113], v[190:193], v[138:141], v[110:113]
	v_mfma_f32_16x16x32_bf16 v[106:109], v[190:193], v[146:149], v[106:109]
	v_mfma_f32_16x16x32_bf16 v[102:105], v[198:201], v[138:141], v[102:105]
	v_mfma_f32_16x16x32_bf16 v[94:97], v[198:201], v[146:149], v[94:97]
	v_mfma_f32_16x16x32_bf16 v[126:129], v[158:161], v[142:145], v[126:129]
	v_mfma_f32_16x16x32_bf16 v[122:125], v[158:161], v[150:153], v[122:125]
	v_mfma_f32_16x16x32_bf16 v[118:121], v[186:189], v[142:145], v[118:121]
	v_mfma_f32_16x16x32_bf16 v[114:117], v[186:189], v[150:153], v[114:117]
	v_mfma_f32_16x16x32_bf16 v[110:113], v[194:197], v[142:145], v[110:113]
	v_mfma_f32_16x16x32_bf16 v[106:109], v[194:197], v[150:153], v[106:109]
	v_mfma_f32_16x16x32_bf16 v[102:105], v[202:205], v[142:145], v[102:105]
	v_mfma_f32_16x16x32_bf16 v[94:97], v[202:205], v[150:153], v[94:97]
	v_mfma_f32_16x16x32_bf16 v[50:53], v[154:157], v[206:209], v[50:53]
	v_mfma_f32_16x16x32_bf16 v[42:45], v[154:157], v[214:217], v[42:45]
	v_mfma_f32_16x16x32_bf16 v[38:41], v[182:185], v[206:209], v[38:41]
	v_mfma_f32_16x16x32_bf16 v[34:37], v[182:185], v[214:217], v[34:37]
	v_mfma_f32_16x16x32_bf16 v[30:33], v[190:193], v[206:209], v[30:33]
	v_mfma_f32_16x16x32_bf16 v[26:29], v[190:193], v[214:217], v[26:29]
	v_mfma_f32_16x16x32_bf16 v[22:25], v[198:201], v[206:209], v[22:25]
	v_mfma_f32_16x16x32_bf16 v[18:21], v[198:201], v[214:217], v[18:21]
	v_mfma_f32_16x16x32_bf16 v[50:53], v[158:161], v[210:213], v[50:53]
	v_mfma_f32_16x16x32_bf16 v[42:45], v[158:161], v[218:221], v[42:45]
	v_mfma_f32_16x16x32_bf16 v[38:41], v[186:189], v[210:213], v[38:41]
	v_mfma_f32_16x16x32_bf16 v[34:37], v[186:189], v[218:221], v[34:37]
	v_mfma_f32_16x16x32_bf16 v[30:33], v[194:197], v[210:213], v[30:33]
	v_mfma_f32_16x16x32_bf16 v[26:29], v[194:197], v[218:221], v[26:29]
	v_mfma_f32_16x16x32_bf16 v[22:25], v[202:205], v[210:213], v[22:25]
	v_mfma_f32_16x16x32_bf16 v[18:21], v[202:205], v[218:221], v[18:21]
	s_barrier
	s_setprio 0
	s_mov_b32 m0, s69
	s_nop 0
	global_load_lds_dwordx4 v224, s[100:101]
	s_mov_b32 m0, s70
	s_nop 0
	global_load_lds_dwordx4 v225, s[100:101]
	s_mov_b32 m0, s68
	s_nop 0
	global_load_lds_dwordx4 v226, s[98:99]
	s_mov_b32 m0, s71
	s_nop 0
	global_load_lds_dwordx4 v227, s[98:99]
	s_mov_b32 m0, s76
	s_nop 0
	global_load_lds_dwordx4 v228, s[100:101]
	s_mov_b32 m0, s77
	s_nop 0
	global_load_lds_dwordx4 v229, s[100:101]
	ds_read_b128 v[154:157], v176 offset:16384
	ds_read_b128 v[158:161], v176 offset:17408
	ds_read_b128 v[182:185], v176 offset:18432
	ds_read_b128 v[186:189], v176 offset:19456
	ds_read_b128 v[190:193], v176 offset:20480
	ds_read_b128 v[194:197], v176 offset:21504
	ds_read_b128 v[198:201], v176 offset:22528
	ds_read_b128 v[202:205], v176 offset:23552
	s_waitcnt vmcnt(8)
	s_waitcnt lgkmcnt(0)
	s_setprio 1
	s_barrier
	v_mfma_f32_16x16x32_bf16 v[14:17], v[154:157], v[138:141], v[14:17]
	v_mfma_f32_16x16x32_bf16 v[10:13], v[154:157], v[146:149], v[10:13]
	v_mfma_f32_16x16x32_bf16 v[6:9], v[182:185], v[138:141], v[6:9]
	v_mfma_f32_16x16x32_bf16 v[2:5], v[182:185], v[146:149], v[2:5]
	v_mfma_f32_16x16x32_bf16 v[46:49], v[190:193], v[138:141], v[46:49]
	v_mfma_f32_16x16x32_bf16 v[54:57], v[190:193], v[146:149], v[54:57]
	v_mfma_f32_16x16x32_bf16 v[58:61], v[198:201], v[138:141], v[58:61]
	v_mfma_f32_16x16x32_bf16 v[62:65], v[198:201], v[146:149], v[62:65]
	v_mfma_f32_16x16x32_bf16 v[14:17], v[158:161], v[142:145], v[14:17]
	v_mfma_f32_16x16x32_bf16 v[10:13], v[158:161], v[150:153], v[10:13]
	v_mfma_f32_16x16x32_bf16 v[6:9], v[186:189], v[142:145], v[6:9]
	v_mfma_f32_16x16x32_bf16 v[2:5], v[186:189], v[150:153], v[2:5]
	v_mfma_f32_16x16x32_bf16 v[46:49], v[194:197], v[142:145], v[46:49]
	v_mfma_f32_16x16x32_bf16 v[54:57], v[194:197], v[150:153], v[54:57]
	v_mfma_f32_16x16x32_bf16 v[58:61], v[202:205], v[142:145], v[58:61]
	v_mfma_f32_16x16x32_bf16 v[62:65], v[202:205], v[150:153], v[62:65]
	v_mfma_f32_16x16x32_bf16 v[66:69], v[154:157], v[206:209], v[66:69]
	v_mfma_f32_16x16x32_bf16 v[70:73], v[154:157], v[214:217], v[70:73]
	v_mfma_f32_16x16x32_bf16 v[74:77], v[182:185], v[206:209], v[74:77]
	v_mfma_f32_16x16x32_bf16 v[78:81], v[182:185], v[214:217], v[78:81]
	v_mfma_f32_16x16x32_bf16 v[82:85], v[190:193], v[206:209], v[82:85]
	v_mfma_f32_16x16x32_bf16 v[86:89], v[190:193], v[214:217], v[86:89]
	v_mfma_f32_16x16x32_bf16 v[90:93], v[198:201], v[206:209], v[90:93]
	v_mfma_f32_16x16x32_bf16 v[98:101], v[198:201], v[214:217], v[98:101]
	v_mfma_f32_16x16x32_bf16 v[66:69], v[158:161], v[210:213], v[66:69]
	v_mfma_f32_16x16x32_bf16 v[70:73], v[158:161], v[218:221], v[70:73]
	v_mfma_f32_16x16x32_bf16 v[74:77], v[186:189], v[210:213], v[74:77]
	v_mfma_f32_16x16x32_bf16 v[78:81], v[186:189], v[218:221], v[78:81]
	v_mfma_f32_16x16x32_bf16 v[82:85], v[194:197], v[210:213], v[82:85]
	v_mfma_f32_16x16x32_bf16 v[86:89], v[194:197], v[218:221], v[86:89]
	v_mfma_f32_16x16x32_bf16 v[90:93], v[202:205], v[210:213], v[90:93]
	v_mfma_f32_16x16x32_bf16 v[98:101], v[202:205], v[218:221], v[98:101]
	s_barrier
; #define LDA(dst, b, h)                                                                                     \
;   _Pragma("unroll") for (int m = 0; m < 4; ++m) _Pragma("unroll") for (int k = 0; k < 2; ++k) dst[m][k] = \
;       *reinterpret_cast<const bf16x8*>(shmc + aL + (((b) * 2 + (h)) * 16384 + (m * 2 + k) * 1024))
; #define LDB(dst, b, h)                                                                                     \
;   _Pragma("unroll") for (int n = 0; n < 2; ++n) _Pragma("unroll") for (int k = 0; k < 2; ++k) dst[n][k] = \
;       *reinterpret_cast<const bf16x8*>(shmc + bL + (((b) * 2 + (h)) * 16384 + (n * 2 + k) * 1024))
; #define WAIT_V(n) asm volatile("s_waitcnt vmcnt(" #n ")" ::: "memory")
; #define WAIT_L(n) asm volatile("s_waitcnt lgkmcnt(" #n ")" ::: "memory")
; #define BAR __builtin_amdgcn_s_barrier()
; #define SCHED __builtin_amdgcn_sched_barrier(0)
; template <int EPI>
; __device__ __forceinline__ void phase_gemm(const Params& p, const GemmDesc& d, char* shmc) {
;     ...
;       LDB(B0, 1, 0); SCHED; LDA(At, 1, 0); STAGE_A(SA(0, 1), 1, t + 2);
;       WAIT_L(8); BAR; WAIT_L(0); MMA(0, 0, At, B0); BAR; SCHED;
;       LDB(B1, 1, 1); STAGE_B(SB(1, 0), 0, t + 3);
;       BAR; WAIT_L(0); MMA(0, 1, At, B1); BAR;
;       LDA(At, 1, 1); STAGE_A(SA(1, 0), 0, t + 3);
;       BAR; WAIT_L(0); MMA(1, 0, At, B0); BAR; SCHED;
;       STAGE_B(SB(1, 1), 1, t + 3);
;       WAIT_V(6); BAR; MMA(1, 1, At, B1); BAR;
;     }
	s_setprio 0
	s_mov_b32 m0, s80
	s_nop 0
	global_load_lds_dwordx4 v230, s[98:99]
	s_mov_b32 m0, s81
	s_nop 0
	global_load_lds_dwordx4 v231, s[98:99]
	ds_read_b128 v[138:141], v175 offset:32768
	ds_read_b128 v[142:145], v175 offset:33792
	ds_read_b128 v[146:149], v175 offset:34816
	ds_read_b128 v[150:153], v175 offset:35840
	ds_read_b128 v[206:209], v175 offset:49152
	ds_read_b128 v[210:213], v175 offset:50176
	ds_read_b128 v[214:217], v175 offset:51200
	ds_read_b128 v[218:221], v175 offset:52224
	ds_read_b128 v[154:157], v176 offset:32768
	ds_read_b128 v[158:161], v176 offset:33792
	ds_read_b128 v[182:185], v176 offset:34816
	ds_read_b128 v[186:189], v176 offset:35840
	ds_read_b128 v[190:193], v176 offset:36864
	ds_read_b128 v[194:197], v176 offset:37888
	ds_read_b128 v[198:201], v176 offset:38912
	ds_read_b128 v[202:205], v176 offset:39936
	s_waitcnt vmcnt(8)
	s_waitcnt lgkmcnt(0)
	s_setprio 1
	s_barrier
	v_mfma_f32_16x16x32_bf16 v[126:129], v[154:157], v[138:141], v[126:129]
	v_mfma_f32_16x16x32_bf16 v[122:125], v[154:157], v[146:149], v[122:125]
	v_mfma_f32_16x16x32_bf16 v[118:121], v[182:185], v[138:141], v[118:121]
	v_mfma_f32_16x16x32_bf16 v[114:117], v[182:185], v[146:149], v[114:117]
	v_mfma_f32_16x16x32_bf16 v[110:113], v[190:193], v[138:141], v[110:113]
	v_mfma_f32_16x16x32_bf16 v[106:109], v[190:193], v[146:149], v[106:109]
	v_mfma_f32_16x16x32_bf16 v[102:105], v[198:201], v[138:141], v[102:105]
	v_mfma_f32_16x16x32_bf16 v[94:97], v[198:201], v[146:149], v[94:97]
	v_mfma_f32_16x16x32_bf16 v[126:129], v[158:161], v[142:145], v[126:129]
	v_mfma_f32_16x16x32_bf16 v[122:125], v[158:161], v[150:153], v[122:125]
	v_mfma_f32_16x16x32_bf16 v[118:121], v[186:189], v[142:145], v[118:121]
	v_mfma_f32_16x16x32_bf16 v[114:117], v[186:189], v[150:153], v[114:117]
	v_mfma_f32_16x16x32_bf16 v[110:113], v[194:197], v[142:145], v[110:113]
	v_mfma_f32_16x16x32_bf16 v[106:109], v[194:197], v[150:153], v[106:109]
	v_mfma_f32_16x16x32_bf16 v[102:105], v[202:205], v[142:145], v[102:105]
	v_mfma_f32_16x16x32_bf16 v[94:97], v[202:205], v[150:153], v[94:97]
	v_mfma_f32_16x16x32_bf16 v[50:53], v[154:157], v[206:209], v[50:53]
	v_mfma_f32_16x16x32_bf16 v[42:45], v[154:157], v[214:217], v[42:45]
	v_mfma_f32_16x16x32_bf16 v[38:41], v[182:185], v[206:209], v[38:41]
	v_mfma_f32_16x16x32_bf16 v[34:37], v[182:185], v[214:217], v[34:37]
	v_mfma_f32_16x16x32_bf16 v[30:33], v[190:193], v[206:209], v[30:33]
	v_mfma_f32_16x16x32_bf16 v[26:29], v[190:193], v[214:217], v[26:29]
	v_mfma_f32_16x16x32_bf16 v[22:25], v[198:201], v[206:209], v[22:25]
	v_mfma_f32_16x16x32_bf16 v[18:21], v[198:201], v[214:217], v[18:21]
	v_mfma_f32_16x16x32_bf16 v[50:53], v[158:161], v[210:213], v[50:53]
	v_mfma_f32_16x16x32_bf16 v[42:45], v[158:161], v[218:221], v[42:45]
	v_mfma_f32_16x16x32_bf16 v[38:41], v[186:189], v[210:213], v[38:41]
	v_mfma_f32_16x16x32_bf16 v[34:37], v[186:189], v[218:221], v[34:37]
	v_mfma_f32_16x16x32_bf16 v[30:33], v[194:197], v[210:213], v[30:33]
	v_mfma_f32_16x16x32_bf16 v[26:29], v[194:197], v[218:221], v[26:29]
	v_mfma_f32_16x16x32_bf16 v[22:25], v[202:205], v[210:213], v[22:25]
	v_mfma_f32_16x16x32_bf16 v[18:21], v[202:205], v[218:221], v[18:21]
	s_barrier
	s_setprio 0
	s_mov_b32 m0, s61
	s_nop 0
	global_load_lds_dwordx4 v232, s[100:101]
	s_mov_b32 m0, s78
	s_nop 0
	global_load_lds_dwordx4 v233, s[100:101]
	s_mov_b32 m0, s79
	s_nop 0
	global_load_lds_dwordx4 v234, s[98:99]
	s_mov_b32 m0, s86
	s_nop 0
	global_load_lds_dwordx4 v235, s[98:99]
	s_mov_b32 m0, s64
	s_nop 0
	global_load_lds_dwordx4 v236, s[100:101]
	s_mov_b32 m0, s65
	s_nop 0
	global_load_lds_dwordx4 v237, s[100:101]
	ds_read_b128 v[154:157], v176 offset:49152
	ds_read_b128 v[158:161], v176 offset:50176
	ds_read_b128 v[182:185], v176 offset:51200
	ds_read_b128 v[186:189], v176 offset:52224
	ds_read_b128 v[190:193], v176 offset:53248
	ds_read_b128 v[194:197], v176 offset:54272
	ds_read_b128 v[198:201], v176 offset:55296
	ds_read_b128 v[202:205], v176 offset:56320
	s_add_i32 s87, s87, 2
	s_add_u32 s62, s62, 0x100
	s_addc_u32 s63, s63, 0
	s_add_u32 s98, s98, 0x100
	s_addc_u32 s99, s99, 0
	s_add_u32 s100, s100, 0x100
	s_addc_u32 s101, s101, 0
	s_cmp_gt_u32 s87, 27
	s_waitcnt vmcnt(8)
	s_waitcnt lgkmcnt(0)
	s_setprio 1
	s_barrier
	v_mfma_f32_16x16x32_bf16 v[14:17], v[154:157], v[138:141], v[14:17]
	v_mfma_f32_16x16x32_bf16 v[10:13], v[154:157], v[146:149], v[10:13]
	v_mfma_f32_16x16x32_bf16 v[6:9], v[182:185], v[138:141], v[6:9]
	v_mfma_f32_16x16x32_bf16 v[2:5], v[182:185], v[146:149], v[2:5]
	v_mfma_f32_16x16x32_bf16 v[46:49], v[190:193], v[138:141], v[46:49]
	v_mfma_f32_16x16x32_bf16 v[54:57], v[190:193], v[146:149], v[54:57]
	v_mfma_f32_16x16x32_bf16 v[58:61], v[198:201], v[138:141], v[58:61]
	v_mfma_f32_16x16x32_bf16 v[62:65], v[198:201], v[146:149], v[62:65]
	v_mfma_f32_16x16x32_bf16 v[14:17], v[158:161], v[142:145], v[14:17]
	v_mfma_f32_16x16x32_bf16 v[10:13], v[158:161], v[150:153], v[10:13]
	v_mfma_f32_16x16x32_bf16 v[6:9], v[186:189], v[142:145], v[6:9]
	v_mfma_f32_16x16x32_bf16 v[2:5], v[186:189], v[150:153], v[2:5]
	v_mfma_f32_16x16x32_bf16 v[46:49], v[194:197], v[142:145], v[46:49]
	v_mfma_f32_16x16x32_bf16 v[54:57], v[194:197], v[150:153], v[54:57]
	v_mfma_f32_16x16x32_bf16 v[58:61], v[202:205], v[142:145], v[58:61]
	v_mfma_f32_16x16x32_bf16 v[62:65], v[202:205], v[150:153], v[62:65]
	v_mfma_f32_16x16x32_bf16 v[66:69], v[154:157], v[206:209], v[66:69]
	v_mfma_f32_16x16x32_bf16 v[70:73], v[154:157], v[214:217], v[70:73]
	v_mfma_f32_16x16x32_bf16 v[74:77], v[182:185], v[206:209], v[74:77]
	v_mfma_f32_16x16x32_bf16 v[78:81], v[182:185], v[214:217], v[78:81]
	v_mfma_f32_16x16x32_bf16 v[82:85], v[190:193], v[206:209], v[82:85]
	v_mfma_f32_16x16x32_bf16 v[86:89], v[190:193], v[214:217], v[86:89]
	v_mfma_f32_16x16x32_bf16 v[90:93], v[198:201], v[206:209], v[90:93]
	v_mfma_f32_16x16x32_bf16 v[98:101], v[198:201], v[214:217], v[98:101]
	v_mfma_f32_16x16x32_bf16 v[66:69], v[158:161], v[210:213], v[66:69]
	v_mfma_f32_16x16x32_bf16 v[70:73], v[158:161], v[218:221], v[70:73]
	v_mfma_f32_16x16x32_bf16 v[74:77], v[186:189], v[210:213], v[74:77]
	v_mfma_f32_16x16x32_bf16 v[78:81], v[186:189], v[218:221], v[78:81]
	v_mfma_f32_16x16x32_bf16 v[82:85], v[194:197], v[210:213], v[82:85]
	v_mfma_f32_16x16x32_bf16 v[86:89], v[194:197], v[218:221], v[86:89]
	v_mfma_f32_16x16x32_bf16 v[90:93], v[202:205], v[210:213], v[90:93]
	v_mfma_f32_16x16x32_bf16 v[98:101], v[202:205], v[218:221], v[98:101]
	s_barrier
; #define LDA(dst, b, h)                                                                                     \
;   _Pragma("unroll") for (int m = 0; m < 4; ++m) _Pragma("unroll") for (int k = 0; k < 2; ++k) dst[m][k] = \
;       *reinterpret_cast<const bf16x8*>(shmc + aL + (((b) * 2 + (h)) * 16384 + (m * 2 + k) * 1024))
; #define LDB(dst, b, h)                                                                                     \
;   _Pragma("unroll") for (int n = 0; n < 2; ++n) _Pragma("unroll") for (int k = 0; k < 2; ++k) dst[n][k] = \
;       *reinterpret_cast<const bf16x8*>(shmc + bL + (((b) * 2 + (h)) * 16384 + (n * 2 + k) * 1024))
; #define OPAQ asm volatile("" : "+v"(aL), "+v"(bL))
; #define WAIT_V(n) asm volatile("s_waitcnt vmcnt(" #n ")" ::: "memory")
; #define WAIT_L(n) asm volatile("s_waitcnt lgkmcnt(" #n ")" ::: "memory")
; #define BAR __builtin_amdgcn_s_barrier()
; template <int EPI>
; __device__ __forceinline__ void phase_gemm(const Params& p, const GemmDesc& d, char* shmc) {
;     ...
;     {
;       OPAQ;
;       LDB(B0, 0, 0); LDA(At, 0, 0); STAGE_A(SA(1, 1), 1, nt - 1);
;       BAR; WAIT_L(0); MMA(0, 0, At, B0); BAR;
;       LDB(B1, 0, 1); BAR; WAIT_L(0); MMA(0, 1, At, B1); BAR;
;       LDA(At, 0, 1); WAIT_V(4); BAR; WAIT_L(0); MMA(1, 0, At, B0); MMA(1, 1, At, B1); BAR;
;     }
	s_cbranch_scc0 .LBB0_598
	s_setprio 0
	s_add_u32 s8, s8, 0x80f80
	s_addc_u32 s9, s9, 0
	v_add_u32_e32 v175, 0, v179
	v_add_u32_e32 v176, 0, v177
	s_mov_b32 m0, s88
	ds_read_b128 v[130:133], v175
	ds_read_b128 v[134:137], v175 offset:1024
	ds_read_b128 v[138:141], v175 offset:2048
	ds_read_b128 v[142:145], v175 offset:3072
	ds_read_b128 v[146:149], v176
	ds_read_b128 v[150:153], v176 offset:1024
	ds_read_b128 v[154:157], v176 offset:2048
	ds_read_b128 v[158:161], v176 offset:3072
	ds_read_b128 v[182:185], v176 offset:4096
	ds_read_b128 v[186:189], v176 offset:5120
	ds_read_b128 v[190:193], v176 offset:6144
	ds_read_b128 v[194:197], v176 offset:7168
	global_load_lds_dwordx4 v162, s[8:9]
	s_mov_b32 m0, s89
	s_nop 0
	global_load_lds_dwordx4 v174, s[8:9]
	s_waitcnt vmcnt(8)
	s_barrier
	s_waitcnt lgkmcnt(0)
	s_setprio 1
	s_waitcnt lgkmcnt(0)
	v_mfma_f32_16x16x32_bf16 v[126:129], v[146:149], v[130:133], v[126:129]
	v_mfma_f32_16x16x32_bf16 v[122:125], v[146:149], v[138:141], v[122:125]
	v_mfma_f32_16x16x32_bf16 v[114:117], v[154:157], v[138:141], v[114:117]
	v_mfma_f32_16x16x32_bf16 v[110:113], v[182:185], v[130:133], v[110:113]
	v_mfma_f32_16x16x32_bf16 v[126:129], v[150:153], v[134:137], v[126:129]
	v_mfma_f32_16x16x32_bf16 v[122:125], v[150:153], v[142:145], v[122:125]
	v_mfma_f32_16x16x32_bf16 v[118:121], v[154:157], v[130:133], v[118:121]
	v_mfma_f32_16x16x32_bf16 v[114:117], v[158:161], v[142:145], v[114:117]
	v_mfma_f32_16x16x32_bf16 v[110:113], v[186:189], v[134:137], v[110:113]
	v_mfma_f32_16x16x32_bf16 v[106:109], v[182:185], v[138:141], v[106:109]
	v_mfma_f32_16x16x32_bf16 v[102:105], v[190:193], v[130:133], v[102:105]
	v_mfma_f32_16x16x32_bf16 v[94:97], v[190:193], v[138:141], v[94:97]
	v_mfma_f32_16x16x32_bf16 v[118:121], v[158:161], v[134:137], v[118:121]
	v_mfma_f32_16x16x32_bf16 v[106:109], v[186:189], v[142:145], v[106:109]
	v_mfma_f32_16x16x32_bf16 v[102:105], v[194:197], v[134:137], v[102:105]
	v_mfma_f32_16x16x32_bf16 v[94:97], v[194:197], v[142:145], v[94:97]
	s_setprio 0
	s_barrier
	ds_read_b128 v[198:201], v175 offset:16384
	ds_read_b128 v[202:205], v175 offset:17408
	ds_read_b128 v[206:209], v175 offset:18432
	ds_read_b128 v[210:213], v175 offset:19456
	s_barrier
	s_waitcnt lgkmcnt(0)
	s_setprio 1
	s_waitcnt lgkmcnt(0)
	v_mfma_f32_16x16x32_bf16 v[50:53], v[146:149], v[198:201], v[50:53]
	v_mfma_f32_16x16x32_bf16 v[42:45], v[146:149], v[206:209], v[42:45]
	v_mfma_f32_16x16x32_bf16 v[38:41], v[154:157], v[198:201], v[38:41]
	v_mfma_f32_16x16x32_bf16 v[30:33], v[182:185], v[198:201], v[30:33]
	v_mfma_f32_16x16x32_bf16 v[22:25], v[190:193], v[198:201], v[22:25]
	v_mfma_f32_16x16x32_bf16 v[50:53], v[150:153], v[202:205], v[50:53]
	v_mfma_f32_16x16x32_bf16 v[42:45], v[150:153], v[210:213], v[42:45]
	v_mfma_f32_16x16x32_bf16 v[38:41], v[158:161], v[202:205], v[38:41]
	v_mfma_f32_16x16x32_bf16 v[34:37], v[154:157], v[206:209], v[34:37]
	v_mfma_f32_16x16x32_bf16 v[30:33], v[186:189], v[202:205], v[30:33]
	v_mfma_f32_16x16x32_bf16 v[26:29], v[182:185], v[206:209], v[26:29]
	v_mfma_f32_16x16x32_bf16 v[22:25], v[194:197], v[202:205], v[22:25]
	v_mfma_f32_16x16x32_bf16 v[18:21], v[190:193], v[206:209], v[18:21]
	v_mfma_f32_16x16x32_bf16 v[34:37], v[158:161], v[210:213], v[34:37]
	v_mfma_f32_16x16x32_bf16 v[26:29], v[186:189], v[210:213], v[26:29]
	v_mfma_f32_16x16x32_bf16 v[18:21], v[194:197], v[210:213], v[18:21]
	s_setprio 0
	s_barrier
	ds_read_b128 v[146:149], v176 offset:16384
	ds_read_b128 v[150:153], v176 offset:17408
	ds_read_b128 v[154:157], v176 offset:18432
	ds_read_b128 v[158:161], v176 offset:19456
	ds_read_b128 v[182:185], v176 offset:20480
	ds_read_b128 v[186:189], v176 offset:21504
	ds_read_b128 v[190:193], v176 offset:22528
	ds_read_b128 v[194:197], v176 offset:23552
	s_waitcnt vmcnt(4)
	s_barrier
	s_waitcnt lgkmcnt(0)
	s_setprio 1
	s_waitcnt lgkmcnt(0)
	v_mfma_f32_16x16x32_bf16 v[14:17], v[146:149], v[130:133], v[14:17]
	v_mfma_f32_16x16x32_bf16 v[6:9], v[154:157], v[130:133], v[6:9]
	v_mfma_f32_16x16x32_bf16 v[2:5], v[154:157], v[138:141], v[2:5]
	v_mfma_f32_16x16x32_bf16 v[46:49], v[182:185], v[130:133], v[46:49]
	v_mfma_f32_16x16x32_bf16 v[54:57], v[182:185], v[138:141], v[54:57]
	v_mfma_f32_16x16x32_bf16 v[58:61], v[190:193], v[130:133], v[58:61]
	v_mfma_f32_16x16x32_bf16 v[14:17], v[150:153], v[134:137], v[14:17]
	v_mfma_f32_16x16x32_bf16 v[10:13], v[146:149], v[138:141], v[10:13]
	v_mfma_f32_16x16x32_bf16 v[6:9], v[158:161], v[134:137], v[6:9]
	v_mfma_f32_16x16x32_bf16 v[2:5], v[158:161], v[142:145], v[2:5]
	v_mfma_f32_16x16x32_bf16 v[46:49], v[186:189], v[134:137], v[46:49]
	v_mfma_f32_16x16x32_bf16 v[54:57], v[186:189], v[142:145], v[54:57]
	v_mfma_f32_16x16x32_bf16 v[214:217], v[194:197], v[134:137], v[58:61]
	v_mfma_f32_16x16x32_bf16 v[58:61], v[190:193], v[138:141], v[62:65]
	v_mfma_f32_16x16x32_bf16 v[10:13], v[150:153], v[142:145], v[10:13]
	v_mfma_f32_16x16x32_bf16 v[218:221], v[194:197], v[142:145], v[58:61]
	s_setprio 0
	s_setprio 1
	v_mfma_f32_16x16x32_bf16 v[58:61], v[146:149], v[198:201], v[66:69]
	v_mfma_f32_16x16x32_bf16 v[222:225], v[150:153], v[202:205], v[58:61]
	v_mfma_f32_16x16x32_bf16 v[58:61], v[146:149], v[206:209], v[70:73]
	v_mfma_f32_16x16x32_bf16 v[226:229], v[150:153], v[210:213], v[58:61]
	v_mfma_f32_16x16x32_bf16 v[58:61], v[154:157], v[198:201], v[74:77]
	v_mfma_f32_16x16x32_bf16 v[230:233], v[158:161], v[202:205], v[58:61]
	v_mfma_f32_16x16x32_bf16 v[58:61], v[154:157], v[206:209], v[78:81]
	v_mfma_f32_16x16x32_bf16 v[234:237], v[158:161], v[210:213], v[58:61]
	v_mfma_f32_16x16x32_bf16 v[58:61], v[182:185], v[198:201], v[82:85]
	v_mfma_f32_16x16x32_bf16 v[238:241], v[186:189], v[202:205], v[58:61]
	v_mfma_f32_16x16x32_bf16 v[58:61], v[182:185], v[206:209], v[86:89]
	v_mfma_f32_16x16x32_bf16 v[182:185], v[186:189], v[210:213], v[58:61]
	v_mfma_f32_16x16x32_bf16 v[58:61], v[190:193], v[198:201], v[90:93]
	v_mfma_f32_16x16x32_bf16 v[186:189], v[194:197], v[202:205], v[58:61]
	v_mfma_f32_16x16x32_bf16 v[58:61], v[190:193], v[206:209], v[98:101]
	v_mfma_f32_16x16x32_bf16 v[190:193], v[194:197], v[210:213], v[58:61]
	s_setprio 0
	s_barrier
; #define LDA(dst, b, h)                                                                                     \
;   _Pragma("unroll") for (int m = 0; m < 4; ++m) _Pragma("unroll") for (int k = 0; k < 2; ++k) dst[m][k] = \
;       *reinterpret_cast<const bf16x8*>(shmc + aL + (((b) * 2 + (h)) * 16384 + (m * 2 + k) * 1024))
; #define LDB(dst, b, h)                                                                                     \
;   _Pragma("unroll") for (int n = 0; n < 2; ++n) _Pragma("unroll") for (int k = 0; k < 2; ++k) dst[n][k] = \
;       *reinterpret_cast<const bf16x8*>(shmc + bL + (((b) * 2 + (h)) * 16384 + (n * 2 + k) * 1024))
; #define WAIT_V(n) asm volatile("s_waitcnt vmcnt(" #n ")" ::: "memory")
; #define WAIT_L(n) asm volatile("s_waitcnt lgkmcnt(" #n ")" ::: "memory")
; #define BAR __builtin_amdgcn_s_barrier()
; template <int EPI>
; __device__ __forceinline__ void phase_gemm(const Params& p, const GemmDesc& d, char* shmc) {
;     ...
;     {
;       LDB(B0, 1, 0); LDA(At, 1, 0); WAIT_V(2); BAR; WAIT_L(0); MMA(0, 0, At, B0); BAR;
;       LDB(B1, 1, 1); WAIT_V(0); BAR; WAIT_L(0); MMA(0, 1, At, B1); BAR;
;       LDA(At, 1, 1); BAR; WAIT_L(0); MMA(1, 0, At, B0); MMA(1, 1, At, B1); BAR;
;     }
;     if (wr == 0) BAR;
	ds_read_b128 v[66:69], v175 offset:32768
	ds_read_b128 v[194:197], v175 offset:33792
	ds_read_b128 v[198:201], v175 offset:34816
	ds_read_b128 v[202:205], v175 offset:35840
	s_nop 0
	ds_read_b128 v[58:61], v176 offset:32768
	ds_read_b128 v[62:65], v176 offset:33792
	ds_read_b128 v[70:73], v176 offset:34816
	ds_read_b128 v[74:77], v176 offset:35840
	ds_read_b128 v[78:81], v176 offset:36864
	ds_read_b128 v[82:85], v176 offset:37888
	ds_read_b128 v[206:209], v176 offset:38912
	ds_read_b128 v[210:213], v176 offset:39936
	s_waitcnt vmcnt(2)
	s_barrier
	s_waitcnt lgkmcnt(0)
	s_setprio 1
	s_waitcnt lgkmcnt(0)
	v_mfma_f32_16x16x32_bf16 v[86:89], v[58:61], v[66:69], v[126:129]
	v_mfma_f32_16x16x32_bf16 v[158:161], v[62:65], v[194:197], v[86:89]
	v_mfma_f32_16x16x32_bf16 v[86:89], v[58:61], v[198:201], v[122:125]
	v_mfma_f32_16x16x32_bf16 v[142:145], v[62:65], v[202:205], v[86:89]
	v_mfma_f32_16x16x32_bf16 v[86:89], v[70:73], v[66:69], v[118:121]
	v_mfma_f32_16x16x32_bf16 v[154:157], v[74:77], v[194:197], v[86:89]
	v_mfma_f32_16x16x32_bf16 v[86:89], v[70:73], v[198:201], v[114:117]
	v_mfma_f32_16x16x32_bf16 v[138:141], v[74:77], v[202:205], v[86:89]
	v_mfma_f32_16x16x32_bf16 v[86:89], v[78:81], v[66:69], v[110:113]
	v_mfma_f32_16x16x32_bf16 v[150:153], v[82:85], v[194:197], v[86:89]
	v_mfma_f32_16x16x32_bf16 v[86:89], v[78:81], v[198:201], v[106:109]
	v_mfma_f32_16x16x32_bf16 v[134:137], v[82:85], v[202:205], v[86:89]
	v_mfma_f32_16x16x32_bf16 v[86:89], v[206:209], v[66:69], v[102:105]
	v_mfma_f32_16x16x32_bf16 v[146:149], v[210:213], v[194:197], v[86:89]
	v_mfma_f32_16x16x32_bf16 v[86:89], v[206:209], v[198:201], v[94:97]
	v_mfma_f32_16x16x32_bf16 v[130:133], v[210:213], v[202:205], v[86:89]
	s_setprio 0
	s_barrier
	ds_read_b128 v[94:97], v175 offset:49152
	ds_read_b128 v[102:105], v175 offset:50176
	ds_read_b128 v[106:109], v175 offset:51200
	ds_read_b128 v[118:121], v175 offset:52224
	s_waitcnt vmcnt(0)
	s_barrier
	s_waitcnt lgkmcnt(0)
	s_setprio 1
	s_waitcnt lgkmcnt(0)
	v_mfma_f32_16x16x32_bf16 v[50:53], v[58:61], v[94:97], v[50:53]
	v_mfma_f32_16x16x32_bf16 v[42:45], v[58:61], v[106:109], v[42:45]
	v_mfma_f32_16x16x32_bf16 v[38:41], v[70:73], v[94:97], v[38:41]
	v_mfma_f32_16x16x32_bf16 v[34:37], v[70:73], v[106:109], v[34:37]
	v_mfma_f32_16x16x32_bf16 v[30:33], v[78:81], v[94:97], v[30:33]
	v_mfma_f32_16x16x32_bf16 v[26:29], v[78:81], v[106:109], v[26:29]
	v_mfma_f32_16x16x32_bf16 v[22:25], v[206:209], v[94:97], v[22:25]
	v_mfma_f32_16x16x32_bf16 v[18:21], v[206:209], v[106:109], v[18:21]
	v_mfma_f32_16x16x32_bf16 v[126:129], v[62:65], v[102:105], v[50:53]
	v_mfma_f32_16x16x32_bf16 v[98:101], v[62:65], v[118:121], v[42:45]
	v_mfma_f32_16x16x32_bf16 v[122:125], v[74:77], v[102:105], v[38:41]
	v_mfma_f32_16x16x32_bf16 v[90:93], v[74:77], v[118:121], v[34:37]
	v_mfma_f32_16x16x32_bf16 v[114:117], v[82:85], v[102:105], v[30:33]
	v_mfma_f32_16x16x32_bf16 v[86:89], v[82:85], v[118:121], v[26:29]
	v_mfma_f32_16x16x32_bf16 v[110:113], v[210:213], v[102:105], v[22:25]
	v_mfma_f32_16x16x32_bf16 v[82:85], v[210:213], v[118:121], v[18:21]
	s_setprio 0
	s_barrier
	s_nop 0
	ds_read_b128 v[18:21], v176 offset:49152
	ds_read_b128 v[22:25], v176 offset:50176
	ds_read_b128 v[26:29], v176 offset:51200
	ds_read_b128 v[30:33], v176 offset:52224
	ds_read_b128 v[34:37], v176 offset:53248
	ds_read_b128 v[206:209], v176 offset:54272
	ds_read_b128 v[210:213], v176 offset:55296
	ds_read_b128 v[242:245], v176 offset:56320
	s_barrier
	s_waitcnt lgkmcnt(0)
	s_setprio 1
	s_waitcnt lgkmcnt(0)
	v_mfma_f32_16x16x32_bf16 v[2:5], v[26:29], v[198:201], v[2:5]
	v_mfma_f32_16x16x32_bf16 v[58:61], v[30:33], v[202:205], v[2:5]
	v_mfma_f32_16x16x32_bf16 v[2:5], v[34:37], v[66:69], v[46:49]
	v_mfma_f32_16x16x32_bf16 v[70:73], v[206:209], v[194:197], v[2:5]
	v_mfma_f32_16x16x32_bf16 v[2:5], v[34:37], v[198:201], v[54:57]
	v_mfma_f32_16x16x32_bf16 v[54:57], v[206:209], v[202:205], v[2:5]
	v_mfma_f32_16x16x32_bf16 v[2:5], v[210:213], v[66:69], v[214:217]
	v_mfma_f32_16x16x32_bf16 v[14:17], v[18:21], v[66:69], v[14:17]
	v_mfma_f32_16x16x32_bf16 v[10:13], v[18:21], v[198:201], v[10:13]
	v_mfma_f32_16x16x32_bf16 v[6:9], v[26:29], v[66:69], v[6:9]
	v_mfma_f32_16x16x32_bf16 v[66:69], v[242:245], v[194:197], v[2:5]
	v_mfma_f32_16x16x32_bf16 v[2:5], v[210:213], v[198:201], v[218:221]
	v_mfma_f32_16x16x32_bf16 v[78:81], v[22:25], v[194:197], v[14:17]
	v_mfma_f32_16x16x32_bf16 v[62:65], v[22:25], v[202:205], v[10:13]
	v_mfma_f32_16x16x32_bf16 v[74:77], v[30:33], v[194:197], v[6:9]
	v_mfma_f32_16x16x32_bf16 v[50:53], v[242:245], v[202:205], v[2:5]
	s_setprio 0
	s_setprio 1
	v_mfma_f32_16x16x32_bf16 v[2:5], v[18:21], v[94:97], v[222:225]
	v_mfma_f32_16x16x32_bf16 v[46:49], v[22:25], v[102:105], v[2:5]
	v_mfma_f32_16x16x32_bf16 v[2:5], v[18:21], v[106:109], v[226:229]
	v_mfma_f32_16x16x32_bf16 v[22:25], v[22:25], v[118:121], v[2:5]
	v_mfma_f32_16x16x32_bf16 v[2:5], v[26:29], v[94:97], v[230:233]
	v_mfma_f32_16x16x32_bf16 v[42:45], v[30:33], v[102:105], v[2:5]
	v_mfma_f32_16x16x32_bf16 v[2:5], v[26:29], v[106:109], v[234:237]
	v_mfma_f32_16x16x32_bf16 v[14:17], v[30:33], v[118:121], v[2:5]
	v_mfma_f32_16x16x32_bf16 v[2:5], v[34:37], v[94:97], v[238:241]
	v_mfma_f32_16x16x32_bf16 v[38:41], v[206:209], v[102:105], v[2:5]
	v_mfma_f32_16x16x32_bf16 v[2:5], v[34:37], v[106:109], v[182:185]
	v_mfma_f32_16x16x32_bf16 v[6:9], v[206:209], v[118:121], v[2:5]
	v_mfma_f32_16x16x32_bf16 v[2:5], v[210:213], v[94:97], v[186:189]
	v_mfma_f32_16x16x32_bf16 v[30:33], v[242:245], v[102:105], v[2:5]
	v_mfma_f32_16x16x32_bf16 v[2:5], v[210:213], v[106:109], v[190:193]
	v_mfma_f32_16x16x32_bf16 v[2:5], v[242:245], v[118:121], v[2:5]
	s_setprio 0
	s_barrier
	s_and_saveexec_b64 s[8:9], s[6:7]
	s_cbranch_execz .LBB0_601
	s_barrier

; #define LDA(dst, b, h)                                                                                     \
;   _Pragma("unroll") for (int m = 0; m < 4; ++m) _Pragma("unroll") for (int k = 0; k < 2; ++k) dst[m][k] = \
;       *reinterpret_cast<const bf16x8*>(shmc + aL + (((b) * 2 + (h)) * 16384 + (m * 2 + k) * 1024))
; #define LDB(dst, b, h)                                                                                     \
;   _Pragma("unroll") for (int n = 0; n < 2; ++n) _Pragma("unroll") for (int k = 0; k < 2; ++k) dst[n][k] = \
;       *reinterpret_cast<const bf16x8*>(shmc + bL + (((b) * 2 + (h)) * 16384 + (n * 2 + k) * 1024))
; #define OPAQ asm volatile("" : "+v"(aL), "+v"(bL))
; #define WAIT_V(n) asm volatile("s_waitcnt vmcnt(" #n ")" ::: "memory")
; #define WAIT_L(n) asm volatile("s_waitcnt lgkmcnt(" #n ")" ::: "memory")
; #define BAR __builtin_amdgcn_s_barrier()
; #define SCHED __builtin_amdgcn_sched_barrier(0)
; template <int EPI>
; __device__ __forceinline__ void phase_gemm(const Params& p, const GemmDesc& d, char* shmc) {
;     ...
;     for (int t = 0; t < nt - 2; t += 2) {
;       OPAQ;
;       LDB(B0, 0, 0); SCHED; LDA(At, 0, 0); STAGE_A(SA(1, 1), 1, t + 1);
;       WAIT_L(8); BAR; WAIT_L(0); MMA(0, 0, At, B0); BAR; SCHED;
;       LDB(B1, 0, 1); STAGE_B(SB(0, 0), 0, t + 2);
;       BAR; WAIT_L(0); MMA(0, 1, At, B1); BAR;
;       LDA(At, 0, 1); STAGE_A(SA(0, 0), 0, t + 2);
;       BAR; WAIT_L(0); MMA(1, 0, At, B0); BAR; SCHED;
;       STAGE_B(SB(0, 1), 1, t + 2);
;       WAIT_V(6); BAR; MMA(1, 1, At, B1); BAR;
.LBB0_1010:
	s_nop 0
	v_add_u32_e32 v130, 0, v153
	v_add_u32_e32 v141, 0, v152
	s_setprio 0
	s_mov_b32 m0, s80
	s_nop 0
	global_load_lds_dwordx4 v220, s[98:99]
	s_mov_b32 m0, s81
	s_nop 0
	global_load_lds_dwordx4 v221, s[98:99]
	ds_read_b128 v[156:159], v130
	ds_read_b128 v[160:163], v130 offset:1024
	ds_read_b128 v[164:167], v130 offset:2048
	ds_read_b128 v[168:171], v130 offset:3072
	ds_read_b128 v[204:207], v130 offset:16384
	ds_read_b128 v[208:211], v130 offset:17408
	ds_read_b128 v[212:215], v130 offset:18432
	ds_read_b128 v[216:219], v130 offset:19456
	ds_read_b128 v[172:175], v141
	ds_read_b128 v[176:179], v141 offset:1024
	ds_read_b128 v[180:183], v141 offset:2048
	ds_read_b128 v[184:187], v141 offset:3072
	ds_read_b128 v[188:191], v141 offset:4096
	ds_read_b128 v[192:195], v141 offset:5120
	ds_read_b128 v[196:199], v141 offset:6144
	ds_read_b128 v[200:203], v141 offset:7168
	s_waitcnt vmcnt(8)
	s_waitcnt lgkmcnt(0)
	s_setprio 1
	s_barrier
	v_mfma_f32_16x16x32_bf16 v[126:129], v[156:159], v[172:175], v[126:129]
	v_mfma_f32_16x16x32_bf16 v[122:125], v[164:167], v[172:175], v[122:125]
	v_mfma_f32_16x16x32_bf16 v[118:121], v[156:159], v[180:183], v[118:121]
	v_mfma_f32_16x16x32_bf16 v[114:117], v[164:167], v[180:183], v[114:117]
	v_mfma_f32_16x16x32_bf16 v[110:113], v[156:159], v[188:191], v[110:113]
	v_mfma_f32_16x16x32_bf16 v[106:109], v[164:167], v[188:191], v[106:109]
	v_mfma_f32_16x16x32_bf16 v[102:105], v[156:159], v[196:199], v[102:105]
	v_mfma_f32_16x16x32_bf16 v[98:101], v[164:167], v[196:199], v[98:101]
	v_mfma_f32_16x16x32_bf16 v[126:129], v[160:163], v[176:179], v[126:129]
	v_mfma_f32_16x16x32_bf16 v[122:125], v[168:171], v[176:179], v[122:125]
	v_mfma_f32_16x16x32_bf16 v[118:121], v[160:163], v[184:187], v[118:121]
	v_mfma_f32_16x16x32_bf16 v[114:117], v[168:171], v[184:187], v[114:117]
	v_mfma_f32_16x16x32_bf16 v[110:113], v[160:163], v[192:195], v[110:113]
	v_mfma_f32_16x16x32_bf16 v[106:109], v[168:171], v[192:195], v[106:109]
	v_mfma_f32_16x16x32_bf16 v[102:105], v[160:163], v[200:203], v[102:105]
	v_mfma_f32_16x16x32_bf16 v[98:101], v[168:171], v[200:203], v[98:101]
	v_mfma_f32_16x16x32_bf16 v[86:89], v[204:207], v[172:175], v[86:89]
	v_mfma_f32_16x16x32_bf16 v[70:73], v[212:215], v[172:175], v[70:73]
	v_mfma_f32_16x16x32_bf16 v[54:57], v[204:207], v[180:183], v[54:57]
	v_mfma_f32_16x16x32_bf16 v[50:53], v[212:215], v[180:183], v[50:53]
	v_mfma_f32_16x16x32_bf16 v[46:49], v[204:207], v[188:191], v[46:49]
	v_mfma_f32_16x16x32_bf16 v[42:45], v[212:215], v[188:191], v[42:45]
	v_mfma_f32_16x16x32_bf16 v[38:41], v[204:207], v[196:199], v[38:41]
	v_mfma_f32_16x16x32_bf16 v[34:37], v[212:215], v[196:199], v[34:37]
	v_mfma_f32_16x16x32_bf16 v[86:89], v[208:211], v[176:179], v[86:89]
	v_mfma_f32_16x16x32_bf16 v[70:73], v[216:219], v[176:179], v[70:73]
	v_mfma_f32_16x16x32_bf16 v[54:57], v[208:211], v[184:187], v[54:57]
	v_mfma_f32_16x16x32_bf16 v[50:53], v[216:219], v[184:187], v[50:53]
	v_mfma_f32_16x16x32_bf16 v[46:49], v[208:211], v[192:195], v[46:49]
	v_mfma_f32_16x16x32_bf16 v[42:45], v[216:219], v[192:195], v[42:45]
	v_mfma_f32_16x16x32_bf16 v[38:41], v[208:211], v[200:203], v[38:41]
	v_mfma_f32_16x16x32_bf16 v[34:37], v[216:219], v[200:203], v[34:37]
	s_barrier
	s_setprio 0
	s_mov_b32 m0, s35
	s_nop 0
	global_load_lds_dwordx4 v222, s[100:101]
	s_mov_b32 m0, s64
	s_nop 0
	global_load_lds_dwordx4 v223, s[100:101]
	s_mov_b32 m0, s34
	s_nop 0
	global_load_lds_dwordx4 v224, s[98:99]
	s_mov_b32 m0, s65
	s_nop 0
	global_load_lds_dwordx4 v225, s[98:99]
	s_mov_b32 m0, s66
	s_nop 0
	global_load_lds_dwordx4 v226, s[100:101]
	s_mov_b32 m0, s67
	s_nop 0
	global_load_lds_dwordx4 v227, s[100:101]
	ds_read_b128 v[172:175], v141 offset:16384
	ds_read_b128 v[176:179], v141 offset:17408
	ds_read_b128 v[180:183], v141 offset:18432
	ds_read_b128 v[184:187], v141 offset:19456
	ds_read_b128 v[188:191], v141 offset:20480
	ds_read_b128 v[192:195], v141 offset:21504
	ds_read_b128 v[196:199], v141 offset:22528
	ds_read_b128 v[200:203], v141 offset:23552
	s_waitcnt vmcnt(8)
	s_waitcnt lgkmcnt(0)
	s_setprio 1
	s_barrier
	v_mfma_f32_16x16x32_bf16 v[30:33], v[156:159], v[172:175], v[30:33]
	v_mfma_f32_16x16x32_bf16 v[26:29], v[164:167], v[172:175], v[26:29]
	v_mfma_f32_16x16x32_bf16 v[22:25], v[156:159], v[180:183], v[22:25]
	v_mfma_f32_16x16x32_bf16 v[18:21], v[164:167], v[180:183], v[18:21]
	v_mfma_f32_16x16x32_bf16 v[14:17], v[156:159], v[188:191], v[14:17]
	v_mfma_f32_16x16x32_bf16 v[10:13], v[164:167], v[188:191], v[10:13]
	v_mfma_f32_16x16x32_bf16 v[6:9], v[156:159], v[196:199], v[6:9]
	v_mfma_f32_16x16x32_bf16 v[2:5], v[164:167], v[196:199], v[2:5]
	v_mfma_f32_16x16x32_bf16 v[30:33], v[160:163], v[176:179], v[30:33]
	v_mfma_f32_16x16x32_bf16 v[26:29], v[168:171], v[176:179], v[26:29]
	v_mfma_f32_16x16x32_bf16 v[22:25], v[160:163], v[184:187], v[22:25]
	v_mfma_f32_16x16x32_bf16 v[18:21], v[168:171], v[184:187], v[18:21]
	v_mfma_f32_16x16x32_bf16 v[14:17], v[160:163], v[192:195], v[14:17]
	v_mfma_f32_16x16x32_bf16 v[10:13], v[168:171], v[192:195], v[10:13]
	v_mfma_f32_16x16x32_bf16 v[6:9], v[160:163], v[200:203], v[6:9]
	v_mfma_f32_16x16x32_bf16 v[2:5], v[168:171], v[200:203], v[2:5]
	v_mfma_f32_16x16x32_bf16 v[58:61], v[204:207], v[172:175], v[58:61]
	v_mfma_f32_16x16x32_bf16 v[62:65], v[212:215], v[172:175], v[62:65]
	v_mfma_f32_16x16x32_bf16 v[66:69], v[204:207], v[180:183], v[66:69]
	v_mfma_f32_16x16x32_bf16 v[74:77], v[212:215], v[180:183], v[74:77]
	v_mfma_f32_16x16x32_bf16 v[78:81], v[204:207], v[188:191], v[78:81]
	v_mfma_f32_16x16x32_bf16 v[82:85], v[212:215], v[188:191], v[82:85]
	v_mfma_f32_16x16x32_bf16 v[90:93], v[204:207], v[196:199], v[90:93]
	v_mfma_f32_16x16x32_bf16 v[94:97], v[212:215], v[196:199], v[94:97]
	v_mfma_f32_16x16x32_bf16 v[58:61], v[208:211], v[176:179], v[58:61]
	v_mfma_f32_16x16x32_bf16 v[62:65], v[216:219], v[176:179], v[62:65]
	v_mfma_f32_16x16x32_bf16 v[66:69], v[208:211], v[184:187], v[66:69]
	v_mfma_f32_16x16x32_bf16 v[74:77], v[216:219], v[184:187], v[74:77]
	v_mfma_f32_16x16x32_bf16 v[78:81], v[208:211], v[192:195], v[78:81]
	v_mfma_f32_16x16x32_bf16 v[82:85], v[216:219], v[192:195], v[82:85]
	v_mfma_f32_16x16x32_bf16 v[90:93], v[208:211], v[200:203], v[90:93]
	v_mfma_f32_16x16x32_bf16 v[94:97], v[216:219], v[200:203], v[94:97]
	s_barrier
; #define LDA(dst, b, h)                                                                                     \
;   _Pragma("unroll") for (int m = 0; m < 4; ++m) _Pragma("unroll") for (int k = 0; k < 2; ++k) dst[m][k] = \
;       *reinterpret_cast<const bf16x8*>(shmc + aL + (((b) * 2 + (h)) * 16384 + (m * 2 + k) * 1024))
; #define LDB(dst, b, h)                                                                                     \
;   _Pragma("unroll") for (int n = 0; n < 2; ++n) _Pragma("unroll") for (int k = 0; k < 2; ++k) dst[n][k] = \
;       *reinterpret_cast<const bf16x8*>(shmc + bL + (((b) * 2 + (h)) * 16384 + (n * 2 + k) * 1024))
; #define WAIT_V(n) asm volatile("s_waitcnt vmcnt(" #n ")" ::: "memory")
; #define WAIT_L(n) asm volatile("s_waitcnt lgkmcnt(" #n ")" ::: "memory")
; #define BAR __builtin_amdgcn_s_barrier()
; #define SCHED __builtin_amdgcn_sched_barrier(0)
; template <int EPI>
; __device__ __forceinline__ void phase_gemm(const Params& p, const GemmDesc& d, char* shmc) {
;     ...
;       LDB(B0, 1, 0); SCHED; LDA(At, 1, 0); STAGE_A(SA(0, 1), 1, t + 2);
;       WAIT_L(8); BAR; WAIT_L(0); MMA(0, 0, At, B0); BAR; SCHED;
;       LDB(B1, 1, 1); STAGE_B(SB(1, 0), 0, t + 3);
;       BAR; WAIT_L(0); MMA(0, 1, At, B1); BAR;
;       LDA(At, 1, 1); STAGE_A(SA(1, 0), 0, t + 3);
;       BAR; WAIT_L(0); MMA(1, 0, At, B0); BAR; SCHED;
;       STAGE_B(SB(1, 1), 1, t + 3);
;       WAIT_V(6); BAR; MMA(1, 1, At, B1); BAR;
	s_setprio 0
	s_mov_b32 m0, s68
	s_nop 0
	global_load_lds_dwordx4 v228, s[98:99]
	s_mov_b32 m0, s69
	s_nop 0
	global_load_lds_dwordx4 v229, s[98:99]
	ds_read_b128 v[156:159], v130 offset:32768
	ds_read_b128 v[160:163], v130 offset:33792
	ds_read_b128 v[164:167], v130 offset:34816
	ds_read_b128 v[168:171], v130 offset:35840
	ds_read_b128 v[204:207], v130 offset:49152
	ds_read_b128 v[208:211], v130 offset:50176
	ds_read_b128 v[212:215], v130 offset:51200
	ds_read_b128 v[216:219], v130 offset:52224
	ds_read_b128 v[172:175], v141 offset:32768
	ds_read_b128 v[176:179], v141 offset:33792
	ds_read_b128 v[180:183], v141 offset:34816
	ds_read_b128 v[184:187], v141 offset:35840
	ds_read_b128 v[188:191], v141 offset:36864
	ds_read_b128 v[192:195], v141 offset:37888
	ds_read_b128 v[196:199], v141 offset:38912
	ds_read_b128 v[200:203], v141 offset:39936
	s_waitcnt vmcnt(8)
	s_waitcnt lgkmcnt(0)
	s_setprio 1
	s_barrier
	v_mfma_f32_16x16x32_bf16 v[126:129], v[156:159], v[172:175], v[126:129]
	v_mfma_f32_16x16x32_bf16 v[122:125], v[164:167], v[172:175], v[122:125]
	v_mfma_f32_16x16x32_bf16 v[118:121], v[156:159], v[180:183], v[118:121]
	v_mfma_f32_16x16x32_bf16 v[114:117], v[164:167], v[180:183], v[114:117]
	v_mfma_f32_16x16x32_bf16 v[110:113], v[156:159], v[188:191], v[110:113]
	v_mfma_f32_16x16x32_bf16 v[106:109], v[164:167], v[188:191], v[106:109]
	v_mfma_f32_16x16x32_bf16 v[102:105], v[156:159], v[196:199], v[102:105]
	v_mfma_f32_16x16x32_bf16 v[98:101], v[164:167], v[196:199], v[98:101]
	v_mfma_f32_16x16x32_bf16 v[126:129], v[160:163], v[176:179], v[126:129]
	v_mfma_f32_16x16x32_bf16 v[122:125], v[168:171], v[176:179], v[122:125]
	v_mfma_f32_16x16x32_bf16 v[118:121], v[160:163], v[184:187], v[118:121]
	v_mfma_f32_16x16x32_bf16 v[114:117], v[168:171], v[184:187], v[114:117]
	v_mfma_f32_16x16x32_bf16 v[110:113], v[160:163], v[192:195], v[110:113]
	v_mfma_f32_16x16x32_bf16 v[106:109], v[168:171], v[192:195], v[106:109]
	v_mfma_f32_16x16x32_bf16 v[102:105], v[160:163], v[200:203], v[102:105]
	v_mfma_f32_16x16x32_bf16 v[98:101], v[168:171], v[200:203], v[98:101]
	v_mfma_f32_16x16x32_bf16 v[86:89], v[204:207], v[172:175], v[86:89]
	v_mfma_f32_16x16x32_bf16 v[70:73], v[212:215], v[172:175], v[70:73]
	v_mfma_f32_16x16x32_bf16 v[54:57], v[204:207], v[180:183], v[54:57]
	v_mfma_f32_16x16x32_bf16 v[50:53], v[212:215], v[180:183], v[50:53]
	v_mfma_f32_16x16x32_bf16 v[46:49], v[204:207], v[188:191], v[46:49]
	v_mfma_f32_16x16x32_bf16 v[42:45], v[212:215], v[188:191], v[42:45]
	v_mfma_f32_16x16x32_bf16 v[38:41], v[204:207], v[196:199], v[38:41]
	v_mfma_f32_16x16x32_bf16 v[34:37], v[212:215], v[196:199], v[34:37]
	v_mfma_f32_16x16x32_bf16 v[86:89], v[208:211], v[176:179], v[86:89]
	v_mfma_f32_16x16x32_bf16 v[70:73], v[216:219], v[176:179], v[70:73]
	v_mfma_f32_16x16x32_bf16 v[54:57], v[208:211], v[184:187], v[54:57]
	v_mfma_f32_16x16x32_bf16 v[50:53], v[216:219], v[184:187], v[50:53]
	v_mfma_f32_16x16x32_bf16 v[46:49], v[208:211], v[192:195], v[46:49]
	v_mfma_f32_16x16x32_bf16 v[42:45], v[216:219], v[192:195], v[42:45]
	v_mfma_f32_16x16x32_bf16 v[38:41], v[208:211], v[200:203], v[38:41]
	v_mfma_f32_16x16x32_bf16 v[34:37], v[216:219], v[200:203], v[34:37]
	s_barrier
	s_setprio 0
	s_mov_b32 m0, s70
	s_nop 0
	global_load_lds_dwordx4 v232, s[100:101]
	s_mov_b32 m0, s71
	s_nop 0
	global_load_lds_dwordx4 v233, s[100:101]
	s_mov_b32 m0, s76
	s_nop 0
	global_load_lds_dwordx4 v234, s[98:99]
	s_mov_b32 m0, s77
	s_nop 0
	global_load_lds_dwordx4 v235, s[98:99]
	s_mov_b32 m0, s78
	s_nop 0
	global_load_lds_dwordx4 v236, s[100:101]
	s_mov_b32 m0, s79
	s_nop 0
	global_load_lds_dwordx4 v237, s[100:101]
	ds_read_b128 v[172:175], v141 offset:49152
	ds_read_b128 v[176:179], v141 offset:50176
	ds_read_b128 v[180:183], v141 offset:51200
	ds_read_b128 v[184:187], v141 offset:52224
	ds_read_b128 v[188:191], v141 offset:53248
	ds_read_b128 v[192:195], v141 offset:54272
	ds_read_b128 v[196:199], v141 offset:55296
	ds_read_b128 v[200:203], v141 offset:56320
	s_add_i32 s53, s53, 2
	s_add_u32 s58, s58, 0x100
	s_addc_u32 s59, s59, 0
	s_add_u32 s98, s98, 0x100
	s_addc_u32 s99, s99, 0
	s_add_u32 s100, s100, 0x100
	s_addc_u32 s101, s101, 0
	s_cmp_gt_u32 s53, 27
	s_waitcnt vmcnt(8)
	s_waitcnt lgkmcnt(0)
	s_setprio 1
	s_barrier
	v_mfma_f32_16x16x32_bf16 v[30:33], v[156:159], v[172:175], v[30:33]
	v_mfma_f32_16x16x32_bf16 v[26:29], v[164:167], v[172:175], v[26:29]
	v_mfma_f32_16x16x32_bf16 v[22:25], v[156:159], v[180:183], v[22:25]
	v_mfma_f32_16x16x32_bf16 v[18:21], v[164:167], v[180:183], v[18:21]
	v_mfma_f32_16x16x32_bf16 v[14:17], v[156:159], v[188:191], v[14:17]
	v_mfma_f32_16x16x32_bf16 v[10:13], v[164:167], v[188:191], v[10:13]
	v_mfma_f32_16x16x32_bf16 v[6:9], v[156:159], v[196:199], v[6:9]
	v_mfma_f32_16x16x32_bf16 v[2:5], v[164:167], v[196:199], v[2:5]
	v_mfma_f32_16x16x32_bf16 v[30:33], v[160:163], v[176:179], v[30:33]
	v_mfma_f32_16x16x32_bf16 v[26:29], v[168:171], v[176:179], v[26:29]
	v_mfma_f32_16x16x32_bf16 v[22:25], v[160:163], v[184:187], v[22:25]
	v_mfma_f32_16x16x32_bf16 v[18:21], v[168:171], v[184:187], v[18:21]
	v_mfma_f32_16x16x32_bf16 v[14:17], v[160:163], v[192:195], v[14:17]
	v_mfma_f32_16x16x32_bf16 v[10:13], v[168:171], v[192:195], v[10:13]
	v_mfma_f32_16x16x32_bf16 v[6:9], v[160:163], v[200:203], v[6:9]
	v_mfma_f32_16x16x32_bf16 v[2:5], v[168:171], v[200:203], v[2:5]
	v_mfma_f32_16x16x32_bf16 v[58:61], v[204:207], v[172:175], v[58:61]
	v_mfma_f32_16x16x32_bf16 v[62:65], v[212:215], v[172:175], v[62:65]
	v_mfma_f32_16x16x32_bf16 v[66:69], v[204:207], v[180:183], v[66:69]
	v_mfma_f32_16x16x32_bf16 v[74:77], v[212:215], v[180:183], v[74:77]
	v_mfma_f32_16x16x32_bf16 v[78:81], v[204:207], v[188:191], v[78:81]
	v_mfma_f32_16x16x32_bf16 v[82:85], v[212:215], v[188:191], v[82:85]
	v_mfma_f32_16x16x32_bf16 v[90:93], v[204:207], v[196:199], v[90:93]
	v_mfma_f32_16x16x32_bf16 v[94:97], v[212:215], v[196:199], v[94:97]
	v_mfma_f32_16x16x32_bf16 v[58:61], v[208:211], v[176:179], v[58:61]
	v_mfma_f32_16x16x32_bf16 v[62:65], v[216:219], v[176:179], v[62:65]
	v_mfma_f32_16x16x32_bf16 v[66:69], v[208:211], v[184:187], v[66:69]
	v_mfma_f32_16x16x32_bf16 v[74:77], v[216:219], v[184:187], v[74:77]
	v_mfma_f32_16x16x32_bf16 v[78:81], v[208:211], v[192:195], v[78:81]
	v_mfma_f32_16x16x32_bf16 v[82:85], v[216:219], v[192:195], v[82:85]
	v_mfma_f32_16x16x32_bf16 v[90:93], v[208:211], v[200:203], v[90:93]
	v_mfma_f32_16x16x32_bf16 v[94:97], v[216:219], v[200:203], v[94:97]
	s_barrier
; #define LDA(dst, b, h)                                                                                     \
;   _Pragma("unroll") for (int m = 0; m < 4; ++m) _Pragma("unroll") for (int k = 0; k < 2; ++k) dst[m][k] = \
;       *reinterpret_cast<const bf16x8*>(shmc + aL + (((b) * 2 + (h)) * 16384 + (m * 2 + k) * 1024))
; #define LDB(dst, b, h)                                                                                     \
;   _Pragma("unroll") for (int n = 0; n < 2; ++n) _Pragma("unroll") for (int k = 0; k < 2; ++k) dst[n][k] = \
;       *reinterpret_cast<const bf16x8*>(shmc + bL + (((b) * 2 + (h)) * 16384 + (n * 2 + k) * 1024))
; #define OPAQ asm volatile("" : "+v"(aL), "+v"(bL))
; #define WAIT_V(n) asm volatile("s_waitcnt vmcnt(" #n ")" ::: "memory")
; #define WAIT_L(n) asm volatile("s_waitcnt lgkmcnt(" #n ")" ::: "memory")
; #define BAR __builtin_amdgcn_s_barrier()
; template <int EPI>
; __device__ __forceinline__ void phase_gemm(const Params& p, const GemmDesc& d, char* shmc) {
;     ...
;     {
;       OPAQ;
;       LDB(B0, 0, 0); LDA(At, 0, 0); STAGE_A(SA(1, 1), 1, nt - 1);
;       BAR; WAIT_L(0); MMA(0, 0, At, B0); BAR;
;       LDB(B1, 0, 1); BAR; WAIT_L(0); MMA(0, 1, At, B1); BAR;
;       LDA(At, 0, 1); WAIT_V(4); BAR; WAIT_L(0); MMA(1, 0, At, B0); MMA(1, 1, At, B1); BAR;
;     }
	s_cbranch_scc0 .LBB0_1010
	s_setprio 0
	s_add_u32 s56, s56, 0x80f80
	s_addc_u32 s57, s57, 0
	v_add_u32_e32 v130, 0, v153
	v_add_u32_e32 v141, 0, v152
	s_mov_b32 m0, s80
	ds_read_b128 v[144:147], v130
	ds_read_b128 v[148:151], v130 offset:1024
	ds_read_b128 v[156:159], v130 offset:2048
	ds_read_b128 v[160:163], v130 offset:3072
	ds_read_b128 v[164:167], v141
	ds_read_b128 v[168:171], v141 offset:1024
	ds_read_b128 v[172:175], v141 offset:2048
	ds_read_b128 v[176:179], v141 offset:3072
	ds_read_b128 v[180:183], v141 offset:4096
	ds_read_b128 v[184:187], v141 offset:5120
	ds_read_b128 v[188:191], v141 offset:6144
	ds_read_b128 v[192:195], v141 offset:7168
	global_load_lds_dwordx4 v140, s[56:57]
	s_mov_b32 m0, s81
	s_nop 0
	global_load_lds_dwordx4 v142, s[56:57]
	s_waitcnt vmcnt(8)
	s_barrier
	s_waitcnt lgkmcnt(0)
	s_setprio 1
	s_waitcnt lgkmcnt(0)
	v_mfma_f32_16x16x32_bf16 v[126:129], v[144:147], v[164:167], v[126:129]
	v_mfma_f32_16x16x32_bf16 v[122:125], v[156:159], v[164:167], v[122:125]
	v_mfma_f32_16x16x32_bf16 v[114:117], v[156:159], v[172:175], v[114:117]
	v_mfma_f32_16x16x32_bf16 v[110:113], v[144:147], v[180:183], v[110:113]
	v_mfma_f32_16x16x32_bf16 v[102:105], v[144:147], v[188:191], v[102:105]
	v_mfma_f32_16x16x32_bf16 v[126:129], v[148:151], v[168:171], v[126:129]
	v_mfma_f32_16x16x32_bf16 v[122:125], v[160:163], v[168:171], v[122:125]
	v_mfma_f32_16x16x32_bf16 v[118:121], v[144:147], v[172:175], v[118:121]
	v_mfma_f32_16x16x32_bf16 v[114:117], v[160:163], v[176:179], v[114:117]
	v_mfma_f32_16x16x32_bf16 v[110:113], v[148:151], v[184:187], v[110:113]
	v_mfma_f32_16x16x32_bf16 v[106:109], v[156:159], v[180:183], v[106:109]
	v_mfma_f32_16x16x32_bf16 v[102:105], v[148:151], v[192:195], v[102:105]
	v_mfma_f32_16x16x32_bf16 v[98:101], v[156:159], v[188:191], v[98:101]
	v_mfma_f32_16x16x32_bf16 v[196:199], v[148:151], v[176:179], v[118:121]
	v_mfma_f32_16x16x32_bf16 v[200:203], v[160:163], v[184:187], v[106:109]
	v_mfma_f32_16x16x32_bf16 v[204:207], v[160:163], v[192:195], v[98:101]
	s_setprio 0
	s_barrier
	s_nop 2
	ds_read_b128 v[98:101], v130 offset:16384
	ds_read_b128 v[106:109], v130 offset:17408
	ds_read_b128 v[118:121], v130 offset:18432
	ds_read_b128 v[208:211], v130 offset:19456
	s_barrier
	s_waitcnt lgkmcnt(0)
	s_setprio 1
	s_waitcnt lgkmcnt(0)
	v_mfma_f32_16x16x32_bf16 v[86:89], v[98:101], v[164:167], v[86:89]
	v_mfma_f32_16x16x32_bf16 v[70:73], v[118:121], v[164:167], v[70:73]
	v_mfma_f32_16x16x32_bf16 v[54:57], v[98:101], v[172:175], v[54:57]
	v_mfma_f32_16x16x32_bf16 v[50:53], v[118:121], v[172:175], v[50:53]
	v_mfma_f32_16x16x32_bf16 v[46:49], v[98:101], v[180:183], v[46:49]
	v_mfma_f32_16x16x32_bf16 v[42:45], v[118:121], v[180:183], v[42:45]
	v_mfma_f32_16x16x32_bf16 v[38:41], v[98:101], v[188:191], v[38:41]
	v_mfma_f32_16x16x32_bf16 v[34:37], v[118:121], v[188:191], v[34:37]
	v_mfma_f32_16x16x32_bf16 v[86:89], v[106:109], v[168:171], v[86:89]
	v_mfma_f32_16x16x32_bf16 v[70:73], v[208:211], v[168:171], v[70:73]
	v_mfma_f32_16x16x32_bf16 v[54:57], v[106:109], v[176:179], v[54:57]
	v_mfma_f32_16x16x32_bf16 v[50:53], v[208:211], v[176:179], v[50:53]
	v_mfma_f32_16x16x32_bf16 v[46:49], v[106:109], v[184:187], v[46:49]
	v_mfma_f32_16x16x32_bf16 v[42:45], v[208:211], v[184:187], v[42:45]
	v_mfma_f32_16x16x32_bf16 v[38:41], v[106:109], v[192:195], v[38:41]
	v_mfma_f32_16x16x32_bf16 v[34:37], v[208:211], v[192:195], v[34:37]
	s_setprio 0
	s_barrier
	ds_read_b128 v[164:167], v141 offset:16384
	ds_read_b128 v[168:171], v141 offset:17408
	ds_read_b128 v[172:175], v141 offset:18432
	ds_read_b128 v[176:179], v141 offset:19456
	ds_read_b128 v[180:183], v141 offset:20480
	ds_read_b128 v[184:187], v141 offset:21504
	ds_read_b128 v[188:191], v141 offset:22528
	ds_read_b128 v[192:195], v141 offset:23552
	s_waitcnt vmcnt(4)
	s_barrier
	s_waitcnt lgkmcnt(0)
	s_setprio 1
	s_waitcnt lgkmcnt(0)
	v_mfma_f32_16x16x32_bf16 v[30:33], v[144:147], v[164:167], v[30:33]
	v_mfma_f32_16x16x32_bf16 v[26:29], v[156:159], v[164:167], v[26:29]
	v_mfma_f32_16x16x32_bf16 v[22:25], v[144:147], v[172:175], v[22:25]
	v_mfma_f32_16x16x32_bf16 v[18:21], v[156:159], v[172:175], v[18:21]
	v_mfma_f32_16x16x32_bf16 v[14:17], v[144:147], v[180:183], v[14:17]
	v_mfma_f32_16x16x32_bf16 v[10:13], v[156:159], v[180:183], v[10:13]
	v_mfma_f32_16x16x32_bf16 v[6:9], v[144:147], v[188:191], v[6:9]
	v_mfma_f32_16x16x32_bf16 v[2:5], v[156:159], v[188:191], v[2:5]
	v_mfma_f32_16x16x32_bf16 v[30:33], v[148:151], v[168:171], v[30:33]
	v_mfma_f32_16x16x32_bf16 v[26:29], v[160:163], v[168:171], v[26:29]
	v_mfma_f32_16x16x32_bf16 v[22:25], v[148:151], v[176:179], v[22:25]
	v_mfma_f32_16x16x32_bf16 v[18:21], v[160:163], v[176:179], v[18:21]
	v_mfma_f32_16x16x32_bf16 v[14:17], v[148:151], v[184:187], v[14:17]
	v_mfma_f32_16x16x32_bf16 v[10:13], v[160:163], v[184:187], v[10:13]
	v_mfma_f32_16x16x32_bf16 v[6:9], v[148:151], v[192:195], v[6:9]
	v_mfma_f32_16x16x32_bf16 v[2:5], v[160:163], v[192:195], v[2:5]
	s_setprio 0
	s_setprio 1
	v_mfma_f32_16x16x32_bf16 v[62:65], v[118:121], v[164:167], v[62:65]
	v_mfma_f32_16x16x32_bf16 v[144:147], v[208:211], v[168:171], v[62:65]
	v_mfma_f32_16x16x32_bf16 v[62:65], v[98:101], v[172:175], v[66:69]
	v_mfma_f32_16x16x32_bf16 v[148:151], v[106:109], v[176:179], v[62:65]
	v_mfma_f32_16x16x32_bf16 v[62:65], v[118:121], v[172:175], v[74:77]
	v_mfma_f32_16x16x32_bf16 v[156:159], v[208:211], v[176:179], v[62:65]
	v_mfma_f32_16x16x32_bf16 v[62:65], v[98:101], v[180:183], v[78:81]
	v_mfma_f32_16x16x32_bf16 v[160:163], v[106:109], v[184:187], v[62:65]
	v_mfma_f32_16x16x32_bf16 v[62:65], v[118:121], v[180:183], v[82:85]
	v_mfma_f32_16x16x32_bf16 v[58:61], v[98:101], v[164:167], v[58:61]
	v_mfma_f32_16x16x32_bf16 v[164:167], v[208:211], v[184:187], v[62:65]
	v_mfma_f32_16x16x32_bf16 v[62:65], v[98:101], v[188:191], v[90:93]
	v_mfma_f32_16x16x32_bf16 v[58:61], v[106:109], v[168:171], v[58:61]
	v_mfma_f32_16x16x32_bf16 v[168:171], v[106:109], v[192:195], v[62:65]
	v_mfma_f32_16x16x32_bf16 v[62:65], v[118:121], v[188:191], v[94:97]
	v_mfma_f32_16x16x32_bf16 v[172:175], v[208:211], v[192:195], v[62:65]
	s_setprio 0
	s_barrier
; #define LDA(dst, b, h)                                                                                     \
;   _Pragma("unroll") for (int m = 0; m < 4; ++m) _Pragma("unroll") for (int k = 0; k < 2; ++k) dst[m][k] = \
;       *reinterpret_cast<const bf16x8*>(shmc + aL + (((b) * 2 + (h)) * 16384 + (m * 2 + k) * 1024))
; #define LDB(dst, b, h)                                                                                     \
;   _Pragma("unroll") for (int n = 0; n < 2; ++n) _Pragma("unroll") for (int k = 0; k < 2; ++k) dst[n][k] = \
;       *reinterpret_cast<const bf16x8*>(shmc + bL + (((b) * 2 + (h)) * 16384 + (n * 2 + k) * 1024))
; #define WAIT_V(n) asm volatile("s_waitcnt vmcnt(" #n ")" ::: "memory")
; #define WAIT_L(n) asm volatile("s_waitcnt lgkmcnt(" #n ")" ::: "memory")
; #define BAR __builtin_amdgcn_s_barrier()
; template <int EPI>
; __device__ __forceinline__ void phase_gemm(const Params& p, const GemmDesc& d, char* shmc) {
;     ...
;     {
;       LDB(B0, 1, 0); LDA(At, 1, 0); WAIT_V(2); BAR; WAIT_L(0); MMA(0, 0, At, B0); BAR;
;       LDB(B1, 1, 1); WAIT_V(0); BAR; WAIT_L(0); MMA(0, 1, At, B1); BAR;
;       LDA(At, 1, 1); BAR; WAIT_L(0); MMA(1, 0, At, B0); MMA(1, 1, At, B1); BAR;
;     }
;     if (wr == 0) BAR;
	ds_read_b128 v[176:179], v130 offset:32768
	ds_read_b128 v[180:183], v130 offset:33792
	ds_read_b128 v[184:187], v130 offset:34816
	ds_read_b128 v[188:191], v130 offset:35840
	s_nop 0
	ds_read_b128 v[62:65], v141 offset:32768
	ds_read_b128 v[78:81], v141 offset:33792
	ds_read_b128 v[94:97], v141 offset:34816
	ds_read_b128 v[192:195], v141 offset:35840
	ds_read_b128 v[208:211], v141 offset:36864
	ds_read_b128 v[212:215], v141 offset:37888
	ds_read_b128 v[216:219], v141 offset:38912
	ds_read_b128 v[220:223], v141 offset:39936
	s_waitcnt vmcnt(2)
	s_barrier
	s_waitcnt lgkmcnt(0)
	s_setprio 1
	s_waitcnt lgkmcnt(0)
	v_mfma_f32_16x16x32_bf16 v[66:69], v[176:179], v[62:65], v[126:129]
	v_mfma_f32_16x16x32_bf16 v[126:129], v[180:183], v[78:81], v[66:69]
	v_mfma_f32_16x16x32_bf16 v[66:69], v[184:187], v[62:65], v[122:125]
	v_mfma_f32_16x16x32_bf16 v[118:121], v[188:191], v[78:81], v[66:69]
	v_mfma_f32_16x16x32_bf16 v[66:69], v[176:179], v[94:97], v[196:199]
	v_mfma_f32_16x16x32_bf16 v[106:109], v[180:183], v[192:195], v[66:69]
	v_mfma_f32_16x16x32_bf16 v[66:69], v[184:187], v[94:97], v[114:117]
	v_mfma_f32_16x16x32_bf16 v[98:101], v[188:191], v[192:195], v[66:69]
	v_mfma_f32_16x16x32_bf16 v[66:69], v[176:179], v[208:211], v[110:113]
	v_mfma_f32_16x16x32_bf16 v[90:93], v[180:183], v[212:215], v[66:69]
	v_mfma_f32_16x16x32_bf16 v[66:69], v[184:187], v[208:211], v[200:203]
	v_mfma_f32_16x16x32_bf16 v[82:85], v[188:191], v[212:215], v[66:69]
	v_mfma_f32_16x16x32_bf16 v[66:69], v[176:179], v[216:219], v[102:105]
	v_mfma_f32_16x16x32_bf16 v[74:77], v[180:183], v[220:223], v[66:69]
	v_mfma_f32_16x16x32_bf16 v[66:69], v[184:187], v[216:219], v[204:207]
	v_mfma_f32_16x16x32_bf16 v[66:69], v[188:191], v[220:223], v[66:69]
	s_setprio 0
	s_barrier
	ds_read_b128 v[196:199], v130 offset:49152
	ds_read_b128 v[200:203], v130 offset:50176
	ds_read_b128 v[204:207], v130 offset:51200
	ds_read_b128 v[224:227], v130 offset:52224
	s_waitcnt vmcnt(0)
	s_barrier
	s_waitcnt lgkmcnt(0)
	s_setprio 1
	s_waitcnt lgkmcnt(0)
	v_mfma_f32_16x16x32_bf16 v[86:89], v[196:199], v[62:65], v[86:89]
	v_mfma_f32_16x16x32_bf16 v[62:65], v[204:207], v[62:65], v[70:73]
	v_mfma_f32_16x16x32_bf16 v[54:57], v[196:199], v[94:97], v[54:57]
	v_mfma_f32_16x16x32_bf16 v[50:53], v[204:207], v[94:97], v[50:53]
	v_mfma_f32_16x16x32_bf16 v[46:49], v[196:199], v[208:211], v[46:49]
	v_mfma_f32_16x16x32_bf16 v[42:45], v[204:207], v[208:211], v[42:45]
	v_mfma_f32_16x16x32_bf16 v[38:41], v[196:199], v[216:219], v[38:41]
	v_mfma_f32_16x16x32_bf16 v[34:37], v[204:207], v[216:219], v[34:37]
	v_mfma_f32_16x16x32_bf16 v[122:125], v[200:203], v[78:81], v[86:89]
	v_mfma_f32_16x16x32_bf16 v[114:117], v[224:227], v[78:81], v[62:65]
	v_mfma_f32_16x16x32_bf16 v[110:113], v[200:203], v[192:195], v[54:57]
	v_mfma_f32_16x16x32_bf16 v[102:105], v[224:227], v[192:195], v[50:53]
	v_mfma_f32_16x16x32_bf16 v[94:97], v[200:203], v[212:215], v[46:49]
	v_mfma_f32_16x16x32_bf16 v[86:89], v[224:227], v[212:215], v[42:45]
	v_mfma_f32_16x16x32_bf16 v[78:81], v[200:203], v[220:223], v[38:41]
	v_mfma_f32_16x16x32_bf16 v[70:73], v[224:227], v[220:223], v[34:37]
	s_setprio 0
	s_barrier
	s_nop 0
	ds_read_b128 v[34:37], v141 offset:49152
	ds_read_b128 v[42:45], v141 offset:50176
	ds_read_b128 v[192:195], v141 offset:51200
	ds_read_b128 v[208:211], v141 offset:52224
	ds_read_b128 v[212:215], v141 offset:53248
	ds_read_b128 v[216:219], v141 offset:54272
	ds_read_b128 v[220:223], v141 offset:55296
	ds_read_b128 v[228:231], v141 offset:56320
	s_barrier
	s_waitcnt lgkmcnt(0)
	s_setprio 1
	s_waitcnt lgkmcnt(0)
	v_mfma_f32_16x16x32_bf16 v[30:33], v[176:179], v[34:37], v[30:33]
	v_mfma_f32_16x16x32_bf16 v[26:29], v[184:187], v[34:37], v[26:29]
	v_mfma_f32_16x16x32_bf16 v[22:25], v[176:179], v[192:195], v[22:25]
	v_mfma_f32_16x16x32_bf16 v[18:21], v[184:187], v[192:195], v[18:21]
	v_mfma_f32_16x16x32_bf16 v[14:17], v[176:179], v[212:215], v[14:17]
	v_mfma_f32_16x16x32_bf16 v[10:13], v[184:187], v[212:215], v[10:13]
	v_mfma_f32_16x16x32_bf16 v[6:9], v[176:179], v[220:223], v[6:9]
	v_mfma_f32_16x16x32_bf16 v[2:5], v[184:187], v[220:223], v[2:5]
	v_mfma_f32_16x16x32_bf16 v[62:65], v[180:183], v[42:45], v[30:33]
	v_mfma_f32_16x16x32_bf16 v[54:57], v[188:191], v[42:45], v[26:29]
	v_mfma_f32_16x16x32_bf16 v[46:49], v[180:183], v[208:211], v[22:25]
	v_mfma_f32_16x16x32_bf16 v[38:41], v[188:191], v[208:211], v[18:21]
	v_mfma_f32_16x16x32_bf16 v[30:33], v[180:183], v[216:219], v[14:17]
	v_mfma_f32_16x16x32_bf16 v[22:25], v[188:191], v[216:219], v[10:13]
	v_mfma_f32_16x16x32_bf16 v[14:17], v[180:183], v[228:231], v[6:9]
	v_mfma_f32_16x16x32_bf16 v[6:9], v[188:191], v[228:231], v[2:5]
	s_setprio 0
	s_setprio 1
	v_mfma_f32_16x16x32_bf16 v[2:5], v[196:199], v[34:37], v[58:61]
	v_mfma_f32_16x16x32_bf16 v[58:61], v[200:203], v[42:45], v[2:5]
	v_mfma_f32_16x16x32_bf16 v[2:5], v[204:207], v[34:37], v[144:147]
	v_mfma_f32_16x16x32_bf16 v[50:53], v[224:227], v[42:45], v[2:5]
	v_mfma_f32_16x16x32_bf16 v[2:5], v[196:199], v[192:195], v[148:151]
	v_mfma_f32_16x16x32_bf16 v[42:45], v[200:203], v[208:211], v[2:5]
	v_mfma_f32_16x16x32_bf16 v[2:5], v[204:207], v[192:195], v[156:159]
	v_mfma_f32_16x16x32_bf16 v[34:37], v[224:227], v[208:211], v[2:5]
	v_mfma_f32_16x16x32_bf16 v[2:5], v[196:199], v[212:215], v[160:163]
	v_mfma_f32_16x16x32_bf16 v[26:29], v[200:203], v[216:219], v[2:5]
	v_mfma_f32_16x16x32_bf16 v[2:5], v[204:207], v[212:215], v[164:167]
	v_mfma_f32_16x16x32_bf16 v[18:21], v[224:227], v[216:219], v[2:5]
	v_mfma_f32_16x16x32_bf16 v[2:5], v[196:199], v[220:223], v[168:171]
	v_mfma_f32_16x16x32_bf16 v[10:13], v[200:203], v[228:231], v[2:5]
	v_mfma_f32_16x16x32_bf16 v[2:5], v[204:207], v[220:223], v[172:175]
	v_mfma_f32_16x16x32_bf16 v[2:5], v[224:227], v[228:231], v[2:5]
	s_setprio 0
	s_barrier
	s_and_saveexec_b64 s[56:57], s[4:5]
	s_cbranch_execz .LBB0_1013
	s_barrier

; #define LDA(dst, b, h)                                                                                     \
;   _Pragma("unroll") for (int m = 0; m < 4; ++m) _Pragma("unroll") for (int k = 0; k < 2; ++k) dst[m][k] = \
;       *reinterpret_cast<const bf16x8*>(shmc + aL + (((b) * 2 + (h)) * 16384 + (m * 2 + k) * 1024))
; #define LDB(dst, b, h)                                                                                     \
;   _Pragma("unroll") for (int n = 0; n < 2; ++n) _Pragma("unroll") for (int k = 0; k < 2; ++k) dst[n][k] = \
;       *reinterpret_cast<const bf16x8*>(shmc + bL + (((b) * 2 + (h)) * 16384 + (n * 2 + k) * 1024))
; #define OPAQ asm volatile("" : "+v"(aL), "+v"(bL))
; #define WAIT_V(n) asm volatile("s_waitcnt vmcnt(" #n ")" ::: "memory")
; #define WAIT_L(n) asm volatile("s_waitcnt lgkmcnt(" #n ")" ::: "memory")
; #define BAR __builtin_amdgcn_s_barrier()
; #define SCHED __builtin_amdgcn_sched_barrier(0)
; template <int EPI>
; __device__ __forceinline__ void phase_gemm(const Params& p, const GemmDesc& d, char* shmc) {
;     ...
;     for (int t = 0; t < nt - 2; t += 2) {
;       OPAQ;
;       LDB(B0, 0, 0); SCHED; LDA(At, 0, 0); STAGE_A(SA(1, 1), 1, t + 1);
;       WAIT_L(8); BAR; WAIT_L(0); MMA(0, 0, At, B0); BAR; SCHED;
;       LDB(B1, 0, 1); STAGE_B(SB(0, 0), 0, t + 2);
;       BAR; WAIT_L(0); MMA(0, 1, At, B1); BAR;
;       LDA(At, 0, 1); STAGE_A(SA(0, 0), 0, t + 2);
;       BAR; WAIT_L(0); MMA(1, 0, At, B0); BAR; SCHED;
;       STAGE_B(SB(0, 1), 1, t + 2);
;       WAIT_V(6); BAR; MMA(1, 1, At, B1); BAR;
.LBB0_1153:
	s_nop 0
	v_add_u32_e32 v162, 0, v205
	v_add_u32_e32 v175, 0, v204
	s_setprio 0
	s_add_i32 s59, s64, 0xc000
	s_mov_b32 m0, s59
	s_nop 0
	global_load_lds_dwordx4 v202, s[98:99]
	s_add_i32 s68, s64, 0xe000
	s_mov_b32 m0, s68
	s_nop 0
	global_load_lds_dwordx4 v203, s[98:99]
	ds_read_b128 v[138:141], v162
	ds_read_b128 v[142:145], v162 offset:1024
	ds_read_b128 v[146:149], v162 offset:2048
	ds_read_b128 v[150:153], v162 offset:3072
	ds_read_b128 v[208:211], v162 offset:16384
	ds_read_b128 v[212:215], v162 offset:17408
	ds_read_b128 v[216:219], v162 offset:18432
	ds_read_b128 v[220:223], v162 offset:19456
	ds_read_b128 v[154:157], v175
	ds_read_b128 v[158:161], v175 offset:1024
	ds_read_b128 v[178:181], v175 offset:2048
	ds_read_b128 v[182:185], v175 offset:3072
	ds_read_b128 v[186:189], v175 offset:4096
	ds_read_b128 v[190:193], v175 offset:5120
	ds_read_b128 v[194:197], v175 offset:6144
	ds_read_b128 v[198:201], v175 offset:7168
	s_waitcnt vmcnt(8)
	s_waitcnt lgkmcnt(0)
	s_setprio 1
	s_barrier
	v_mfma_f32_16x16x32_bf16 v[2:5], v[154:157], v[138:141], v[2:5]
	v_mfma_f32_16x16x32_bf16 v[6:9], v[154:157], v[146:149], v[6:9]
	v_mfma_f32_16x16x32_bf16 v[10:13], v[178:181], v[138:141], v[10:13]
	v_mfma_f32_16x16x32_bf16 v[18:21], v[178:181], v[146:149], v[18:21]
	v_mfma_f32_16x16x32_bf16 v[30:33], v[186:189], v[138:141], v[30:33]
	v_mfma_f32_16x16x32_bf16 v[42:45], v[186:189], v[146:149], v[42:45]
	v_mfma_f32_16x16x32_bf16 v[54:57], v[194:197], v[138:141], v[54:57]
	v_mfma_f32_16x16x32_bf16 v[66:69], v[194:197], v[146:149], v[66:69]
	v_mfma_f32_16x16x32_bf16 v[2:5], v[158:161], v[142:145], v[2:5]
	v_mfma_f32_16x16x32_bf16 v[6:9], v[158:161], v[150:153], v[6:9]
	v_mfma_f32_16x16x32_bf16 v[10:13], v[182:185], v[142:145], v[10:13]
	v_mfma_f32_16x16x32_bf16 v[18:21], v[182:185], v[150:153], v[18:21]
	v_mfma_f32_16x16x32_bf16 v[30:33], v[190:193], v[142:145], v[30:33]
	v_mfma_f32_16x16x32_bf16 v[42:45], v[190:193], v[150:153], v[42:45]
	v_mfma_f32_16x16x32_bf16 v[54:57], v[198:201], v[142:145], v[54:57]
	v_mfma_f32_16x16x32_bf16 v[66:69], v[198:201], v[150:153], v[66:69]
	v_mfma_f32_16x16x32_bf16 v[14:17], v[154:157], v[208:211], v[14:17]
	v_mfma_f32_16x16x32_bf16 v[22:25], v[154:157], v[216:219], v[22:25]
	v_mfma_f32_16x16x32_bf16 v[34:37], v[178:181], v[208:211], v[34:37]
	v_mfma_f32_16x16x32_bf16 v[46:49], v[178:181], v[216:219], v[46:49]
	v_mfma_f32_16x16x32_bf16 v[58:61], v[186:189], v[208:211], v[58:61]
	v_mfma_f32_16x16x32_bf16 v[70:73], v[186:189], v[216:219], v[70:73]
	v_mfma_f32_16x16x32_bf16 v[78:81], v[194:197], v[208:211], v[78:81]
	v_mfma_f32_16x16x32_bf16 v[86:89], v[194:197], v[216:219], v[86:89]
	v_mfma_f32_16x16x32_bf16 v[14:17], v[158:161], v[212:215], v[14:17]
	v_mfma_f32_16x16x32_bf16 v[22:25], v[158:161], v[220:223], v[22:25]
	v_mfma_f32_16x16x32_bf16 v[34:37], v[182:185], v[212:215], v[34:37]
	v_mfma_f32_16x16x32_bf16 v[46:49], v[182:185], v[220:223], v[46:49]
	v_mfma_f32_16x16x32_bf16 v[58:61], v[190:193], v[212:215], v[58:61]
	v_mfma_f32_16x16x32_bf16 v[70:73], v[190:193], v[220:223], v[70:73]
	v_mfma_f32_16x16x32_bf16 v[78:81], v[198:201], v[212:215], v[78:81]
	v_mfma_f32_16x16x32_bf16 v[86:89], v[198:201], v[220:223], v[86:89]
	s_barrier
	s_setprio 0
	s_mov_b32 m0, s65
	s_nop 0
	global_load_lds_dwordx4 v224, s[100:101]
	s_mov_b32 m0, s66
	s_nop 0
	global_load_lds_dwordx4 v225, s[100:101]
	s_mov_b32 m0, s64
	s_nop 0
	global_load_lds_dwordx4 v226, s[98:99]
	s_mov_b32 m0, s67
	s_nop 0
	global_load_lds_dwordx4 v227, s[98:99]
	s_mov_b32 m0, s71
	s_nop 0
	global_load_lds_dwordx4 v228, s[100:101]
	s_mov_b32 m0, s76
	s_nop 0
	global_load_lds_dwordx4 v229, s[100:101]
	ds_read_b128 v[154:157], v175 offset:16384
	ds_read_b128 v[158:161], v175 offset:17408
	ds_read_b128 v[178:181], v175 offset:18432
	ds_read_b128 v[182:185], v175 offset:19456
	ds_read_b128 v[186:189], v175 offset:20480
	ds_read_b128 v[190:193], v175 offset:21504
	ds_read_b128 v[194:197], v175 offset:22528
	ds_read_b128 v[198:201], v175 offset:23552
	s_waitcnt vmcnt(8)
	s_waitcnt lgkmcnt(0)
	s_setprio 1
	s_barrier
	v_mfma_f32_16x16x32_bf16 v[26:29], v[154:157], v[138:141], v[26:29]
	v_mfma_f32_16x16x32_bf16 v[38:41], v[154:157], v[146:149], v[38:41]
	v_mfma_f32_16x16x32_bf16 v[50:53], v[178:181], v[138:141], v[50:53]
	v_mfma_f32_16x16x32_bf16 v[62:65], v[178:181], v[146:149], v[62:65]
	v_mfma_f32_16x16x32_bf16 v[74:77], v[186:189], v[138:141], v[74:77]
	v_mfma_f32_16x16x32_bf16 v[82:85], v[186:189], v[146:149], v[82:85]
	v_mfma_f32_16x16x32_bf16 v[90:93], v[194:197], v[138:141], v[90:93]
	v_mfma_f32_16x16x32_bf16 v[94:97], v[194:197], v[146:149], v[94:97]
	v_mfma_f32_16x16x32_bf16 v[26:29], v[158:161], v[142:145], v[26:29]
	v_mfma_f32_16x16x32_bf16 v[38:41], v[158:161], v[150:153], v[38:41]
	v_mfma_f32_16x16x32_bf16 v[50:53], v[182:185], v[142:145], v[50:53]
	v_mfma_f32_16x16x32_bf16 v[62:65], v[182:185], v[150:153], v[62:65]
	v_mfma_f32_16x16x32_bf16 v[74:77], v[190:193], v[142:145], v[74:77]
	v_mfma_f32_16x16x32_bf16 v[82:85], v[190:193], v[150:153], v[82:85]
	v_mfma_f32_16x16x32_bf16 v[90:93], v[198:201], v[142:145], v[90:93]
	v_mfma_f32_16x16x32_bf16 v[94:97], v[198:201], v[150:153], v[94:97]
	v_mfma_f32_16x16x32_bf16 v[98:101], v[154:157], v[208:211], v[98:101]
	v_mfma_f32_16x16x32_bf16 v[102:105], v[154:157], v[216:219], v[102:105]
	v_mfma_f32_16x16x32_bf16 v[106:109], v[178:181], v[208:211], v[106:109]
	v_mfma_f32_16x16x32_bf16 v[110:113], v[178:181], v[216:219], v[110:113]
	v_mfma_f32_16x16x32_bf16 v[114:117], v[186:189], v[208:211], v[114:117]
	v_mfma_f32_16x16x32_bf16 v[118:121], v[186:189], v[216:219], v[118:121]
	v_mfma_f32_16x16x32_bf16 v[122:125], v[194:197], v[208:211], v[122:125]
	v_mfma_f32_16x16x32_bf16 v[126:129], v[194:197], v[216:219], v[126:129]
	v_mfma_f32_16x16x32_bf16 v[98:101], v[158:161], v[212:215], v[98:101]
	v_mfma_f32_16x16x32_bf16 v[102:105], v[158:161], v[220:223], v[102:105]
	v_mfma_f32_16x16x32_bf16 v[106:109], v[182:185], v[212:215], v[106:109]
	v_mfma_f32_16x16x32_bf16 v[110:113], v[182:185], v[220:223], v[110:113]
	v_mfma_f32_16x16x32_bf16 v[114:117], v[190:193], v[212:215], v[114:117]
	v_mfma_f32_16x16x32_bf16 v[118:121], v[190:193], v[220:223], v[118:121]
	v_mfma_f32_16x16x32_bf16 v[122:125], v[198:201], v[212:215], v[122:125]
	v_mfma_f32_16x16x32_bf16 v[126:129], v[198:201], v[220:223], v[126:129]
	s_barrier
; #define LDA(dst, b, h)                                                                                     \
;   _Pragma("unroll") for (int m = 0; m < 4; ++m) _Pragma("unroll") for (int k = 0; k < 2; ++k) dst[m][k] = \
;       *reinterpret_cast<const bf16x8*>(shmc + aL + (((b) * 2 + (h)) * 16384 + (m * 2 + k) * 1024))
; #define LDB(dst, b, h)                                                                                     \
;   _Pragma("unroll") for (int n = 0; n < 2; ++n) _Pragma("unroll") for (int k = 0; k < 2; ++k) dst[n][k] = \
;       *reinterpret_cast<const bf16x8*>(shmc + bL + (((b) * 2 + (h)) * 16384 + (n * 2 + k) * 1024))
; #define WAIT_V(n) asm volatile("s_waitcnt vmcnt(" #n ")" ::: "memory")
; #define WAIT_L(n) asm volatile("s_waitcnt lgkmcnt(" #n ")" ::: "memory")
; #define BAR __builtin_amdgcn_s_barrier()
; #define SCHED __builtin_amdgcn_sched_barrier(0)
; template <int EPI>
; __device__ __forceinline__ void phase_gemm(const Params& p, const GemmDesc& d, char* shmc) {
;     ...
;       LDB(B0, 1, 0); SCHED; LDA(At, 1, 0); STAGE_A(SA(0, 1), 1, t + 2);
;       WAIT_L(8); BAR; WAIT_L(0); MMA(0, 0, At, B0); BAR; SCHED;
;       LDB(B1, 1, 1); STAGE_B(SB(1, 0), 0, t + 3);
;       BAR; WAIT_L(0); MMA(0, 1, At, B1); BAR;
;       LDA(At, 1, 1); STAGE_A(SA(1, 0), 0, t + 3);
;       BAR; WAIT_L(0); MMA(1, 0, At, B0); BAR; SCHED;
;       STAGE_B(SB(1, 1), 1, t + 3);
;       WAIT_V(6); BAR; MMA(1, 1, At, B1); BAR;
	s_setprio 0
	s_mov_b32 m0, s77
	s_nop 0
	global_load_lds_dwordx4 v230, s[98:99]
	s_mov_b32 m0, s78
	s_nop 0
	global_load_lds_dwordx4 v231, s[98:99]
	ds_read_b128 v[138:141], v162 offset:32768
	ds_read_b128 v[142:145], v162 offset:33792
	ds_read_b128 v[146:149], v162 offset:34816
	ds_read_b128 v[150:153], v162 offset:35840
	ds_read_b128 v[208:211], v162 offset:49152
	ds_read_b128 v[212:215], v162 offset:50176
	ds_read_b128 v[216:219], v162 offset:51200
	ds_read_b128 v[220:223], v162 offset:52224
	ds_read_b128 v[154:157], v175 offset:32768
	ds_read_b128 v[158:161], v175 offset:33792
	ds_read_b128 v[178:181], v175 offset:34816
	ds_read_b128 v[182:185], v175 offset:35840
	ds_read_b128 v[186:189], v175 offset:36864
	ds_read_b128 v[190:193], v175 offset:37888
	ds_read_b128 v[194:197], v175 offset:38912
	ds_read_b128 v[198:201], v175 offset:39936
	s_waitcnt vmcnt(8)
	s_waitcnt lgkmcnt(0)
	s_setprio 1
	s_barrier
	v_mfma_f32_16x16x32_bf16 v[2:5], v[154:157], v[138:141], v[2:5]
	v_mfma_f32_16x16x32_bf16 v[6:9], v[154:157], v[146:149], v[6:9]
	v_mfma_f32_16x16x32_bf16 v[10:13], v[178:181], v[138:141], v[10:13]
	v_mfma_f32_16x16x32_bf16 v[18:21], v[178:181], v[146:149], v[18:21]
	v_mfma_f32_16x16x32_bf16 v[30:33], v[186:189], v[138:141], v[30:33]
	v_mfma_f32_16x16x32_bf16 v[42:45], v[186:189], v[146:149], v[42:45]
	v_mfma_f32_16x16x32_bf16 v[54:57], v[194:197], v[138:141], v[54:57]
	v_mfma_f32_16x16x32_bf16 v[66:69], v[194:197], v[146:149], v[66:69]
	v_mfma_f32_16x16x32_bf16 v[2:5], v[158:161], v[142:145], v[2:5]
	v_mfma_f32_16x16x32_bf16 v[6:9], v[158:161], v[150:153], v[6:9]
	v_mfma_f32_16x16x32_bf16 v[10:13], v[182:185], v[142:145], v[10:13]
	v_mfma_f32_16x16x32_bf16 v[18:21], v[182:185], v[150:153], v[18:21]
	v_mfma_f32_16x16x32_bf16 v[30:33], v[190:193], v[142:145], v[30:33]
	v_mfma_f32_16x16x32_bf16 v[42:45], v[190:193], v[150:153], v[42:45]
	v_mfma_f32_16x16x32_bf16 v[54:57], v[198:201], v[142:145], v[54:57]
	v_mfma_f32_16x16x32_bf16 v[66:69], v[198:201], v[150:153], v[66:69]
	v_mfma_f32_16x16x32_bf16 v[14:17], v[154:157], v[208:211], v[14:17]
	v_mfma_f32_16x16x32_bf16 v[22:25], v[154:157], v[216:219], v[22:25]
	v_mfma_f32_16x16x32_bf16 v[34:37], v[178:181], v[208:211], v[34:37]
	v_mfma_f32_16x16x32_bf16 v[46:49], v[178:181], v[216:219], v[46:49]
	v_mfma_f32_16x16x32_bf16 v[58:61], v[186:189], v[208:211], v[58:61]
	v_mfma_f32_16x16x32_bf16 v[70:73], v[186:189], v[216:219], v[70:73]
	v_mfma_f32_16x16x32_bf16 v[78:81], v[194:197], v[208:211], v[78:81]
	v_mfma_f32_16x16x32_bf16 v[86:89], v[194:197], v[216:219], v[86:89]
	v_mfma_f32_16x16x32_bf16 v[14:17], v[158:161], v[212:215], v[14:17]
	v_mfma_f32_16x16x32_bf16 v[22:25], v[158:161], v[220:223], v[22:25]
	v_mfma_f32_16x16x32_bf16 v[34:37], v[182:185], v[212:215], v[34:37]
	v_mfma_f32_16x16x32_bf16 v[46:49], v[182:185], v[220:223], v[46:49]
	v_mfma_f32_16x16x32_bf16 v[58:61], v[190:193], v[212:215], v[58:61]
	v_mfma_f32_16x16x32_bf16 v[70:73], v[190:193], v[220:223], v[70:73]
	v_mfma_f32_16x16x32_bf16 v[78:81], v[198:201], v[212:215], v[78:81]
	v_mfma_f32_16x16x32_bf16 v[86:89], v[198:201], v[220:223], v[86:89]
	s_barrier
	s_setprio 0
	s_mov_b32 m0, s35
	s_nop 0
	global_load_lds_dwordx4 v232, s[100:101]
	s_mov_b32 m0, s53
	s_nop 0
	global_load_lds_dwordx4 v233, s[100:101]
	s_mov_b32 m0, s56
	s_nop 0
	global_load_lds_dwordx4 v234, s[98:99]
	s_mov_b32 m0, s57
	s_nop 0
	global_load_lds_dwordx4 v235, s[98:99]
	s_mov_b32 m0, s54
	s_nop 0
	global_load_lds_dwordx4 v236, s[100:101]
	s_mov_b32 m0, s55
	s_nop 0
	global_load_lds_dwordx4 v237, s[100:101]
	ds_read_b128 v[154:157], v175 offset:49152
	ds_read_b128 v[158:161], v175 offset:50176
	ds_read_b128 v[178:181], v175 offset:51200
	ds_read_b128 v[182:185], v175 offset:52224
	ds_read_b128 v[186:189], v175 offset:53248
	ds_read_b128 v[190:193], v175 offset:54272
	ds_read_b128 v[194:197], v175 offset:55296
	ds_read_b128 v[198:201], v175 offset:56320
	s_add_i32 s58, s58, 2
	s_add_u32 s10, s10, 0x100
	s_addc_u32 s11, s11, 0
	s_add_u32 s98, s98, 0x100
	s_addc_u32 s99, s99, 0
	s_add_u32 s100, s100, 0x100
	s_addc_u32 s101, s101, 0
	s_cmp_gt_u32 s58, 27
	s_waitcnt vmcnt(8)
	s_waitcnt lgkmcnt(0)
	s_setprio 1
	s_barrier
	v_mfma_f32_16x16x32_bf16 v[26:29], v[154:157], v[138:141], v[26:29]
	v_mfma_f32_16x16x32_bf16 v[38:41], v[154:157], v[146:149], v[38:41]
	v_mfma_f32_16x16x32_bf16 v[50:53], v[178:181], v[138:141], v[50:53]
	v_mfma_f32_16x16x32_bf16 v[62:65], v[178:181], v[146:149], v[62:65]
	v_mfma_f32_16x16x32_bf16 v[74:77], v[186:189], v[138:141], v[74:77]
	v_mfma_f32_16x16x32_bf16 v[82:85], v[186:189], v[146:149], v[82:85]
	v_mfma_f32_16x16x32_bf16 v[90:93], v[194:197], v[138:141], v[90:93]
	v_mfma_f32_16x16x32_bf16 v[94:97], v[194:197], v[146:149], v[94:97]
	v_mfma_f32_16x16x32_bf16 v[26:29], v[158:161], v[142:145], v[26:29]
	v_mfma_f32_16x16x32_bf16 v[38:41], v[158:161], v[150:153], v[38:41]
	v_mfma_f32_16x16x32_bf16 v[50:53], v[182:185], v[142:145], v[50:53]
	v_mfma_f32_16x16x32_bf16 v[62:65], v[182:185], v[150:153], v[62:65]
	v_mfma_f32_16x16x32_bf16 v[74:77], v[190:193], v[142:145], v[74:77]
	v_mfma_f32_16x16x32_bf16 v[82:85], v[190:193], v[150:153], v[82:85]
	v_mfma_f32_16x16x32_bf16 v[90:93], v[198:201], v[142:145], v[90:93]
	v_mfma_f32_16x16x32_bf16 v[94:97], v[198:201], v[150:153], v[94:97]
	v_mfma_f32_16x16x32_bf16 v[98:101], v[154:157], v[208:211], v[98:101]
	v_mfma_f32_16x16x32_bf16 v[102:105], v[154:157], v[216:219], v[102:105]
	v_mfma_f32_16x16x32_bf16 v[106:109], v[178:181], v[208:211], v[106:109]
	v_mfma_f32_16x16x32_bf16 v[110:113], v[178:181], v[216:219], v[110:113]
	v_mfma_f32_16x16x32_bf16 v[114:117], v[186:189], v[208:211], v[114:117]
	v_mfma_f32_16x16x32_bf16 v[118:121], v[186:189], v[216:219], v[118:121]
	v_mfma_f32_16x16x32_bf16 v[122:125], v[194:197], v[208:211], v[122:125]
	v_mfma_f32_16x16x32_bf16 v[126:129], v[194:197], v[216:219], v[126:129]
	v_mfma_f32_16x16x32_bf16 v[98:101], v[158:161], v[212:215], v[98:101]
	v_mfma_f32_16x16x32_bf16 v[102:105], v[158:161], v[220:223], v[102:105]
	v_mfma_f32_16x16x32_bf16 v[106:109], v[182:185], v[212:215], v[106:109]
	v_mfma_f32_16x16x32_bf16 v[110:113], v[182:185], v[220:223], v[110:113]
	v_mfma_f32_16x16x32_bf16 v[114:117], v[190:193], v[212:215], v[114:117]
	v_mfma_f32_16x16x32_bf16 v[118:121], v[190:193], v[220:223], v[118:121]
	v_mfma_f32_16x16x32_bf16 v[122:125], v[198:201], v[212:215], v[122:125]
	v_mfma_f32_16x16x32_bf16 v[126:129], v[198:201], v[220:223], v[126:129]
	s_barrier
; #define LDA(dst, b, h)                                                                                     \
;   _Pragma("unroll") for (int m = 0; m < 4; ++m) _Pragma("unroll") for (int k = 0; k < 2; ++k) dst[m][k] = \
;       *reinterpret_cast<const bf16x8*>(shmc + aL + (((b) * 2 + (h)) * 16384 + (m * 2 + k) * 1024))
; #define LDB(dst, b, h)                                                                                     \
;   _Pragma("unroll") for (int n = 0; n < 2; ++n) _Pragma("unroll") for (int k = 0; k < 2; ++k) dst[n][k] = \
;       *reinterpret_cast<const bf16x8*>(shmc + bL + (((b) * 2 + (h)) * 16384 + (n * 2 + k) * 1024))
; #define OPAQ asm volatile("" : "+v"(aL), "+v"(bL))
; #define WAIT_V(n) asm volatile("s_waitcnt vmcnt(" #n ")" ::: "memory")
; #define WAIT_L(n) asm volatile("s_waitcnt lgkmcnt(" #n ")" ::: "memory")
; #define BAR __builtin_amdgcn_s_barrier()
; template <int EPI>
; __device__ __forceinline__ void phase_gemm(const Params& p, const GemmDesc& d, char* shmc) {
;     ...
;     {
;       OPAQ;
;       LDB(B0, 0, 0); LDA(At, 0, 0); STAGE_A(SA(1, 1), 1, nt - 1);
;       BAR; WAIT_L(0); MMA(0, 0, At, B0); BAR;
;       LDB(B1, 0, 1); BAR; WAIT_L(0); MMA(0, 1, At, B1); BAR;
;       LDA(At, 0, 1); WAIT_V(4); BAR; WAIT_L(0); MMA(1, 0, At, B0); MMA(1, 1, At, B1); BAR;
;     }
	s_cbranch_scc0 .LBB0_1153
	s_setprio 0
	s_add_u32 s8, s8, 0x80f80
	s_addc_u32 s9, s9, 0
	v_add_u32_e32 v162, 0, v205
	v_add_u32_e32 v175, 0, v204
	s_mov_b32 m0, s59
	ds_read_b128 v[130:133], v162
	ds_read_b128 v[134:137], v162 offset:1024
	ds_read_b128 v[138:141], v162 offset:2048
	ds_read_b128 v[142:145], v162 offset:3072
	ds_read_b128 v[146:149], v175
	ds_read_b128 v[150:153], v175 offset:1024
	ds_read_b128 v[154:157], v175 offset:2048
	ds_read_b128 v[158:161], v175 offset:3072
	ds_read_b128 v[178:181], v175 offset:4096
	ds_read_b128 v[182:185], v175 offset:5120
	ds_read_b128 v[186:189], v175 offset:6144
	ds_read_b128 v[190:193], v175 offset:7168
	global_load_lds_dwordx4 v174, s[8:9]
	s_mov_b32 m0, s68
	s_nop 0
	global_load_lds_dwordx4 v176, s[8:9]
	s_waitcnt vmcnt(8)
	s_barrier
	s_waitcnt lgkmcnt(0)
	s_setprio 1
	s_waitcnt lgkmcnt(0)
	v_mfma_f32_16x16x32_bf16 v[2:5], v[146:149], v[130:133], v[2:5]
	v_mfma_f32_16x16x32_bf16 v[6:9], v[146:149], v[138:141], v[6:9]
	v_mfma_f32_16x16x32_bf16 v[10:13], v[154:157], v[130:133], v[10:13]
	v_mfma_f32_16x16x32_bf16 v[18:21], v[154:157], v[138:141], v[18:21]
	v_mfma_f32_16x16x32_bf16 v[66:69], v[186:189], v[138:141], v[66:69]
	v_mfma_f32_16x16x32_bf16 v[2:5], v[150:153], v[134:137], v[2:5]
	v_mfma_f32_16x16x32_bf16 v[6:9], v[150:153], v[142:145], v[6:9]
	v_mfma_f32_16x16x32_bf16 v[10:13], v[158:161], v[134:137], v[10:13]
	v_mfma_f32_16x16x32_bf16 v[18:21], v[158:161], v[142:145], v[18:21]
	v_mfma_f32_16x16x32_bf16 v[30:33], v[178:181], v[130:133], v[30:33]
	v_mfma_f32_16x16x32_bf16 v[42:45], v[178:181], v[138:141], v[42:45]
	v_mfma_f32_16x16x32_bf16 v[54:57], v[186:189], v[130:133], v[54:57]
	v_mfma_f32_16x16x32_bf16 v[66:69], v[190:193], v[142:145], v[66:69]
	v_mfma_f32_16x16x32_bf16 v[30:33], v[182:185], v[134:137], v[30:33]
	v_mfma_f32_16x16x32_bf16 v[42:45], v[182:185], v[142:145], v[42:45]
	v_mfma_f32_16x16x32_bf16 v[54:57], v[190:193], v[134:137], v[54:57]
	s_setprio 0
	s_barrier
	ds_read_b128 v[194:197], v162 offset:16384
	ds_read_b128 v[198:201], v162 offset:17408
	ds_read_b128 v[208:211], v162 offset:18432
	ds_read_b128 v[212:215], v162 offset:19456
	s_barrier
	s_waitcnt lgkmcnt(0)
	s_setprio 1
	s_waitcnt lgkmcnt(0)
	v_mfma_f32_16x16x32_bf16 v[14:17], v[146:149], v[194:197], v[14:17]
	v_mfma_f32_16x16x32_bf16 v[22:25], v[146:149], v[208:211], v[22:25]
	v_mfma_f32_16x16x32_bf16 v[58:61], v[178:181], v[194:197], v[58:61]
	v_mfma_f32_16x16x32_bf16 v[14:17], v[150:153], v[198:201], v[14:17]
	v_mfma_f32_16x16x32_bf16 v[22:25], v[150:153], v[212:215], v[22:25]
	v_mfma_f32_16x16x32_bf16 v[150:153], v[182:185], v[198:201], v[58:61]
	v_mfma_f32_16x16x32_bf16 v[58:61], v[178:181], v[208:211], v[70:73]
	v_mfma_f32_16x16x32_bf16 v[34:37], v[154:157], v[194:197], v[34:37]
	v_mfma_f32_16x16x32_bf16 v[46:49], v[154:157], v[208:211], v[46:49]
	v_mfma_f32_16x16x32_bf16 v[154:157], v[182:185], v[212:215], v[58:61]
	v_mfma_f32_16x16x32_bf16 v[58:61], v[186:189], v[194:197], v[78:81]
	v_mfma_f32_16x16x32_bf16 v[78:81], v[190:193], v[198:201], v[58:61]
	v_mfma_f32_16x16x32_bf16 v[58:61], v[186:189], v[208:211], v[86:89]
	v_mfma_f32_16x16x32_bf16 v[86:89], v[190:193], v[212:215], v[58:61]
	v_mfma_f32_16x16x32_bf16 v[34:37], v[158:161], v[198:201], v[34:37]
	v_mfma_f32_16x16x32_bf16 v[46:49], v[158:161], v[212:215], v[46:49]
	s_setprio 0
	s_barrier
	s_nop 2
	ds_read_b128 v[58:61], v175 offset:16384
	ds_read_b128 v[70:73], v175 offset:17408
	ds_read_b128 v[146:149], v175 offset:18432
	ds_read_b128 v[158:161], v175 offset:19456
	ds_read_b128 v[178:181], v175 offset:20480
	ds_read_b128 v[182:185], v175 offset:21504
	ds_read_b128 v[186:189], v175 offset:22528
	ds_read_b128 v[190:193], v175 offset:23552
	s_waitcnt vmcnt(4)
	s_barrier
	s_waitcnt lgkmcnt(0)
	s_setprio 1
	s_waitcnt lgkmcnt(0)
	v_mfma_f32_16x16x32_bf16 v[74:77], v[178:181], v[130:133], v[74:77]
	v_mfma_f32_16x16x32_bf16 v[216:219], v[182:185], v[134:137], v[74:77]
	v_mfma_f32_16x16x32_bf16 v[74:77], v[178:181], v[138:141], v[82:85]
	v_mfma_f32_16x16x32_bf16 v[26:29], v[58:61], v[130:133], v[26:29]
	v_mfma_f32_16x16x32_bf16 v[82:85], v[182:185], v[142:145], v[74:77]
	v_mfma_f32_16x16x32_bf16 v[74:77], v[186:189], v[130:133], v[90:93]
	v_mfma_f32_16x16x32_bf16 v[26:29], v[70:73], v[134:137], v[26:29]
	v_mfma_f32_16x16x32_bf16 v[38:41], v[58:61], v[138:141], v[38:41]
	v_mfma_f32_16x16x32_bf16 v[50:53], v[146:149], v[130:133], v[50:53]
	v_mfma_f32_16x16x32_bf16 v[62:65], v[146:149], v[138:141], v[62:65]
	v_mfma_f32_16x16x32_bf16 v[90:93], v[190:193], v[134:137], v[74:77]
	v_mfma_f32_16x16x32_bf16 v[74:77], v[186:189], v[138:141], v[94:97]
	v_mfma_f32_16x16x32_bf16 v[38:41], v[70:73], v[142:145], v[38:41]
	v_mfma_f32_16x16x32_bf16 v[50:53], v[158:161], v[134:137], v[50:53]
	v_mfma_f32_16x16x32_bf16 v[62:65], v[158:161], v[142:145], v[62:65]
	v_mfma_f32_16x16x32_bf16 v[220:223], v[190:193], v[142:145], v[74:77]
	s_setprio 0
	s_setprio 1
	v_mfma_f32_16x16x32_bf16 v[74:77], v[58:61], v[194:197], v[98:101]
	v_mfma_f32_16x16x32_bf16 v[58:61], v[58:61], v[208:211], v[102:105]
	v_mfma_f32_16x16x32_bf16 v[228:231], v[70:73], v[212:215], v[58:61]
	v_mfma_f32_16x16x32_bf16 v[58:61], v[146:149], v[194:197], v[106:109]
	v_mfma_f32_16x16x32_bf16 v[232:235], v[158:161], v[198:201], v[58:61]
	v_mfma_f32_16x16x32_bf16 v[58:61], v[146:149], v[208:211], v[110:113]
	v_mfma_f32_16x16x32_bf16 v[236:239], v[158:161], v[212:215], v[58:61]
	v_mfma_f32_16x16x32_bf16 v[58:61], v[178:181], v[194:197], v[114:117]
	v_mfma_f32_16x16x32_bf16 v[240:243], v[182:185], v[198:201], v[58:61]
	v_mfma_f32_16x16x32_bf16 v[58:61], v[178:181], v[208:211], v[118:121]
	v_mfma_f32_16x16x32_bf16 v[178:181], v[182:185], v[212:215], v[58:61]
	v_mfma_f32_16x16x32_bf16 v[58:61], v[186:189], v[194:197], v[122:125]
	v_mfma_f32_16x16x32_bf16 v[182:185], v[190:193], v[198:201], v[58:61]
	v_mfma_f32_16x16x32_bf16 v[58:61], v[186:189], v[208:211], v[126:129]
	v_mfma_f32_16x16x32_bf16 v[224:227], v[70:73], v[198:201], v[74:77]
	v_mfma_f32_16x16x32_bf16 v[186:189], v[190:193], v[212:215], v[58:61]
	s_setprio 0
	s_barrier
; #define LDA(dst, b, h)                                                                                     \
;   _Pragma("unroll") for (int m = 0; m < 4; ++m) _Pragma("unroll") for (int k = 0; k < 2; ++k) dst[m][k] = \
;       *reinterpret_cast<const bf16x8*>(shmc + aL + (((b) * 2 + (h)) * 16384 + (m * 2 + k) * 1024))
; #define LDB(dst, b, h)                                                                                     \
;   _Pragma("unroll") for (int n = 0; n < 2; ++n) _Pragma("unroll") for (int k = 0; k < 2; ++k) dst[n][k] = \
;       *reinterpret_cast<const bf16x8*>(shmc + bL + (((b) * 2 + (h)) * 16384 + (n * 2 + k) * 1024))
; #define WAIT_V(n) asm volatile("s_waitcnt vmcnt(" #n ")" ::: "memory")
; #define WAIT_L(n) asm volatile("s_waitcnt lgkmcnt(" #n ")" ::: "memory")
; #define BAR __builtin_amdgcn_s_barrier()
; template <int EPI>
; __device__ __forceinline__ void phase_gemm(const Params& p, const GemmDesc& d, char* shmc) {
;     ...
;     {
;       LDB(B0, 1, 0); LDA(At, 1, 0); WAIT_V(2); BAR; WAIT_L(0); MMA(0, 0, At, B0); BAR;
;       LDB(B1, 1, 1); WAIT_V(0); BAR; WAIT_L(0); MMA(0, 1, At, B1); BAR;
;       LDA(At, 1, 1); BAR; WAIT_L(0); MMA(1, 0, At, B0); MMA(1, 1, At, B1); BAR;
;     }
;     if (wr == 0) BAR;
	ds_read_b128 v[98:101], v162 offset:32768
	ds_read_b128 v[106:109], v162 offset:33792
	ds_read_b128 v[190:193], v162 offset:34816
	ds_read_b128 v[194:197], v162 offset:35840
	ds_read_b128 v[58:61], v175 offset:32768
	ds_read_b128 v[70:73], v175 offset:33792
	ds_read_b128 v[114:117], v175 offset:34816
	ds_read_b128 v[122:125], v175 offset:35840
	ds_read_b128 v[130:133], v175 offset:36864
	ds_read_b128 v[138:141], v175 offset:37888
	ds_read_b128 v[198:201], v175 offset:38912
	ds_read_b128 v[208:211], v175 offset:39936
	s_waitcnt vmcnt(2)
	s_barrier
	s_waitcnt lgkmcnt(0)
	s_setprio 1
	s_waitcnt lgkmcnt(0)
	v_mfma_f32_16x16x32_bf16 v[2:5], v[58:61], v[98:101], v[2:5]
	v_mfma_f32_16x16x32_bf16 v[158:161], v[70:73], v[106:109], v[2:5]
	v_mfma_f32_16x16x32_bf16 v[2:5], v[58:61], v[190:193], v[6:9]
	v_mfma_f32_16x16x32_bf16 v[146:149], v[70:73], v[194:197], v[2:5]
	v_mfma_f32_16x16x32_bf16 v[2:5], v[114:117], v[98:101], v[10:13]
	v_mfma_f32_16x16x32_bf16 v[142:145], v[122:125], v[106:109], v[2:5]
	v_mfma_f32_16x16x32_bf16 v[2:5], v[114:117], v[190:193], v[18:21]
	v_mfma_f32_16x16x32_bf16 v[134:137], v[122:125], v[194:197], v[2:5]
	v_mfma_f32_16x16x32_bf16 v[2:5], v[130:133], v[98:101], v[30:33]
	v_mfma_f32_16x16x32_bf16 v[126:129], v[138:141], v[106:109], v[2:5]
	v_mfma_f32_16x16x32_bf16 v[2:5], v[130:133], v[190:193], v[42:45]
	v_mfma_f32_16x16x32_bf16 v[118:121], v[138:141], v[194:197], v[2:5]
	v_mfma_f32_16x16x32_bf16 v[2:5], v[198:201], v[98:101], v[54:57]
	v_mfma_f32_16x16x32_bf16 v[110:113], v[208:211], v[106:109], v[2:5]
	v_mfma_f32_16x16x32_bf16 v[2:5], v[198:201], v[190:193], v[66:69]
	v_mfma_f32_16x16x32_bf16 v[102:105], v[208:211], v[194:197], v[2:5]
	s_setprio 0
	s_barrier
	ds_read_b128 v[30:33], v162 offset:49152
	ds_read_b128 v[42:45], v162 offset:50176
	ds_read_b128 v[54:57], v162 offset:51200
	ds_read_b128 v[212:215], v162 offset:52224
	s_waitcnt vmcnt(0)
	s_barrier
	s_waitcnt lgkmcnt(0)
	s_setprio 1
	s_waitcnt lgkmcnt(0)
	v_mfma_f32_16x16x32_bf16 v[2:5], v[58:61], v[30:33], v[14:17]
	v_mfma_f32_16x16x32_bf16 v[94:97], v[70:73], v[42:45], v[2:5]
	v_mfma_f32_16x16x32_bf16 v[2:5], v[58:61], v[54:57], v[22:25]
	v_mfma_f32_16x16x32_bf16 v[58:61], v[70:73], v[212:215], v[2:5]
	v_mfma_f32_16x16x32_bf16 v[2:5], v[114:117], v[30:33], v[34:37]
	v_mfma_f32_16x16x32_bf16 v[74:77], v[122:125], v[42:45], v[2:5]
	v_mfma_f32_16x16x32_bf16 v[2:5], v[114:117], v[54:57], v[46:49]
	v_mfma_f32_16x16x32_bf16 v[10:13], v[122:125], v[212:215], v[2:5]
	v_mfma_f32_16x16x32_bf16 v[2:5], v[130:133], v[30:33], v[150:153]
	v_mfma_f32_16x16x32_bf16 v[70:73], v[138:141], v[42:45], v[2:5]
	v_mfma_f32_16x16x32_bf16 v[2:5], v[130:133], v[54:57], v[154:157]
	v_mfma_f32_16x16x32_bf16 v[6:9], v[138:141], v[212:215], v[2:5]
	v_mfma_f32_16x16x32_bf16 v[2:5], v[198:201], v[30:33], v[78:81]
	v_mfma_f32_16x16x32_bf16 v[66:69], v[208:211], v[42:45], v[2:5]
	v_mfma_f32_16x16x32_bf16 v[2:5], v[198:201], v[54:57], v[86:89]
	v_mfma_f32_16x16x32_bf16 v[2:5], v[208:211], v[212:215], v[2:5]
	s_setprio 0
	s_barrier
	ds_read_b128 v[14:17], v175 offset:49152
	ds_read_b128 v[18:21], v175 offset:50176
	ds_read_b128 v[22:25], v175 offset:51200
	ds_read_b128 v[34:37], v175 offset:52224
	ds_read_b128 v[46:49], v175 offset:53248
	ds_read_b128 v[78:81], v175 offset:54272
	ds_read_b128 v[198:201], v175 offset:55296
	ds_read_b128 v[208:211], v175 offset:56320
	s_barrier
	s_waitcnt lgkmcnt(0)
	s_setprio 1
	s_waitcnt lgkmcnt(0)
	v_mfma_f32_16x16x32_bf16 v[26:29], v[14:17], v[98:101], v[26:29]
	v_mfma_f32_16x16x32_bf16 v[154:157], v[18:21], v[106:109], v[26:29]
	v_mfma_f32_16x16x32_bf16 v[26:29], v[14:17], v[190:193], v[38:41]
	v_mfma_f32_16x16x32_bf16 v[150:153], v[18:21], v[194:197], v[26:29]
	v_mfma_f32_16x16x32_bf16 v[26:29], v[22:25], v[98:101], v[50:53]
	v_mfma_f32_16x16x32_bf16 v[138:141], v[34:37], v[106:109], v[26:29]
	v_mfma_f32_16x16x32_bf16 v[26:29], v[22:25], v[190:193], v[62:65]
	v_mfma_f32_16x16x32_bf16 v[130:133], v[34:37], v[194:197], v[26:29]
	v_mfma_f32_16x16x32_bf16 v[26:29], v[46:49], v[98:101], v[216:219]
	v_mfma_f32_16x16x32_bf16 v[122:125], v[78:81], v[106:109], v[26:29]
	v_mfma_f32_16x16x32_bf16 v[26:29], v[46:49], v[190:193], v[82:85]
	v_mfma_f32_16x16x32_bf16 v[114:117], v[78:81], v[194:197], v[26:29]
	v_mfma_f32_16x16x32_bf16 v[26:29], v[198:201], v[98:101], v[90:93]
	v_mfma_f32_16x16x32_bf16 v[106:109], v[208:211], v[106:109], v[26:29]
	v_mfma_f32_16x16x32_bf16 v[26:29], v[198:201], v[190:193], v[220:223]
	v_mfma_f32_16x16x32_bf16 v[98:101], v[208:211], v[194:197], v[26:29]
	s_setprio 0
	s_setprio 1
	v_mfma_f32_16x16x32_bf16 v[26:29], v[14:17], v[30:33], v[224:227]
	v_mfma_f32_16x16x32_bf16 v[14:17], v[14:17], v[54:57], v[228:231]
	v_mfma_f32_16x16x32_bf16 v[90:93], v[18:21], v[42:45], v[26:29]
	v_mfma_f32_16x16x32_bf16 v[26:29], v[18:21], v[212:215], v[14:17]
	v_mfma_f32_16x16x32_bf16 v[14:17], v[22:25], v[30:33], v[232:235]
	v_mfma_f32_16x16x32_bf16 v[86:89], v[34:37], v[42:45], v[14:17]
	v_mfma_f32_16x16x32_bf16 v[14:17], v[22:25], v[54:57], v[236:239]
	v_mfma_f32_16x16x32_bf16 v[22:25], v[34:37], v[212:215], v[14:17]
	v_mfma_f32_16x16x32_bf16 v[14:17], v[46:49], v[30:33], v[240:243]
	v_mfma_f32_16x16x32_bf16 v[82:85], v[78:81], v[42:45], v[14:17]
	v_mfma_f32_16x16x32_bf16 v[14:17], v[46:49], v[54:57], v[178:181]
	v_mfma_f32_16x16x32_bf16 v[18:21], v[78:81], v[212:215], v[14:17]
	v_mfma_f32_16x16x32_bf16 v[14:17], v[198:201], v[30:33], v[182:185]
	v_mfma_f32_16x16x32_bf16 v[78:81], v[208:211], v[42:45], v[14:17]
	v_mfma_f32_16x16x32_bf16 v[14:17], v[198:201], v[54:57], v[186:189]
	v_mfma_f32_16x16x32_bf16 v[14:17], v[208:211], v[212:215], v[14:17]
	s_setprio 0
	s_barrier
	s_and_saveexec_b64 s[8:9], s[6:7]
	s_cbranch_execz .LBB0_1156
	s_barrier

; #define LDA(dst, b, h)                                                                                     \
;   _Pragma("unroll") for (int m = 0; m < 4; ++m) _Pragma("unroll") for (int k = 0; k < 2; ++k) dst[m][k] = \
;       *reinterpret_cast<const bf16x8*>(shmc + aL + (((b) * 2 + (h)) * 16384 + (m * 2 + k) * 1024))
; #define LDB(dst, b, h)                                                                                     \
;   _Pragma("unroll") for (int n = 0; n < 2; ++n) _Pragma("unroll") for (int k = 0; k < 2; ++k) dst[n][k] = \
;       *reinterpret_cast<const bf16x8*>(shmc + bL + (((b) * 2 + (h)) * 16384 + (n * 2 + k) * 1024))
; #define OPAQ asm volatile("" : "+v"(aL), "+v"(bL))
; #define WAIT_V(n) asm volatile("s_waitcnt vmcnt(" #n ")" ::: "memory")
; #define WAIT_L(n) asm volatile("s_waitcnt lgkmcnt(" #n ")" ::: "memory")
; #define BAR __builtin_amdgcn_s_barrier()
; #define SCHED __builtin_amdgcn_sched_barrier(0)
; template <int EPI>
; __device__ __forceinline__ void phase_gemm(const Params& p, const GemmDesc& d, char* shmc) {
;     ...
;     for (int t = 0; t < nt - 2; t += 2) {
;       OPAQ;
;       LDB(B0, 0, 0); SCHED; LDA(At, 0, 0); STAGE_A(SA(1, 1), 1, t + 1);
;       WAIT_L(8); BAR; WAIT_L(0); MMA(0, 0, At, B0); BAR; SCHED;
;       LDB(B1, 0, 1); STAGE_B(SB(0, 0), 0, t + 2);
;       BAR; WAIT_L(0); MMA(0, 1, At, B1); BAR;
;       LDA(At, 0, 1); STAGE_A(SA(0, 0), 0, t + 2);
;       BAR; WAIT_L(0); MMA(1, 0, At, B0); BAR; SCHED;
;       STAGE_B(SB(0, 1), 1, t + 2);
;       WAIT_V(6); BAR; MMA(1, 1, At, B1); BAR;
.LBB0_1312:
	s_nop 0
	v_add_u32_e32 v130, 0, v153
	v_add_u32_e32 v141, 0, v152
	s_setprio 0
	s_mov_b32 m0, s59
	s_nop 0
	global_load_lds_dwordx4 v220, s[98:99]
	s_mov_b32 m0, s60
	s_nop 0
	global_load_lds_dwordx4 v221, s[98:99]
	ds_read_b128 v[156:159], v130
	ds_read_b128 v[160:163], v130 offset:1024
	ds_read_b128 v[164:167], v130 offset:2048
	ds_read_b128 v[168:171], v130 offset:3072
	ds_read_b128 v[204:207], v130 offset:16384
	ds_read_b128 v[208:211], v130 offset:17408
	ds_read_b128 v[212:215], v130 offset:18432
	ds_read_b128 v[216:219], v130 offset:19456
	ds_read_b128 v[172:175], v141
	ds_read_b128 v[176:179], v141 offset:1024
	ds_read_b128 v[180:183], v141 offset:2048
	ds_read_b128 v[184:187], v141 offset:3072
	ds_read_b128 v[188:191], v141 offset:4096
	ds_read_b128 v[192:195], v141 offset:5120
	ds_read_b128 v[196:199], v141 offset:6144
	ds_read_b128 v[200:203], v141 offset:7168
	s_waitcnt vmcnt(8)
	s_waitcnt lgkmcnt(0)
	s_setprio 1
	s_barrier
	v_mfma_f32_16x16x32_bf16 v[126:129], v[156:159], v[172:175], v[126:129]
	v_mfma_f32_16x16x32_bf16 v[122:125], v[164:167], v[172:175], v[122:125]
	v_mfma_f32_16x16x32_bf16 v[118:121], v[156:159], v[180:183], v[118:121]
	v_mfma_f32_16x16x32_bf16 v[114:117], v[164:167], v[180:183], v[114:117]
	v_mfma_f32_16x16x32_bf16 v[110:113], v[156:159], v[188:191], v[110:113]
	v_mfma_f32_16x16x32_bf16 v[106:109], v[164:167], v[188:191], v[106:109]
	v_mfma_f32_16x16x32_bf16 v[102:105], v[156:159], v[196:199], v[102:105]
	v_mfma_f32_16x16x32_bf16 v[98:101], v[164:167], v[196:199], v[98:101]
	v_mfma_f32_16x16x32_bf16 v[126:129], v[160:163], v[176:179], v[126:129]
	v_mfma_f32_16x16x32_bf16 v[122:125], v[168:171], v[176:179], v[122:125]
	v_mfma_f32_16x16x32_bf16 v[118:121], v[160:163], v[184:187], v[118:121]
	v_mfma_f32_16x16x32_bf16 v[114:117], v[168:171], v[184:187], v[114:117]
	v_mfma_f32_16x16x32_bf16 v[110:113], v[160:163], v[192:195], v[110:113]
	v_mfma_f32_16x16x32_bf16 v[106:109], v[168:171], v[192:195], v[106:109]
	v_mfma_f32_16x16x32_bf16 v[102:105], v[160:163], v[200:203], v[102:105]
	v_mfma_f32_16x16x32_bf16 v[98:101], v[168:171], v[200:203], v[98:101]
	v_mfma_f32_16x16x32_bf16 v[86:89], v[204:207], v[172:175], v[86:89]
	v_mfma_f32_16x16x32_bf16 v[70:73], v[212:215], v[172:175], v[70:73]
	v_mfma_f32_16x16x32_bf16 v[54:57], v[204:207], v[180:183], v[54:57]
	v_mfma_f32_16x16x32_bf16 v[50:53], v[212:215], v[180:183], v[50:53]
	v_mfma_f32_16x16x32_bf16 v[46:49], v[204:207], v[188:191], v[46:49]
	v_mfma_f32_16x16x32_bf16 v[42:45], v[212:215], v[188:191], v[42:45]
	v_mfma_f32_16x16x32_bf16 v[38:41], v[204:207], v[196:199], v[38:41]
	v_mfma_f32_16x16x32_bf16 v[34:37], v[212:215], v[196:199], v[34:37]
	v_mfma_f32_16x16x32_bf16 v[86:89], v[208:211], v[176:179], v[86:89]
	v_mfma_f32_16x16x32_bf16 v[70:73], v[216:219], v[176:179], v[70:73]
	v_mfma_f32_16x16x32_bf16 v[54:57], v[208:211], v[184:187], v[54:57]
	v_mfma_f32_16x16x32_bf16 v[50:53], v[216:219], v[184:187], v[50:53]
	v_mfma_f32_16x16x32_bf16 v[46:49], v[208:211], v[192:195], v[46:49]
	v_mfma_f32_16x16x32_bf16 v[42:45], v[216:219], v[192:195], v[42:45]
	v_mfma_f32_16x16x32_bf16 v[38:41], v[208:211], v[200:203], v[38:41]
	v_mfma_f32_16x16x32_bf16 v[34:37], v[216:219], v[200:203], v[34:37]
	s_barrier
	s_setprio 0
	s_mov_b32 m0, s34
	s_nop 0
	global_load_lds_dwordx4 v222, s[100:101]
	s_mov_b32 m0, s35
	s_nop 0
	global_load_lds_dwordx4 v223, s[100:101]
	s_mov_b32 m0, s33
	s_nop 0
	global_load_lds_dwordx4 v224, s[98:99]
	s_mov_b32 m0, s46
	s_nop 0
	global_load_lds_dwordx4 v225, s[98:99]
	s_mov_b32 m0, s47
	s_nop 0
	global_load_lds_dwordx4 v226, s[100:101]
	s_mov_b32 m0, s48
	s_nop 0
	global_load_lds_dwordx4 v227, s[100:101]
	ds_read_b128 v[172:175], v141 offset:16384
	ds_read_b128 v[176:179], v141 offset:17408
	ds_read_b128 v[180:183], v141 offset:18432
	ds_read_b128 v[184:187], v141 offset:19456
	ds_read_b128 v[188:191], v141 offset:20480
	ds_read_b128 v[192:195], v141 offset:21504
	ds_read_b128 v[196:199], v141 offset:22528
	ds_read_b128 v[200:203], v141 offset:23552
	s_waitcnt vmcnt(8)
	s_waitcnt lgkmcnt(0)
	s_setprio 1
	s_barrier
	v_mfma_f32_16x16x32_bf16 v[30:33], v[156:159], v[172:175], v[30:33]
	v_mfma_f32_16x16x32_bf16 v[26:29], v[164:167], v[172:175], v[26:29]
	v_mfma_f32_16x16x32_bf16 v[22:25], v[156:159], v[180:183], v[22:25]
	v_mfma_f32_16x16x32_bf16 v[18:21], v[164:167], v[180:183], v[18:21]
	v_mfma_f32_16x16x32_bf16 v[14:17], v[156:159], v[188:191], v[14:17]
	v_mfma_f32_16x16x32_bf16 v[10:13], v[164:167], v[188:191], v[10:13]
	v_mfma_f32_16x16x32_bf16 v[6:9], v[156:159], v[196:199], v[6:9]
	v_mfma_f32_16x16x32_bf16 v[2:5], v[164:167], v[196:199], v[2:5]
	v_mfma_f32_16x16x32_bf16 v[30:33], v[160:163], v[176:179], v[30:33]
	v_mfma_f32_16x16x32_bf16 v[26:29], v[168:171], v[176:179], v[26:29]
	v_mfma_f32_16x16x32_bf16 v[22:25], v[160:163], v[184:187], v[22:25]
	v_mfma_f32_16x16x32_bf16 v[18:21], v[168:171], v[184:187], v[18:21]
	v_mfma_f32_16x16x32_bf16 v[14:17], v[160:163], v[192:195], v[14:17]
	v_mfma_f32_16x16x32_bf16 v[10:13], v[168:171], v[192:195], v[10:13]
	v_mfma_f32_16x16x32_bf16 v[6:9], v[160:163], v[200:203], v[6:9]
	v_mfma_f32_16x16x32_bf16 v[2:5], v[168:171], v[200:203], v[2:5]
	v_mfma_f32_16x16x32_bf16 v[58:61], v[204:207], v[172:175], v[58:61]
	v_mfma_f32_16x16x32_bf16 v[62:65], v[212:215], v[172:175], v[62:65]
	v_mfma_f32_16x16x32_bf16 v[66:69], v[204:207], v[180:183], v[66:69]
	v_mfma_f32_16x16x32_bf16 v[74:77], v[212:215], v[180:183], v[74:77]
	v_mfma_f32_16x16x32_bf16 v[78:81], v[204:207], v[188:191], v[78:81]
	v_mfma_f32_16x16x32_bf16 v[82:85], v[212:215], v[188:191], v[82:85]
	v_mfma_f32_16x16x32_bf16 v[90:93], v[204:207], v[196:199], v[90:93]
	v_mfma_f32_16x16x32_bf16 v[94:97], v[212:215], v[196:199], v[94:97]
	v_mfma_f32_16x16x32_bf16 v[58:61], v[208:211], v[176:179], v[58:61]
	v_mfma_f32_16x16x32_bf16 v[62:65], v[216:219], v[176:179], v[62:65]
	v_mfma_f32_16x16x32_bf16 v[66:69], v[208:211], v[184:187], v[66:69]
	v_mfma_f32_16x16x32_bf16 v[74:77], v[216:219], v[184:187], v[74:77]
	v_mfma_f32_16x16x32_bf16 v[78:81], v[208:211], v[192:195], v[78:81]
	v_mfma_f32_16x16x32_bf16 v[82:85], v[216:219], v[192:195], v[82:85]
	v_mfma_f32_16x16x32_bf16 v[90:93], v[208:211], v[200:203], v[90:93]
	v_mfma_f32_16x16x32_bf16 v[94:97], v[216:219], v[200:203], v[94:97]
	s_barrier
; #define LDA(dst, b, h)                                                                                     \
;   _Pragma("unroll") for (int m = 0; m < 4; ++m) _Pragma("unroll") for (int k = 0; k < 2; ++k) dst[m][k] = \
;       *reinterpret_cast<const bf16x8*>(shmc + aL + (((b) * 2 + (h)) * 16384 + (m * 2 + k) * 1024))
; #define LDB(dst, b, h)                                                                                     \
;   _Pragma("unroll") for (int n = 0; n < 2; ++n) _Pragma("unroll") for (int k = 0; k < 2; ++k) dst[n][k] = \
;       *reinterpret_cast<const bf16x8*>(shmc + bL + (((b) * 2 + (h)) * 16384 + (n * 2 + k) * 1024))
; #define WAIT_V(n) asm volatile("s_waitcnt vmcnt(" #n ")" ::: "memory")
; #define WAIT_L(n) asm volatile("s_waitcnt lgkmcnt(" #n ")" ::: "memory")
; #define BAR __builtin_amdgcn_s_barrier()
; #define SCHED __builtin_amdgcn_sched_barrier(0)
; template <int EPI>
; __device__ __forceinline__ void phase_gemm(const Params& p, const GemmDesc& d, char* shmc) {
;     ...
;       LDB(B0, 1, 0); SCHED; LDA(At, 1, 0); STAGE_A(SA(0, 1), 1, t + 2);
;       WAIT_L(8); BAR; WAIT_L(0); MMA(0, 0, At, B0); BAR; SCHED;
;       LDB(B1, 1, 1); STAGE_B(SB(1, 0), 0, t + 3);
;       BAR; WAIT_L(0); MMA(0, 1, At, B1); BAR;
;       LDA(At, 1, 1); STAGE_A(SA(1, 0), 0, t + 3);
;       BAR; WAIT_L(0); MMA(1, 0, At, B0); BAR; SCHED;
;       STAGE_B(SB(1, 1), 1, t + 3);
;       WAIT_V(6); BAR; MMA(1, 1, At, B1); BAR;
	s_setprio 0
	s_mov_b32 m0, s49
	s_nop 0
	global_load_lds_dwordx4 v228, s[98:99]
	s_mov_b32 m0, s52
	s_nop 0
	global_load_lds_dwordx4 v229, s[98:99]
	ds_read_b128 v[156:159], v130 offset:32768
	ds_read_b128 v[160:163], v130 offset:33792
	ds_read_b128 v[164:167], v130 offset:34816
	ds_read_b128 v[168:171], v130 offset:35840
	ds_read_b128 v[204:207], v130 offset:49152
	ds_read_b128 v[208:211], v130 offset:50176
	ds_read_b128 v[212:215], v130 offset:51200
	ds_read_b128 v[216:219], v130 offset:52224
	ds_read_b128 v[172:175], v141 offset:32768
	ds_read_b128 v[176:179], v141 offset:33792
	ds_read_b128 v[180:183], v141 offset:34816
	ds_read_b128 v[184:187], v141 offset:35840
	ds_read_b128 v[188:191], v141 offset:36864
	ds_read_b128 v[192:195], v141 offset:37888
	ds_read_b128 v[196:199], v141 offset:38912
	ds_read_b128 v[200:203], v141 offset:39936
	s_waitcnt vmcnt(8)
	s_waitcnt lgkmcnt(0)
	s_setprio 1
	s_barrier
	v_mfma_f32_16x16x32_bf16 v[126:129], v[156:159], v[172:175], v[126:129]
	v_mfma_f32_16x16x32_bf16 v[122:125], v[164:167], v[172:175], v[122:125]
	v_mfma_f32_16x16x32_bf16 v[118:121], v[156:159], v[180:183], v[118:121]
	v_mfma_f32_16x16x32_bf16 v[114:117], v[164:167], v[180:183], v[114:117]
	v_mfma_f32_16x16x32_bf16 v[110:113], v[156:159], v[188:191], v[110:113]
	v_mfma_f32_16x16x32_bf16 v[106:109], v[164:167], v[188:191], v[106:109]
	v_mfma_f32_16x16x32_bf16 v[102:105], v[156:159], v[196:199], v[102:105]
	v_mfma_f32_16x16x32_bf16 v[98:101], v[164:167], v[196:199], v[98:101]
	v_mfma_f32_16x16x32_bf16 v[126:129], v[160:163], v[176:179], v[126:129]
	v_mfma_f32_16x16x32_bf16 v[122:125], v[168:171], v[176:179], v[122:125]
	v_mfma_f32_16x16x32_bf16 v[118:121], v[160:163], v[184:187], v[118:121]
	v_mfma_f32_16x16x32_bf16 v[114:117], v[168:171], v[184:187], v[114:117]
	v_mfma_f32_16x16x32_bf16 v[110:113], v[160:163], v[192:195], v[110:113]
	v_mfma_f32_16x16x32_bf16 v[106:109], v[168:171], v[192:195], v[106:109]
	v_mfma_f32_16x16x32_bf16 v[102:105], v[160:163], v[200:203], v[102:105]
	v_mfma_f32_16x16x32_bf16 v[98:101], v[168:171], v[200:203], v[98:101]
	v_mfma_f32_16x16x32_bf16 v[86:89], v[204:207], v[172:175], v[86:89]
	v_mfma_f32_16x16x32_bf16 v[70:73], v[212:215], v[172:175], v[70:73]
	v_mfma_f32_16x16x32_bf16 v[54:57], v[204:207], v[180:183], v[54:57]
	v_mfma_f32_16x16x32_bf16 v[50:53], v[212:215], v[180:183], v[50:53]
	v_mfma_f32_16x16x32_bf16 v[46:49], v[204:207], v[188:191], v[46:49]
	v_mfma_f32_16x16x32_bf16 v[42:45], v[212:215], v[188:191], v[42:45]
	v_mfma_f32_16x16x32_bf16 v[38:41], v[204:207], v[196:199], v[38:41]
	v_mfma_f32_16x16x32_bf16 v[34:37], v[212:215], v[196:199], v[34:37]
	v_mfma_f32_16x16x32_bf16 v[86:89], v[208:211], v[176:179], v[86:89]
	v_mfma_f32_16x16x32_bf16 v[70:73], v[216:219], v[176:179], v[70:73]
	v_mfma_f32_16x16x32_bf16 v[54:57], v[208:211], v[184:187], v[54:57]
	v_mfma_f32_16x16x32_bf16 v[50:53], v[216:219], v[184:187], v[50:53]
	v_mfma_f32_16x16x32_bf16 v[46:49], v[208:211], v[192:195], v[46:49]
	v_mfma_f32_16x16x32_bf16 v[42:45], v[216:219], v[192:195], v[42:45]
	v_mfma_f32_16x16x32_bf16 v[38:41], v[208:211], v[200:203], v[38:41]
	v_mfma_f32_16x16x32_bf16 v[34:37], v[216:219], v[200:203], v[34:37]
	s_barrier
	s_setprio 0
	s_mov_b32 m0, s53
	s_nop 0
	global_load_lds_dwordx4 v232, s[100:101]
	s_mov_b32 m0, s54
	s_nop 0
	global_load_lds_dwordx4 v233, s[100:101]
	s_mov_b32 m0, s55
	s_nop 0
	global_load_lds_dwordx4 v234, s[98:99]
	s_mov_b32 m0, s56
	s_nop 0
	global_load_lds_dwordx4 v235, s[98:99]
	s_mov_b32 m0, s57
	s_nop 0
	global_load_lds_dwordx4 v236, s[100:101]
	s_mov_b32 m0, s58
	s_nop 0
	global_load_lds_dwordx4 v237, s[100:101]
	ds_read_b128 v[172:175], v141 offset:49152
	ds_read_b128 v[176:179], v141 offset:50176
	ds_read_b128 v[180:183], v141 offset:51200
	ds_read_b128 v[184:187], v141 offset:52224
	ds_read_b128 v[188:191], v141 offset:53248
	ds_read_b128 v[192:195], v141 offset:54272
	ds_read_b128 v[196:199], v141 offset:55296
	ds_read_b128 v[200:203], v141 offset:56320
	s_add_i32 s42, s42, 2
	s_add_u32 s40, s40, 0x100
	s_addc_u32 s41, s41, 0
	s_add_u32 s98, s98, 0x100
	s_addc_u32 s99, s99, 0
	s_add_u32 s100, s100, 0x100
	s_addc_u32 s101, s101, 0
	s_cmpk_gt_u32 s42, 0x53
	s_waitcnt vmcnt(8)
	s_waitcnt lgkmcnt(0)
	s_setprio 1
	s_barrier
	v_mfma_f32_16x16x32_bf16 v[30:33], v[156:159], v[172:175], v[30:33]
	v_mfma_f32_16x16x32_bf16 v[26:29], v[164:167], v[172:175], v[26:29]
	v_mfma_f32_16x16x32_bf16 v[22:25], v[156:159], v[180:183], v[22:25]
	v_mfma_f32_16x16x32_bf16 v[18:21], v[164:167], v[180:183], v[18:21]
	v_mfma_f32_16x16x32_bf16 v[14:17], v[156:159], v[188:191], v[14:17]
	v_mfma_f32_16x16x32_bf16 v[10:13], v[164:167], v[188:191], v[10:13]
	v_mfma_f32_16x16x32_bf16 v[6:9], v[156:159], v[196:199], v[6:9]
	v_mfma_f32_16x16x32_bf16 v[2:5], v[164:167], v[196:199], v[2:5]
	v_mfma_f32_16x16x32_bf16 v[30:33], v[160:163], v[176:179], v[30:33]
	v_mfma_f32_16x16x32_bf16 v[26:29], v[168:171], v[176:179], v[26:29]
	v_mfma_f32_16x16x32_bf16 v[22:25], v[160:163], v[184:187], v[22:25]
	v_mfma_f32_16x16x32_bf16 v[18:21], v[168:171], v[184:187], v[18:21]
	v_mfma_f32_16x16x32_bf16 v[14:17], v[160:163], v[192:195], v[14:17]
	v_mfma_f32_16x16x32_bf16 v[10:13], v[168:171], v[192:195], v[10:13]
	v_mfma_f32_16x16x32_bf16 v[6:9], v[160:163], v[200:203], v[6:9]
	v_mfma_f32_16x16x32_bf16 v[2:5], v[168:171], v[200:203], v[2:5]
	v_mfma_f32_16x16x32_bf16 v[58:61], v[204:207], v[172:175], v[58:61]
	v_mfma_f32_16x16x32_bf16 v[62:65], v[212:215], v[172:175], v[62:65]
	v_mfma_f32_16x16x32_bf16 v[66:69], v[204:207], v[180:183], v[66:69]
	v_mfma_f32_16x16x32_bf16 v[74:77], v[212:215], v[180:183], v[74:77]
	v_mfma_f32_16x16x32_bf16 v[78:81], v[204:207], v[188:191], v[78:81]
	v_mfma_f32_16x16x32_bf16 v[82:85], v[212:215], v[188:191], v[82:85]
	v_mfma_f32_16x16x32_bf16 v[90:93], v[204:207], v[196:199], v[90:93]
	v_mfma_f32_16x16x32_bf16 v[94:97], v[212:215], v[196:199], v[94:97]
	v_mfma_f32_16x16x32_bf16 v[58:61], v[208:211], v[176:179], v[58:61]
	v_mfma_f32_16x16x32_bf16 v[62:65], v[216:219], v[176:179], v[62:65]
	v_mfma_f32_16x16x32_bf16 v[66:69], v[208:211], v[184:187], v[66:69]
	v_mfma_f32_16x16x32_bf16 v[74:77], v[216:219], v[184:187], v[74:77]
	v_mfma_f32_16x16x32_bf16 v[78:81], v[208:211], v[192:195], v[78:81]
	v_mfma_f32_16x16x32_bf16 v[82:85], v[216:219], v[192:195], v[82:85]
	v_mfma_f32_16x16x32_bf16 v[90:93], v[208:211], v[200:203], v[90:93]
	v_mfma_f32_16x16x32_bf16 v[94:97], v[216:219], v[200:203], v[94:97]
	s_barrier
; #define LDA(dst, b, h)                                                                                     \
;   _Pragma("unroll") for (int m = 0; m < 4; ++m) _Pragma("unroll") for (int k = 0; k < 2; ++k) dst[m][k] = \
;       *reinterpret_cast<const bf16x8*>(shmc + aL + (((b) * 2 + (h)) * 16384 + (m * 2 + k) * 1024))
; #define LDB(dst, b, h)                                                                                     \
;   _Pragma("unroll") for (int n = 0; n < 2; ++n) _Pragma("unroll") for (int k = 0; k < 2; ++k) dst[n][k] = \
;       *reinterpret_cast<const bf16x8*>(shmc + bL + (((b) * 2 + (h)) * 16384 + (n * 2 + k) * 1024))
; #define OPAQ asm volatile("" : "+v"(aL), "+v"(bL))
; #define WAIT_V(n) asm volatile("s_waitcnt vmcnt(" #n ")" ::: "memory")
; #define WAIT_L(n) asm volatile("s_waitcnt lgkmcnt(" #n ")" ::: "memory")
; #define BAR __builtin_amdgcn_s_barrier()
; template <int EPI>
; __device__ __forceinline__ void phase_gemm(const Params& p, const GemmDesc& d, char* shmc) {
;     ...
;     {
;       OPAQ;
;       LDB(B0, 0, 0); LDA(At, 0, 0); STAGE_A(SA(1, 1), 1, nt - 1);
;       BAR; WAIT_L(0); MMA(0, 0, At, B0); BAR;
;       LDB(B1, 0, 1); BAR; WAIT_L(0); MMA(0, 1, At, B1); BAR;
;       LDA(At, 0, 1); WAIT_V(4); BAR; WAIT_L(0); MMA(1, 0, At, B0); MMA(1, 1, At, B1); BAR;
;     }
	s_cbranch_scc0 .LBB0_1312
	s_setprio 0
	s_add_u32 s38, s38, 0x162b80
	s_addc_u32 s39, s39, 0
	v_add_u32_e32 v130, 0, v153
	v_add_u32_e32 v141, 0, v152
	s_mov_b32 m0, s59
	ds_read_b128 v[144:147], v130
	ds_read_b128 v[148:151], v130 offset:1024
	ds_read_b128 v[156:159], v130 offset:2048
	ds_read_b128 v[160:163], v130 offset:3072
	ds_read_b128 v[164:167], v141
	ds_read_b128 v[168:171], v141 offset:1024
	ds_read_b128 v[172:175], v141 offset:2048
	ds_read_b128 v[176:179], v141 offset:3072
	ds_read_b128 v[180:183], v141 offset:4096
	ds_read_b128 v[184:187], v141 offset:5120
	ds_read_b128 v[188:191], v141 offset:6144
	ds_read_b128 v[192:195], v141 offset:7168
	global_load_lds_dwordx4 v140, s[38:39]
	s_mov_b32 m0, s60
	s_nop 0
	global_load_lds_dwordx4 v142, s[38:39]
	s_waitcnt vmcnt(8)
	s_barrier
	s_waitcnt lgkmcnt(0)
	s_setprio 1
	s_waitcnt lgkmcnt(0)
	v_mfma_f32_16x16x32_bf16 v[126:129], v[144:147], v[164:167], v[126:129]
	v_mfma_f32_16x16x32_bf16 v[122:125], v[156:159], v[164:167], v[122:125]
	v_mfma_f32_16x16x32_bf16 v[114:117], v[156:159], v[172:175], v[114:117]
	v_mfma_f32_16x16x32_bf16 v[110:113], v[144:147], v[180:183], v[110:113]
	v_mfma_f32_16x16x32_bf16 v[102:105], v[144:147], v[188:191], v[102:105]
	v_mfma_f32_16x16x32_bf16 v[126:129], v[148:151], v[168:171], v[126:129]
	v_mfma_f32_16x16x32_bf16 v[122:125], v[160:163], v[168:171], v[122:125]
	v_mfma_f32_16x16x32_bf16 v[118:121], v[144:147], v[172:175], v[118:121]
	v_mfma_f32_16x16x32_bf16 v[114:117], v[160:163], v[176:179], v[114:117]
	v_mfma_f32_16x16x32_bf16 v[110:113], v[148:151], v[184:187], v[110:113]
	v_mfma_f32_16x16x32_bf16 v[106:109], v[156:159], v[180:183], v[106:109]
	v_mfma_f32_16x16x32_bf16 v[102:105], v[148:151], v[192:195], v[102:105]
	v_mfma_f32_16x16x32_bf16 v[98:101], v[156:159], v[188:191], v[98:101]
	v_mfma_f32_16x16x32_bf16 v[196:199], v[148:151], v[176:179], v[118:121]
	v_mfma_f32_16x16x32_bf16 v[200:203], v[160:163], v[184:187], v[106:109]
	v_mfma_f32_16x16x32_bf16 v[204:207], v[160:163], v[192:195], v[98:101]
	s_setprio 0
	s_barrier
	s_nop 2
	ds_read_b128 v[98:101], v130 offset:16384
	ds_read_b128 v[106:109], v130 offset:17408
	ds_read_b128 v[118:121], v130 offset:18432
	ds_read_b128 v[208:211], v130 offset:19456
	s_barrier
	s_waitcnt lgkmcnt(0)
	s_setprio 1
	s_waitcnt lgkmcnt(0)
	v_mfma_f32_16x16x32_bf16 v[86:89], v[98:101], v[164:167], v[86:89]
	v_mfma_f32_16x16x32_bf16 v[70:73], v[118:121], v[164:167], v[70:73]
	v_mfma_f32_16x16x32_bf16 v[54:57], v[98:101], v[172:175], v[54:57]
	v_mfma_f32_16x16x32_bf16 v[50:53], v[118:121], v[172:175], v[50:53]
	v_mfma_f32_16x16x32_bf16 v[46:49], v[98:101], v[180:183], v[46:49]
	v_mfma_f32_16x16x32_bf16 v[42:45], v[118:121], v[180:183], v[42:45]
	v_mfma_f32_16x16x32_bf16 v[38:41], v[98:101], v[188:191], v[38:41]
	v_mfma_f32_16x16x32_bf16 v[34:37], v[118:121], v[188:191], v[34:37]
	v_mfma_f32_16x16x32_bf16 v[86:89], v[106:109], v[168:171], v[86:89]
	v_mfma_f32_16x16x32_bf16 v[70:73], v[208:211], v[168:171], v[70:73]
	v_mfma_f32_16x16x32_bf16 v[54:57], v[106:109], v[176:179], v[54:57]
	v_mfma_f32_16x16x32_bf16 v[50:53], v[208:211], v[176:179], v[50:53]
	v_mfma_f32_16x16x32_bf16 v[46:49], v[106:109], v[184:187], v[46:49]
	v_mfma_f32_16x16x32_bf16 v[42:45], v[208:211], v[184:187], v[42:45]
	v_mfma_f32_16x16x32_bf16 v[38:41], v[106:109], v[192:195], v[38:41]
	v_mfma_f32_16x16x32_bf16 v[34:37], v[208:211], v[192:195], v[34:37]
	s_setprio 0
	s_barrier
	ds_read_b128 v[164:167], v141 offset:16384
	ds_read_b128 v[168:171], v141 offset:17408
	ds_read_b128 v[172:175], v141 offset:18432
	ds_read_b128 v[176:179], v141 offset:19456
	ds_read_b128 v[180:183], v141 offset:20480
	ds_read_b128 v[184:187], v141 offset:21504
	ds_read_b128 v[188:191], v141 offset:22528
	ds_read_b128 v[192:195], v141 offset:23552
	s_waitcnt vmcnt(4)
	s_barrier
	s_waitcnt lgkmcnt(0)
	s_setprio 1
	s_waitcnt lgkmcnt(0)
	v_mfma_f32_16x16x32_bf16 v[30:33], v[144:147], v[164:167], v[30:33]
	v_mfma_f32_16x16x32_bf16 v[26:29], v[156:159], v[164:167], v[26:29]
	v_mfma_f32_16x16x32_bf16 v[22:25], v[144:147], v[172:175], v[22:25]
	v_mfma_f32_16x16x32_bf16 v[18:21], v[156:159], v[172:175], v[18:21]
	v_mfma_f32_16x16x32_bf16 v[14:17], v[144:147], v[180:183], v[14:17]
	v_mfma_f32_16x16x32_bf16 v[10:13], v[156:159], v[180:183], v[10:13]
	v_mfma_f32_16x16x32_bf16 v[6:9], v[144:147], v[188:191], v[6:9]
	v_mfma_f32_16x16x32_bf16 v[2:5], v[156:159], v[188:191], v[2:5]
	v_mfma_f32_16x16x32_bf16 v[30:33], v[148:151], v[168:171], v[30:33]
	v_mfma_f32_16x16x32_bf16 v[26:29], v[160:163], v[168:171], v[26:29]
	v_mfma_f32_16x16x32_bf16 v[22:25], v[148:151], v[176:179], v[22:25]
	v_mfma_f32_16x16x32_bf16 v[18:21], v[160:163], v[176:179], v[18:21]
	v_mfma_f32_16x16x32_bf16 v[14:17], v[148:151], v[184:187], v[14:17]
	v_mfma_f32_16x16x32_bf16 v[10:13], v[160:163], v[184:187], v[10:13]
	v_mfma_f32_16x16x32_bf16 v[6:9], v[148:151], v[192:195], v[6:9]
	v_mfma_f32_16x16x32_bf16 v[2:5], v[160:163], v[192:195], v[2:5]
	s_setprio 0
	s_setprio 1
	v_mfma_f32_16x16x32_bf16 v[62:65], v[118:121], v[164:167], v[62:65]
	v_mfma_f32_16x16x32_bf16 v[144:147], v[208:211], v[168:171], v[62:65]
	v_mfma_f32_16x16x32_bf16 v[62:65], v[98:101], v[172:175], v[66:69]
	v_mfma_f32_16x16x32_bf16 v[148:151], v[106:109], v[176:179], v[62:65]
	v_mfma_f32_16x16x32_bf16 v[62:65], v[118:121], v[172:175], v[74:77]
	v_mfma_f32_16x16x32_bf16 v[156:159], v[208:211], v[176:179], v[62:65]
	v_mfma_f32_16x16x32_bf16 v[62:65], v[98:101], v[180:183], v[78:81]
	v_mfma_f32_16x16x32_bf16 v[160:163], v[106:109], v[184:187], v[62:65]
	v_mfma_f32_16x16x32_bf16 v[62:65], v[118:121], v[180:183], v[82:85]
	v_mfma_f32_16x16x32_bf16 v[58:61], v[98:101], v[164:167], v[58:61]
	v_mfma_f32_16x16x32_bf16 v[164:167], v[208:211], v[184:187], v[62:65]
	v_mfma_f32_16x16x32_bf16 v[62:65], v[98:101], v[188:191], v[90:93]
	v_mfma_f32_16x16x32_bf16 v[58:61], v[106:109], v[168:171], v[58:61]
	v_mfma_f32_16x16x32_bf16 v[168:171], v[106:109], v[192:195], v[62:65]
	v_mfma_f32_16x16x32_bf16 v[62:65], v[118:121], v[188:191], v[94:97]
	v_mfma_f32_16x16x32_bf16 v[172:175], v[208:211], v[192:195], v[62:65]
	s_setprio 0
	s_barrier
; #define LDA(dst, b, h)                                                                                     \
;   _Pragma("unroll") for (int m = 0; m < 4; ++m) _Pragma("unroll") for (int k = 0; k < 2; ++k) dst[m][k] = \
;       *reinterpret_cast<const bf16x8*>(shmc + aL + (((b) * 2 + (h)) * 16384 + (m * 2 + k) * 1024))
; #define LDB(dst, b, h)                                                                                     \
;   _Pragma("unroll") for (int n = 0; n < 2; ++n) _Pragma("unroll") for (int k = 0; k < 2; ++k) dst[n][k] = \
;       *reinterpret_cast<const bf16x8*>(shmc + bL + (((b) * 2 + (h)) * 16384 + (n * 2 + k) * 1024))
; #define WAIT_V(n) asm volatile("s_waitcnt vmcnt(" #n ")" ::: "memory")
; #define WAIT_L(n) asm volatile("s_waitcnt lgkmcnt(" #n ")" ::: "memory")
; #define BAR __builtin_amdgcn_s_barrier()
; template <int EPI>
; __device__ __forceinline__ void phase_gemm(const Params& p, const GemmDesc& d, char* shmc) {
;     ...
;     {
;       LDB(B0, 1, 0); LDA(At, 1, 0); WAIT_V(2); BAR; WAIT_L(0); MMA(0, 0, At, B0); BAR;
;       LDB(B1, 1, 1); WAIT_V(0); BAR; WAIT_L(0); MMA(0, 1, At, B1); BAR;
;       LDA(At, 1, 1); BAR; WAIT_L(0); MMA(1, 0, At, B0); MMA(1, 1, At, B1); BAR;
;     }
;     if (wr == 0) BAR;
	ds_read_b128 v[176:179], v130 offset:32768
	ds_read_b128 v[180:183], v130 offset:33792
	ds_read_b128 v[184:187], v130 offset:34816
	ds_read_b128 v[188:191], v130 offset:35840
	s_nop 0
	ds_read_b128 v[62:65], v141 offset:32768
	ds_read_b128 v[78:81], v141 offset:33792
	ds_read_b128 v[94:97], v141 offset:34816
	ds_read_b128 v[192:195], v141 offset:35840
	ds_read_b128 v[208:211], v141 offset:36864
	ds_read_b128 v[212:215], v141 offset:37888
	ds_read_b128 v[216:219], v141 offset:38912
	ds_read_b128 v[220:223], v141 offset:39936
	s_waitcnt vmcnt(2)
	s_barrier
	s_waitcnt lgkmcnt(0)
	s_setprio 1
	s_waitcnt lgkmcnt(0)
	v_mfma_f32_16x16x32_bf16 v[66:69], v[176:179], v[62:65], v[126:129]
	v_mfma_f32_16x16x32_bf16 v[126:129], v[180:183], v[78:81], v[66:69]
	v_mfma_f32_16x16x32_bf16 v[66:69], v[184:187], v[62:65], v[122:125]
	v_mfma_f32_16x16x32_bf16 v[118:121], v[188:191], v[78:81], v[66:69]
	v_mfma_f32_16x16x32_bf16 v[66:69], v[176:179], v[94:97], v[196:199]
	v_mfma_f32_16x16x32_bf16 v[106:109], v[180:183], v[192:195], v[66:69]
	v_mfma_f32_16x16x32_bf16 v[66:69], v[184:187], v[94:97], v[114:117]
	v_mfma_f32_16x16x32_bf16 v[98:101], v[188:191], v[192:195], v[66:69]
	v_mfma_f32_16x16x32_bf16 v[66:69], v[176:179], v[208:211], v[110:113]
	v_mfma_f32_16x16x32_bf16 v[90:93], v[180:183], v[212:215], v[66:69]
	v_mfma_f32_16x16x32_bf16 v[66:69], v[184:187], v[208:211], v[200:203]
	v_mfma_f32_16x16x32_bf16 v[82:85], v[188:191], v[212:215], v[66:69]
	v_mfma_f32_16x16x32_bf16 v[66:69], v[176:179], v[216:219], v[102:105]
	v_mfma_f32_16x16x32_bf16 v[74:77], v[180:183], v[220:223], v[66:69]
	v_mfma_f32_16x16x32_bf16 v[66:69], v[184:187], v[216:219], v[204:207]
	v_mfma_f32_16x16x32_bf16 v[66:69], v[188:191], v[220:223], v[66:69]
	s_setprio 0
	s_barrier
	ds_read_b128 v[196:199], v130 offset:49152
	ds_read_b128 v[200:203], v130 offset:50176
	ds_read_b128 v[204:207], v130 offset:51200
	ds_read_b128 v[224:227], v130 offset:52224
	s_waitcnt vmcnt(0)
	s_barrier
	s_waitcnt lgkmcnt(0)
	s_setprio 1
	s_waitcnt lgkmcnt(0)
	v_mfma_f32_16x16x32_bf16 v[86:89], v[196:199], v[62:65], v[86:89]
	v_mfma_f32_16x16x32_bf16 v[62:65], v[204:207], v[62:65], v[70:73]
	v_mfma_f32_16x16x32_bf16 v[54:57], v[196:199], v[94:97], v[54:57]
	v_mfma_f32_16x16x32_bf16 v[50:53], v[204:207], v[94:97], v[50:53]
	v_mfma_f32_16x16x32_bf16 v[46:49], v[196:199], v[208:211], v[46:49]
	v_mfma_f32_16x16x32_bf16 v[42:45], v[204:207], v[208:211], v[42:45]
	v_mfma_f32_16x16x32_bf16 v[38:41], v[196:199], v[216:219], v[38:41]
	v_mfma_f32_16x16x32_bf16 v[34:37], v[204:207], v[216:219], v[34:37]
	v_mfma_f32_16x16x32_bf16 v[122:125], v[200:203], v[78:81], v[86:89]
	v_mfma_f32_16x16x32_bf16 v[114:117], v[224:227], v[78:81], v[62:65]
	v_mfma_f32_16x16x32_bf16 v[110:113], v[200:203], v[192:195], v[54:57]
	v_mfma_f32_16x16x32_bf16 v[102:105], v[224:227], v[192:195], v[50:53]
	v_mfma_f32_16x16x32_bf16 v[94:97], v[200:203], v[212:215], v[46:49]
	v_mfma_f32_16x16x32_bf16 v[86:89], v[224:227], v[212:215], v[42:45]
	v_mfma_f32_16x16x32_bf16 v[78:81], v[200:203], v[220:223], v[38:41]
	v_mfma_f32_16x16x32_bf16 v[70:73], v[224:227], v[220:223], v[34:37]
	s_setprio 0
	s_barrier
	s_nop 0
	ds_read_b128 v[34:37], v141 offset:49152
	ds_read_b128 v[42:45], v141 offset:50176
	ds_read_b128 v[192:195], v141 offset:51200
	ds_read_b128 v[208:211], v141 offset:52224
	ds_read_b128 v[212:215], v141 offset:53248
	ds_read_b128 v[216:219], v141 offset:54272
	ds_read_b128 v[220:223], v141 offset:55296
	ds_read_b128 v[228:231], v141 offset:56320
	s_barrier
	s_waitcnt lgkmcnt(0)
	s_setprio 1
	s_waitcnt lgkmcnt(0)
	v_mfma_f32_16x16x32_bf16 v[30:33], v[176:179], v[34:37], v[30:33]
	v_mfma_f32_16x16x32_bf16 v[26:29], v[184:187], v[34:37], v[26:29]
	v_mfma_f32_16x16x32_bf16 v[22:25], v[176:179], v[192:195], v[22:25]
	v_mfma_f32_16x16x32_bf16 v[18:21], v[184:187], v[192:195], v[18:21]
	v_mfma_f32_16x16x32_bf16 v[14:17], v[176:179], v[212:215], v[14:17]
	v_mfma_f32_16x16x32_bf16 v[10:13], v[184:187], v[212:215], v[10:13]
	v_mfma_f32_16x16x32_bf16 v[6:9], v[176:179], v[220:223], v[6:9]
	v_mfma_f32_16x16x32_bf16 v[2:5], v[184:187], v[220:223], v[2:5]
	v_mfma_f32_16x16x32_bf16 v[62:65], v[180:183], v[42:45], v[30:33]
	v_mfma_f32_16x16x32_bf16 v[54:57], v[188:191], v[42:45], v[26:29]
	v_mfma_f32_16x16x32_bf16 v[46:49], v[180:183], v[208:211], v[22:25]
	v_mfma_f32_16x16x32_bf16 v[38:41], v[188:191], v[208:211], v[18:21]
	v_mfma_f32_16x16x32_bf16 v[30:33], v[180:183], v[216:219], v[14:17]
	v_mfma_f32_16x16x32_bf16 v[22:25], v[188:191], v[216:219], v[10:13]
	v_mfma_f32_16x16x32_bf16 v[14:17], v[180:183], v[228:231], v[6:9]
	v_mfma_f32_16x16x32_bf16 v[6:9], v[188:191], v[228:231], v[2:5]
	s_setprio 0
	s_setprio 1
	v_mfma_f32_16x16x32_bf16 v[2:5], v[196:199], v[34:37], v[58:61]
	v_mfma_f32_16x16x32_bf16 v[58:61], v[200:203], v[42:45], v[2:5]
	v_mfma_f32_16x16x32_bf16 v[2:5], v[204:207], v[34:37], v[144:147]
	v_mfma_f32_16x16x32_bf16 v[50:53], v[224:227], v[42:45], v[2:5]
	v_mfma_f32_16x16x32_bf16 v[2:5], v[196:199], v[192:195], v[148:151]
	v_mfma_f32_16x16x32_bf16 v[42:45], v[200:203], v[208:211], v[2:5]
	v_mfma_f32_16x16x32_bf16 v[2:5], v[204:207], v[192:195], v[156:159]
	v_mfma_f32_16x16x32_bf16 v[34:37], v[224:227], v[208:211], v[2:5]
	v_mfma_f32_16x16x32_bf16 v[2:5], v[196:199], v[212:215], v[160:163]
	v_mfma_f32_16x16x32_bf16 v[26:29], v[200:203], v[216:219], v[2:5]
	v_mfma_f32_16x16x32_bf16 v[2:5], v[204:207], v[212:215], v[164:167]
	v_mfma_f32_16x16x32_bf16 v[18:21], v[224:227], v[216:219], v[2:5]
	v_mfma_f32_16x16x32_bf16 v[2:5], v[196:199], v[220:223], v[168:171]
	v_mfma_f32_16x16x32_bf16 v[10:13], v[200:203], v[228:231], v[2:5]
	v_mfma_f32_16x16x32_bf16 v[2:5], v[204:207], v[220:223], v[172:175]
	v_mfma_f32_16x16x32_bf16 v[2:5], v[224:227], v[228:231], v[2:5]
	s_setprio 0
	s_barrier
	s_and_saveexec_b64 s[38:39], s[4:5]
	s_cbranch_execz .LBB0_1315
	s_barrier
